# GEMM loops: the two remaining per-iteration VALU LDS-address adds hoisted to per-unit constants (v244/v245)
# speedup vs baseline: 1.0125x; 1.0008x over previous
.LBB0_242:
	s_ashr_i32 s11, s10, 31
	s_xor_b64 s[14:15], s[28:29], -1
	s_lshl_b64 s[12:13], s[10:11], 20
	s_add_u32 s12, s34, s12
	s_addc_u32 s13, s35, s13
	s_and_b64 s[16:17], s[28:29], exec
	s_cselect_b32 s11, s13, s19
	s_cselect_b32 s67, s12, s18
	s_ashr_i32 s9, s8, 31
	s_lshl_b64 s[16:17], s[8:9], 20
	s_add_u32 s16, s22, s16
	s_addc_u32 s17, s23, s17
	s_and_b64 s[28:29], s[28:29], exec
	s_cselect_b32 s9, s17, s37
	s_cselect_b32 s28, s16, s36
	s_add_u32 s18, s18, 0x80080
	s_addc_u32 s19, s19, 0
	s_add_u32 s29, s36, 0x100
	s_addc_u32 s72, s37, 0
	s_mov_b32 s73, -2
	v_add_u32_e32 v244, 0x18000, v143
	v_add_u32_e32 v245, 0x1c000, v143
	ds_read_b128 v[150:153], v146
	ds_read_b128 v[154:157], v146 offset:1024
	ds_read_b128 v[158:161], v146 offset:2048
	ds_read_b128 v[162:165], v146 offset:3072
	s_add_u32 s36, s18, 0xfff80080
	s_addc_u32 s37, s19, -1
	s_cmp_eq_u32 s73, 28
	s_cselect_b32 s55, s11, s37
	s_cselect_b32 s54, s67, s36
	s_cselect_b32 s37, s9, s72
	s_cselect_b32 s36, s28, s29
	s_add_i32 m0, s56, 0xc000
	ds_read_b128 v[166:169], v147
	ds_read_b128 v[170:173], v147 offset:1024
	ds_read_b128 v[174:177], v147 offset:2048
	ds_read_b128 v[178:181], v147 offset:3072
	ds_read_b128 v[182:185], v147 offset:4096
	ds_read_b128 v[186:189], v147 offset:5120
	ds_read_b128 v[190:193], v147 offset:6144
	ds_read_b128 v[194:197], v147 offset:7168
	global_load_lds_dwordx4 v138, s[18:19]
	s_add_i32 m0, s56, 0xe000
	s_nop 0
	global_load_lds_dwordx4 v140, s[18:19]
	s_waitcnt lgkmcnt(8)
	s_barrier
	s_waitcnt lgkmcnt(0)
	v_mfma_f32_16x16x32_bf16 v[124:127], v[150:153], v[166:169], 0
	v_mfma_f32_16x16x32_bf16 v[120:123], v[158:161], v[166:169], 0
	v_mfma_f32_16x16x32_bf16 v[116:119], v[150:153], v[174:177], 0
	v_mfma_f32_16x16x32_bf16 v[108:111], v[158:161], v[174:177], 0
	v_mfma_f32_16x16x32_bf16 v[100:103], v[150:153], v[182:185], 0
	v_mfma_f32_16x16x32_bf16 v[96:99], v[158:161], v[182:185], 0
	v_mfma_f32_16x16x32_bf16 v[84:87], v[150:153], v[190:193], 0
	v_mfma_f32_16x16x32_bf16 v[80:83], v[158:161], v[190:193], 0
	v_mfma_f32_16x16x32_bf16 v[124:127], v[154:157], v[170:173], v[124:127]
	v_mfma_f32_16x16x32_bf16 v[120:123], v[162:165], v[170:173], v[120:123]
	v_mfma_f32_16x16x32_bf16 v[116:119], v[154:157], v[178:181], v[116:119]
	v_mfma_f32_16x16x32_bf16 v[108:111], v[162:165], v[178:181], v[108:111]
	v_mfma_f32_16x16x32_bf16 v[100:103], v[154:157], v[186:189], v[100:103]
	v_mfma_f32_16x16x32_bf16 v[96:99], v[162:165], v[186:189], v[96:99]
	v_mfma_f32_16x16x32_bf16 v[84:87], v[154:157], v[194:197], v[84:87]
	v_mfma_f32_16x16x32_bf16 v[80:83], v[162:165], v[194:197], v[80:83]
	s_barrier
	s_add_i32 s74, s63, s33
	s_add_u32 s98, s36, s6
	s_addc_u32 s99, s37, s7
	s_mov_b32 m0, s74
	ds_read_b128 v[198:201], v148
	ds_read_b128 v[202:205], v148 offset:1024
	ds_read_b128 v[206:209], v148 offset:2048
	ds_read_b128 v[210:213], v148 offset:3072
	global_load_lds_dwordx4 v130, s[36:37]
	s_add_i32 m0, s74, 0x2000
	s_nop 0
	global_load_lds_dwordx4 v134, s[36:37]
	s_barrier
	s_waitcnt lgkmcnt(0)
	v_mfma_f32_16x16x32_bf16 v[112:115], v[198:201], v[166:169], 0
	v_mfma_f32_16x16x32_bf16 v[104:107], v[206:209], v[166:169], 0
	v_mfma_f32_16x16x32_bf16 v[92:95], v[198:201], v[174:177], 0
	v_mfma_f32_16x16x32_bf16 v[88:91], v[206:209], v[174:177], 0
	v_mfma_f32_16x16x32_bf16 v[76:79], v[198:201], v[182:185], 0
	v_mfma_f32_16x16x32_bf16 v[72:75], v[206:209], v[182:185], 0
	v_mfma_f32_16x16x32_bf16 v[68:71], v[198:201], v[190:193], 0
	v_mfma_f32_16x16x32_bf16 v[64:67], v[206:209], v[190:193], 0
	v_mfma_f32_16x16x32_bf16 v[112:115], v[202:205], v[170:173], v[112:115]
	v_mfma_f32_16x16x32_bf16 v[104:107], v[210:213], v[170:173], v[104:107]
	v_mfma_f32_16x16x32_bf16 v[92:95], v[202:205], v[178:181], v[92:95]
	v_mfma_f32_16x16x32_bf16 v[88:91], v[210:213], v[178:181], v[88:91]
	v_mfma_f32_16x16x32_bf16 v[76:79], v[202:205], v[186:189], v[76:79]
	v_mfma_f32_16x16x32_bf16 v[72:75], v[210:213], v[186:189], v[72:75]
	v_mfma_f32_16x16x32_bf16 v[68:71], v[202:205], v[194:197], v[68:71]
	v_mfma_f32_16x16x32_bf16 v[64:67], v[210:213], v[194:197], v[64:67]
	s_mov_b32 m0, s56
	s_add_u32 s100, s54, s6
	s_addc_u32 s101, s55, s7
	s_barrier
	ds_read_b128 v[166:169], v147 offset:16384
	ds_read_b128 v[170:173], v147 offset:17408
	ds_read_b128 v[174:177], v147 offset:18432
	ds_read_b128 v[178:181], v147 offset:19456
	ds_read_b128 v[182:185], v147 offset:20480
	ds_read_b128 v[186:189], v147 offset:21504
	ds_read_b128 v[190:193], v147 offset:22528
	ds_read_b128 v[194:197], v147 offset:23552
	global_load_lds_dwordx4 v128, s[54:55]
	s_mov_b32 m0, s57
	s_nop 0
	global_load_lds_dwordx4 v132, s[54:55]
	s_barrier
	s_waitcnt lgkmcnt(0)
	v_mfma_f32_16x16x32_bf16 v[60:63], v[150:153], v[166:169], 0
	v_mfma_f32_16x16x32_bf16 v[56:59], v[158:161], v[166:169], 0
	v_mfma_f32_16x16x32_bf16 v[52:55], v[150:153], v[174:177], 0
	v_mfma_f32_16x16x32_bf16 v[48:51], v[158:161], v[174:177], 0
	v_mfma_f32_16x16x32_bf16 v[36:39], v[150:153], v[182:185], 0
	v_mfma_f32_16x16x32_bf16 v[32:35], v[158:161], v[182:185], 0
	v_mfma_f32_16x16x32_bf16 v[20:23], v[150:153], v[190:193], 0
	v_mfma_f32_16x16x32_bf16 v[16:19], v[158:161], v[190:193], 0
	v_mfma_f32_16x16x32_bf16 v[60:63], v[154:157], v[170:173], v[60:63]
	v_mfma_f32_16x16x32_bf16 v[56:59], v[162:165], v[170:173], v[56:59]
	v_mfma_f32_16x16x32_bf16 v[52:55], v[154:157], v[178:181], v[52:55]
	v_mfma_f32_16x16x32_bf16 v[48:51], v[162:165], v[178:181], v[48:51]
	v_mfma_f32_16x16x32_bf16 v[36:39], v[154:157], v[186:189], v[36:39]
	v_mfma_f32_16x16x32_bf16 v[32:35], v[162:165], v[186:189], v[32:35]
	v_mfma_f32_16x16x32_bf16 v[20:23], v[154:157], v[194:197], v[20:23]
	v_mfma_f32_16x16x32_bf16 v[16:19], v[162:165], v[194:197], v[16:19]
	s_barrier
	s_add_u32 s74, s36, 0x80000
	s_addc_u32 s75, s37, 0
	s_add_i32 s76, s64, s33
	s_mov_b32 m0, s76
	s_nop 0
	global_load_lds_dwordx4 v130, s[74:75]
	s_add_i32 m0, s76, 0x2000
	s_nop 0
	global_load_lds_dwordx4 v134, s[74:75]
	s_waitcnt vmcnt(6)
	s_barrier
	v_mfma_f32_16x16x32_bf16 v[44:47], v[198:201], v[166:169], 0
	v_mfma_f32_16x16x32_bf16 v[40:43], v[206:209], v[166:169], 0
	v_mfma_f32_16x16x32_bf16 v[28:31], v[198:201], v[174:177], 0
	v_mfma_f32_16x16x32_bf16 v[24:27], v[206:209], v[174:177], 0
	v_mfma_f32_16x16x32_bf16 v[12:15], v[198:201], v[182:185], 0
	v_mfma_f32_16x16x32_bf16 v[8:11], v[206:209], v[182:185], 0
	v_mfma_f32_16x16x32_bf16 v[4:7], v[198:201], v[190:193], 0
	v_mfma_f32_16x16x32_bf16 v[0:3], v[206:209], v[190:193], 0
	v_mfma_f32_16x16x32_bf16 v[44:47], v[202:205], v[170:173], v[44:47]
	v_mfma_f32_16x16x32_bf16 v[40:43], v[210:213], v[170:173], v[40:43]
	v_mfma_f32_16x16x32_bf16 v[28:31], v[202:205], v[178:181], v[28:31]
	v_mfma_f32_16x16x32_bf16 v[24:27], v[210:213], v[178:181], v[24:27]
	v_mfma_f32_16x16x32_bf16 v[12:15], v[202:205], v[186:189], v[12:15]
	v_mfma_f32_16x16x32_bf16 v[8:11], v[210:213], v[186:189], v[8:11]
	v_mfma_f32_16x16x32_bf16 v[4:7], v[202:205], v[194:197], v[4:7]
	v_mfma_f32_16x16x32_bf16 v[0:3], v[210:213], v[194:197], v[0:3]
	s_add_i32 s74, 0, 0x18000
	s_barrier
	ds_read_b128 v[150:153], v244
	ds_read_b128 v[154:157], v244 offset:1024
	ds_read_b128 v[158:161], v244 offset:2048
	ds_read_b128 v[162:165], v244 offset:3072
	s_add_u32 s54, s54, 0x80000
	s_addc_u32 s55, s55, 0
	s_mov_b32 m0, s58
	ds_read_b128 v[166:169], v147 offset:32768
	ds_read_b128 v[170:173], v147 offset:33792
	ds_read_b128 v[174:177], v147 offset:34816
	ds_read_b128 v[178:181], v147 offset:35840
	ds_read_b128 v[182:185], v147 offset:36864
	ds_read_b128 v[186:189], v147 offset:37888
	ds_read_b128 v[190:193], v147 offset:38912
	ds_read_b128 v[194:197], v147 offset:39936
	global_load_lds_dwordx4 v128, s[54:55]
	s_mov_b32 m0, s59
	s_nop 0
	global_load_lds_dwordx4 v132, s[54:55]
	s_waitcnt lgkmcnt(8)
	s_barrier
	s_waitcnt lgkmcnt(0)
	v_mfma_f32_16x16x32_bf16 v[124:127], v[150:153], v[166:169], v[124:127]
	v_mfma_f32_16x16x32_bf16 v[120:123], v[158:161], v[166:169], v[120:123]
	v_mfma_f32_16x16x32_bf16 v[116:119], v[150:153], v[174:177], v[116:119]
	v_mfma_f32_16x16x32_bf16 v[108:111], v[158:161], v[174:177], v[108:111]
	v_mfma_f32_16x16x32_bf16 v[100:103], v[150:153], v[182:185], v[100:103]
	v_mfma_f32_16x16x32_bf16 v[96:99], v[158:161], v[182:185], v[96:99]
	v_mfma_f32_16x16x32_bf16 v[84:87], v[150:153], v[190:193], v[84:87]
	v_mfma_f32_16x16x32_bf16 v[80:83], v[158:161], v[190:193], v[80:83]
	v_mfma_f32_16x16x32_bf16 v[124:127], v[154:157], v[170:173], v[124:127]
	v_mfma_f32_16x16x32_bf16 v[120:123], v[162:165], v[170:173], v[120:123]
	v_mfma_f32_16x16x32_bf16 v[116:119], v[154:157], v[178:181], v[116:119]
	v_mfma_f32_16x16x32_bf16 v[108:111], v[162:165], v[178:181], v[108:111]
	v_mfma_f32_16x16x32_bf16 v[100:103], v[154:157], v[186:189], v[100:103]
	v_mfma_f32_16x16x32_bf16 v[96:99], v[162:165], v[186:189], v[96:99]
	v_mfma_f32_16x16x32_bf16 v[84:87], v[154:157], v[194:197], v[84:87]
	v_mfma_f32_16x16x32_bf16 v[80:83], v[162:165], v[194:197], v[80:83]
	s_barrier
	s_add_i32 s54, 0, 0x1c000
	s_add_i32 s55, s74, s33
	s_mov_b32 m0, s55
	ds_read_b128 v[198:201], v245
	ds_read_b128 v[202:205], v245 offset:1024
	ds_read_b128 v[206:209], v245 offset:2048
	ds_read_b128 v[210:213], v245 offset:3072
	global_load_lds_dwordx4 v130, s[98:99]
	s_add_i32 m0, s55, 0x2000
	s_nop 0
	global_load_lds_dwordx4 v134, s[98:99]
	s_barrier
	s_waitcnt lgkmcnt(0)
	v_mfma_f32_16x16x32_bf16 v[112:115], v[198:201], v[166:169], v[112:115]
	v_mfma_f32_16x16x32_bf16 v[104:107], v[206:209], v[166:169], v[104:107]
	v_mfma_f32_16x16x32_bf16 v[92:95], v[198:201], v[174:177], v[92:95]
	v_mfma_f32_16x16x32_bf16 v[88:91], v[206:209], v[174:177], v[88:91]
	v_mfma_f32_16x16x32_bf16 v[76:79], v[198:201], v[182:185], v[76:79]
	v_mfma_f32_16x16x32_bf16 v[72:75], v[206:209], v[182:185], v[72:75]
	v_mfma_f32_16x16x32_bf16 v[68:71], v[198:201], v[190:193], v[68:71]
	v_mfma_f32_16x16x32_bf16 v[64:67], v[206:209], v[190:193], v[64:67]
	v_mfma_f32_16x16x32_bf16 v[112:115], v[202:205], v[170:173], v[112:115]
	v_mfma_f32_16x16x32_bf16 v[104:107], v[210:213], v[170:173], v[104:107]
	v_mfma_f32_16x16x32_bf16 v[92:95], v[202:205], v[178:181], v[92:95]
	v_mfma_f32_16x16x32_bf16 v[88:91], v[210:213], v[178:181], v[88:91]
	v_mfma_f32_16x16x32_bf16 v[76:79], v[202:205], v[186:189], v[76:79]
	v_mfma_f32_16x16x32_bf16 v[72:75], v[210:213], v[186:189], v[72:75]
	v_mfma_f32_16x16x32_bf16 v[68:71], v[202:205], v[194:197], v[68:71]
	v_mfma_f32_16x16x32_bf16 v[64:67], v[210:213], v[194:197], v[64:67]
	s_mov_b32 m0, s60
	s_barrier
	ds_read_b128 v[166:169], v147 offset:49152
	ds_read_b128 v[170:173], v147 offset:50176
	ds_read_b128 v[174:177], v147 offset:51200
	ds_read_b128 v[178:181], v147 offset:52224
	ds_read_b128 v[182:185], v147 offset:53248
	ds_read_b128 v[186:189], v147 offset:54272
	ds_read_b128 v[190:193], v147 offset:55296
	ds_read_b128 v[194:197], v147 offset:56320
	global_load_lds_dwordx4 v128, s[100:101]
	s_mov_b32 m0, s61
	s_nop 0
	global_load_lds_dwordx4 v132, s[100:101]
	s_barrier
	s_waitcnt lgkmcnt(0)
	v_mfma_f32_16x16x32_bf16 v[60:63], v[150:153], v[166:169], v[60:63]
	v_mfma_f32_16x16x32_bf16 v[56:59], v[158:161], v[166:169], v[56:59]
	v_mfma_f32_16x16x32_bf16 v[52:55], v[150:153], v[174:177], v[52:55]
	v_mfma_f32_16x16x32_bf16 v[48:51], v[158:161], v[174:177], v[48:51]
	v_mfma_f32_16x16x32_bf16 v[36:39], v[150:153], v[182:185], v[36:39]
	v_mfma_f32_16x16x32_bf16 v[32:35], v[158:161], v[182:185], v[32:35]
	v_mfma_f32_16x16x32_bf16 v[20:23], v[150:153], v[190:193], v[20:23]
	v_mfma_f32_16x16x32_bf16 v[16:19], v[158:161], v[190:193], v[16:19]
	v_mfma_f32_16x16x32_bf16 v[60:63], v[154:157], v[170:173], v[60:63]
	v_mfma_f32_16x16x32_bf16 v[56:59], v[162:165], v[170:173], v[56:59]
	v_mfma_f32_16x16x32_bf16 v[52:55], v[154:157], v[178:181], v[52:55]
	v_mfma_f32_16x16x32_bf16 v[48:51], v[162:165], v[178:181], v[48:51]
	v_mfma_f32_16x16x32_bf16 v[36:39], v[154:157], v[186:189], v[36:39]
	v_mfma_f32_16x16x32_bf16 v[32:35], v[162:165], v[186:189], v[32:35]
	v_mfma_f32_16x16x32_bf16 v[20:23], v[154:157], v[194:197], v[20:23]
	v_mfma_f32_16x16x32_bf16 v[16:19], v[162:165], v[194:197], v[16:19]
	s_barrier
	s_add_u32 s36, s36, 0x80080
	s_addc_u32 s37, s37, 0
	s_add_i32 s54, s54, s33
	s_mov_b32 m0, s54
	s_nop 0
	global_load_lds_dwordx4 v130, s[36:37]
	s_add_i32 m0, s54, 0x2000
	s_nop 0
	global_load_lds_dwordx4 v134, s[36:37]
	s_waitcnt vmcnt(6)
	s_barrier
	v_mfma_f32_16x16x32_bf16 v[44:47], v[198:201], v[166:169], v[44:47]
	v_mfma_f32_16x16x32_bf16 v[40:43], v[206:209], v[166:169], v[40:43]
	v_mfma_f32_16x16x32_bf16 v[28:31], v[198:201], v[174:177], v[28:31]
	v_mfma_f32_16x16x32_bf16 v[24:27], v[206:209], v[174:177], v[24:27]
	v_mfma_f32_16x16x32_bf16 v[12:15], v[198:201], v[182:185], v[12:15]
	v_mfma_f32_16x16x32_bf16 v[8:11], v[206:209], v[182:185], v[8:11]
	v_mfma_f32_16x16x32_bf16 v[4:7], v[198:201], v[190:193], v[4:7]
	v_mfma_f32_16x16x32_bf16 v[0:3], v[206:209], v[190:193], v[0:3]
	v_mfma_f32_16x16x32_bf16 v[44:47], v[202:205], v[170:173], v[44:47]
	v_mfma_f32_16x16x32_bf16 v[40:43], v[210:213], v[170:173], v[40:43]
	v_mfma_f32_16x16x32_bf16 v[28:31], v[202:205], v[178:181], v[28:31]
	v_mfma_f32_16x16x32_bf16 v[24:27], v[210:213], v[178:181], v[24:27]
	v_mfma_f32_16x16x32_bf16 v[12:15], v[202:205], v[186:189], v[12:15]
	v_mfma_f32_16x16x32_bf16 v[8:11], v[210:213], v[186:189], v[8:11]
	v_mfma_f32_16x16x32_bf16 v[4:7], v[202:205], v[194:197], v[4:7]
	v_mfma_f32_16x16x32_bf16 v[0:3], v[210:213], v[194:197], v[0:3]
	s_add_i32 s73, s73, 2
	s_add_u32 s18, s18, 0x100
	s_addc_u32 s19, s19, 0
	s_add_u32 s29, s29, 0x100
	s_addc_u32 s72, s72, 0
	s_cmp_gt_u32 s73, 29
	s_barrier
	s_cbranch_scc0 .LBB0_243
.LBB0_243:
	ds_read_b128 v[150:153], v146
	ds_read_b128 v[154:157], v146 offset:1024
	ds_read_b128 v[158:161], v146 offset:2048
	ds_read_b128 v[162:165], v146 offset:3072
	s_add_u32 s36, s18, 0xfff80080
	s_addc_u32 s37, s19, -1
	s_cmp_eq_u32 s73, 28
	s_cselect_b32 s55, s11, s37
	s_cselect_b32 s54, s67, s36
	s_cselect_b32 s37, s9, s72
	s_cselect_b32 s36, s28, s29
	s_add_i32 m0, s56, 0xc000
	ds_read_b128 v[166:169], v147
	ds_read_b128 v[170:173], v147 offset:1024
	ds_read_b128 v[174:177], v147 offset:2048
	ds_read_b128 v[178:181], v147 offset:3072
	ds_read_b128 v[182:185], v147 offset:4096
	ds_read_b128 v[186:189], v147 offset:5120
	ds_read_b128 v[190:193], v147 offset:6144
	ds_read_b128 v[194:197], v147 offset:7168
	global_load_lds_dwordx4 v138, s[18:19]
	s_add_i32 m0, s56, 0xe000
	s_nop 0
	global_load_lds_dwordx4 v140, s[18:19]
	s_waitcnt lgkmcnt(8)
	s_barrier
	s_waitcnt lgkmcnt(0)
	v_mfma_f32_16x16x32_bf16 v[124:127], v[150:153], v[166:169], v[124:127]
	v_mfma_f32_16x16x32_bf16 v[120:123], v[158:161], v[166:169], v[120:123]
	v_mfma_f32_16x16x32_bf16 v[116:119], v[150:153], v[174:177], v[116:119]
	v_mfma_f32_16x16x32_bf16 v[108:111], v[158:161], v[174:177], v[108:111]
	v_mfma_f32_16x16x32_bf16 v[100:103], v[150:153], v[182:185], v[100:103]
	v_mfma_f32_16x16x32_bf16 v[96:99], v[158:161], v[182:185], v[96:99]
	v_mfma_f32_16x16x32_bf16 v[84:87], v[150:153], v[190:193], v[84:87]
	v_mfma_f32_16x16x32_bf16 v[80:83], v[158:161], v[190:193], v[80:83]
	v_mfma_f32_16x16x32_bf16 v[124:127], v[154:157], v[170:173], v[124:127]
	v_mfma_f32_16x16x32_bf16 v[120:123], v[162:165], v[170:173], v[120:123]
	v_mfma_f32_16x16x32_bf16 v[116:119], v[154:157], v[178:181], v[116:119]
	v_mfma_f32_16x16x32_bf16 v[108:111], v[162:165], v[178:181], v[108:111]
	v_mfma_f32_16x16x32_bf16 v[100:103], v[154:157], v[186:189], v[100:103]
	v_mfma_f32_16x16x32_bf16 v[96:99], v[162:165], v[186:189], v[96:99]
	v_mfma_f32_16x16x32_bf16 v[84:87], v[154:157], v[194:197], v[84:87]
	v_mfma_f32_16x16x32_bf16 v[80:83], v[162:165], v[194:197], v[80:83]
	s_barrier
	s_add_i32 s74, s63, s33
	s_add_u32 s98, s36, s6
	s_addc_u32 s99, s37, s7
	s_mov_b32 m0, s74
	ds_read_b128 v[198:201], v148
	ds_read_b128 v[202:205], v148 offset:1024
	ds_read_b128 v[206:209], v148 offset:2048
	ds_read_b128 v[210:213], v148 offset:3072
	global_load_lds_dwordx4 v130, s[36:37]
	s_add_i32 m0, s74, 0x2000
	s_nop 0
	global_load_lds_dwordx4 v134, s[36:37]
	s_barrier
	s_waitcnt lgkmcnt(0)
	v_mfma_f32_16x16x32_bf16 v[112:115], v[198:201], v[166:169], v[112:115]
	v_mfma_f32_16x16x32_bf16 v[104:107], v[206:209], v[166:169], v[104:107]
	v_mfma_f32_16x16x32_bf16 v[92:95], v[198:201], v[174:177], v[92:95]
	v_mfma_f32_16x16x32_bf16 v[88:91], v[206:209], v[174:177], v[88:91]
	v_mfma_f32_16x16x32_bf16 v[76:79], v[198:201], v[182:185], v[76:79]
	v_mfma_f32_16x16x32_bf16 v[72:75], v[206:209], v[182:185], v[72:75]
	v_mfma_f32_16x16x32_bf16 v[68:71], v[198:201], v[190:193], v[68:71]
	v_mfma_f32_16x16x32_bf16 v[64:67], v[206:209], v[190:193], v[64:67]
	v_mfma_f32_16x16x32_bf16 v[112:115], v[202:205], v[170:173], v[112:115]
	v_mfma_f32_16x16x32_bf16 v[104:107], v[210:213], v[170:173], v[104:107]
	v_mfma_f32_16x16x32_bf16 v[92:95], v[202:205], v[178:181], v[92:95]
	v_mfma_f32_16x16x32_bf16 v[88:91], v[210:213], v[178:181], v[88:91]
	v_mfma_f32_16x16x32_bf16 v[76:79], v[202:205], v[186:189], v[76:79]
	v_mfma_f32_16x16x32_bf16 v[72:75], v[210:213], v[186:189], v[72:75]
	v_mfma_f32_16x16x32_bf16 v[68:71], v[202:205], v[194:197], v[68:71]
	v_mfma_f32_16x16x32_bf16 v[64:67], v[210:213], v[194:197], v[64:67]
	s_mov_b32 m0, s56
	s_add_u32 s100, s54, s6
	s_addc_u32 s101, s55, s7
	s_barrier
	ds_read_b128 v[166:169], v147 offset:16384
	ds_read_b128 v[170:173], v147 offset:17408
	ds_read_b128 v[174:177], v147 offset:18432
	ds_read_b128 v[178:181], v147 offset:19456
	ds_read_b128 v[182:185], v147 offset:20480
	ds_read_b128 v[186:189], v147 offset:21504
	ds_read_b128 v[190:193], v147 offset:22528
	ds_read_b128 v[194:197], v147 offset:23552
	global_load_lds_dwordx4 v128, s[54:55]
	s_mov_b32 m0, s57
	s_nop 0
	global_load_lds_dwordx4 v132, s[54:55]
	s_barrier
	s_waitcnt lgkmcnt(0)
	v_mfma_f32_16x16x32_bf16 v[60:63], v[150:153], v[166:169], v[60:63]
	v_mfma_f32_16x16x32_bf16 v[56:59], v[158:161], v[166:169], v[56:59]
	v_mfma_f32_16x16x32_bf16 v[52:55], v[150:153], v[174:177], v[52:55]
	v_mfma_f32_16x16x32_bf16 v[48:51], v[158:161], v[174:177], v[48:51]
	v_mfma_f32_16x16x32_bf16 v[36:39], v[150:153], v[182:185], v[36:39]
	v_mfma_f32_16x16x32_bf16 v[32:35], v[158:161], v[182:185], v[32:35]
	v_mfma_f32_16x16x32_bf16 v[20:23], v[150:153], v[190:193], v[20:23]
	v_mfma_f32_16x16x32_bf16 v[16:19], v[158:161], v[190:193], v[16:19]
	v_mfma_f32_16x16x32_bf16 v[60:63], v[154:157], v[170:173], v[60:63]
	v_mfma_f32_16x16x32_bf16 v[56:59], v[162:165], v[170:173], v[56:59]
	v_mfma_f32_16x16x32_bf16 v[52:55], v[154:157], v[178:181], v[52:55]
	v_mfma_f32_16x16x32_bf16 v[48:51], v[162:165], v[178:181], v[48:51]
	v_mfma_f32_16x16x32_bf16 v[36:39], v[154:157], v[186:189], v[36:39]
	v_mfma_f32_16x16x32_bf16 v[32:35], v[162:165], v[186:189], v[32:35]
	v_mfma_f32_16x16x32_bf16 v[20:23], v[154:157], v[194:197], v[20:23]
	v_mfma_f32_16x16x32_bf16 v[16:19], v[162:165], v[194:197], v[16:19]
	s_barrier
	s_add_u32 s74, s36, 0x80000
	s_addc_u32 s75, s37, 0
	s_add_i32 s76, s64, s33
	s_mov_b32 m0, s76
	s_nop 0
	global_load_lds_dwordx4 v130, s[74:75]
	s_add_i32 m0, s76, 0x2000
	s_nop 0
	global_load_lds_dwordx4 v134, s[74:75]
	s_waitcnt vmcnt(6)
	s_barrier
	v_mfma_f32_16x16x32_bf16 v[44:47], v[198:201], v[166:169], v[44:47]
	v_mfma_f32_16x16x32_bf16 v[40:43], v[206:209], v[166:169], v[40:43]
	v_mfma_f32_16x16x32_bf16 v[28:31], v[198:201], v[174:177], v[28:31]
	v_mfma_f32_16x16x32_bf16 v[24:27], v[206:209], v[174:177], v[24:27]
	v_mfma_f32_16x16x32_bf16 v[12:15], v[198:201], v[182:185], v[12:15]
	v_mfma_f32_16x16x32_bf16 v[8:11], v[206:209], v[182:185], v[8:11]
	v_mfma_f32_16x16x32_bf16 v[4:7], v[198:201], v[190:193], v[4:7]
	v_mfma_f32_16x16x32_bf16 v[0:3], v[206:209], v[190:193], v[0:3]
	v_mfma_f32_16x16x32_bf16 v[44:47], v[202:205], v[170:173], v[44:47]
	v_mfma_f32_16x16x32_bf16 v[40:43], v[210:213], v[170:173], v[40:43]
	v_mfma_f32_16x16x32_bf16 v[28:31], v[202:205], v[178:181], v[28:31]
	v_mfma_f32_16x16x32_bf16 v[24:27], v[210:213], v[178:181], v[24:27]
	v_mfma_f32_16x16x32_bf16 v[12:15], v[202:205], v[186:189], v[12:15]
	v_mfma_f32_16x16x32_bf16 v[8:11], v[210:213], v[186:189], v[8:11]
	v_mfma_f32_16x16x32_bf16 v[4:7], v[202:205], v[194:197], v[4:7]
	v_mfma_f32_16x16x32_bf16 v[0:3], v[210:213], v[194:197], v[0:3]
	s_add_i32 s74, 0, 0x18000
	s_barrier
	ds_read_b128 v[150:153], v244
	ds_read_b128 v[154:157], v244 offset:1024
	ds_read_b128 v[158:161], v244 offset:2048
	ds_read_b128 v[162:165], v244 offset:3072
	s_add_u32 s54, s54, 0x80000
	s_addc_u32 s55, s55, 0
	s_mov_b32 m0, s58
	ds_read_b128 v[166:169], v147 offset:32768
	ds_read_b128 v[170:173], v147 offset:33792
	ds_read_b128 v[174:177], v147 offset:34816
	ds_read_b128 v[178:181], v147 offset:35840
	ds_read_b128 v[182:185], v147 offset:36864
	ds_read_b128 v[186:189], v147 offset:37888
	ds_read_b128 v[190:193], v147 offset:38912
	ds_read_b128 v[194:197], v147 offset:39936
	global_load_lds_dwordx4 v128, s[54:55]
	s_mov_b32 m0, s59
	s_nop 0
	global_load_lds_dwordx4 v132, s[54:55]
	s_waitcnt lgkmcnt(8)
	s_barrier
	s_waitcnt lgkmcnt(0)
	v_mfma_f32_16x16x32_bf16 v[124:127], v[150:153], v[166:169], v[124:127]
	v_mfma_f32_16x16x32_bf16 v[120:123], v[158:161], v[166:169], v[120:123]
	v_mfma_f32_16x16x32_bf16 v[116:119], v[150:153], v[174:177], v[116:119]
	v_mfma_f32_16x16x32_bf16 v[108:111], v[158:161], v[174:177], v[108:111]
	v_mfma_f32_16x16x32_bf16 v[100:103], v[150:153], v[182:185], v[100:103]
	v_mfma_f32_16x16x32_bf16 v[96:99], v[158:161], v[182:185], v[96:99]
	v_mfma_f32_16x16x32_bf16 v[84:87], v[150:153], v[190:193], v[84:87]
	v_mfma_f32_16x16x32_bf16 v[80:83], v[158:161], v[190:193], v[80:83]
	v_mfma_f32_16x16x32_bf16 v[124:127], v[154:157], v[170:173], v[124:127]
	v_mfma_f32_16x16x32_bf16 v[120:123], v[162:165], v[170:173], v[120:123]
	v_mfma_f32_16x16x32_bf16 v[116:119], v[154:157], v[178:181], v[116:119]
	v_mfma_f32_16x16x32_bf16 v[108:111], v[162:165], v[178:181], v[108:111]
	v_mfma_f32_16x16x32_bf16 v[100:103], v[154:157], v[186:189], v[100:103]
	v_mfma_f32_16x16x32_bf16 v[96:99], v[162:165], v[186:189], v[96:99]
	v_mfma_f32_16x16x32_bf16 v[84:87], v[154:157], v[194:197], v[84:87]
	v_mfma_f32_16x16x32_bf16 v[80:83], v[162:165], v[194:197], v[80:83]
	s_barrier
	s_add_i32 s54, 0, 0x1c000
	s_add_i32 s55, s74, s33
	s_mov_b32 m0, s55
	ds_read_b128 v[198:201], v245
	ds_read_b128 v[202:205], v245 offset:1024
	ds_read_b128 v[206:209], v245 offset:2048
	ds_read_b128 v[210:213], v245 offset:3072
	global_load_lds_dwordx4 v130, s[98:99]
	s_add_i32 m0, s55, 0x2000
	s_nop 0
	global_load_lds_dwordx4 v134, s[98:99]
	s_barrier
	s_waitcnt lgkmcnt(0)
	v_mfma_f32_16x16x32_bf16 v[112:115], v[198:201], v[166:169], v[112:115]
	v_mfma_f32_16x16x32_bf16 v[104:107], v[206:209], v[166:169], v[104:107]
	v_mfma_f32_16x16x32_bf16 v[92:95], v[198:201], v[174:177], v[92:95]
	v_mfma_f32_16x16x32_bf16 v[88:91], v[206:209], v[174:177], v[88:91]
	v_mfma_f32_16x16x32_bf16 v[76:79], v[198:201], v[182:185], v[76:79]
	v_mfma_f32_16x16x32_bf16 v[72:75], v[206:209], v[182:185], v[72:75]
	v_mfma_f32_16x16x32_bf16 v[68:71], v[198:201], v[190:193], v[68:71]
	v_mfma_f32_16x16x32_bf16 v[64:67], v[206:209], v[190:193], v[64:67]
	v_mfma_f32_16x16x32_bf16 v[112:115], v[202:205], v[170:173], v[112:115]
	v_mfma_f32_16x16x32_bf16 v[104:107], v[210:213], v[170:173], v[104:107]
	v_mfma_f32_16x16x32_bf16 v[92:95], v[202:205], v[178:181], v[92:95]
	v_mfma_f32_16x16x32_bf16 v[88:91], v[210:213], v[178:181], v[88:91]
	v_mfma_f32_16x16x32_bf16 v[76:79], v[202:205], v[186:189], v[76:79]
	v_mfma_f32_16x16x32_bf16 v[72:75], v[210:213], v[186:189], v[72:75]
	v_mfma_f32_16x16x32_bf16 v[68:71], v[202:205], v[194:197], v[68:71]
	v_mfma_f32_16x16x32_bf16 v[64:67], v[210:213], v[194:197], v[64:67]
	s_mov_b32 m0, s60
	s_barrier
	ds_read_b128 v[166:169], v147 offset:49152
	ds_read_b128 v[170:173], v147 offset:50176
	ds_read_b128 v[174:177], v147 offset:51200
	ds_read_b128 v[178:181], v147 offset:52224
	ds_read_b128 v[182:185], v147 offset:53248
	ds_read_b128 v[186:189], v147 offset:54272
	ds_read_b128 v[190:193], v147 offset:55296
	ds_read_b128 v[194:197], v147 offset:56320
	global_load_lds_dwordx4 v128, s[100:101]
	s_mov_b32 m0, s61
	s_nop 0
	global_load_lds_dwordx4 v132, s[100:101]
	s_barrier
	s_waitcnt lgkmcnt(0)
	v_mfma_f32_16x16x32_bf16 v[60:63], v[150:153], v[166:169], v[60:63]
	v_mfma_f32_16x16x32_bf16 v[56:59], v[158:161], v[166:169], v[56:59]
	v_mfma_f32_16x16x32_bf16 v[52:55], v[150:153], v[174:177], v[52:55]
	v_mfma_f32_16x16x32_bf16 v[48:51], v[158:161], v[174:177], v[48:51]
	v_mfma_f32_16x16x32_bf16 v[36:39], v[150:153], v[182:185], v[36:39]
	v_mfma_f32_16x16x32_bf16 v[32:35], v[158:161], v[182:185], v[32:35]
	v_mfma_f32_16x16x32_bf16 v[20:23], v[150:153], v[190:193], v[20:23]
	v_mfma_f32_16x16x32_bf16 v[16:19], v[158:161], v[190:193], v[16:19]
	v_mfma_f32_16x16x32_bf16 v[60:63], v[154:157], v[170:173], v[60:63]
	v_mfma_f32_16x16x32_bf16 v[56:59], v[162:165], v[170:173], v[56:59]
	v_mfma_f32_16x16x32_bf16 v[52:55], v[154:157], v[178:181], v[52:55]
	v_mfma_f32_16x16x32_bf16 v[48:51], v[162:165], v[178:181], v[48:51]
	v_mfma_f32_16x16x32_bf16 v[36:39], v[154:157], v[186:189], v[36:39]
	v_mfma_f32_16x16x32_bf16 v[32:35], v[162:165], v[186:189], v[32:35]
	v_mfma_f32_16x16x32_bf16 v[20:23], v[154:157], v[194:197], v[20:23]
	v_mfma_f32_16x16x32_bf16 v[16:19], v[162:165], v[194:197], v[16:19]
	s_barrier
	s_add_u32 s36, s36, 0x80080
	s_addc_u32 s37, s37, 0
	s_add_i32 s54, s54, s33
	s_mov_b32 m0, s54
	s_nop 0
	global_load_lds_dwordx4 v130, s[36:37]
	s_add_i32 m0, s54, 0x2000
	s_nop 0
	global_load_lds_dwordx4 v134, s[36:37]
	s_waitcnt vmcnt(6)
	s_barrier
	v_mfma_f32_16x16x32_bf16 v[44:47], v[198:201], v[166:169], v[44:47]
	v_mfma_f32_16x16x32_bf16 v[40:43], v[206:209], v[166:169], v[40:43]
	v_mfma_f32_16x16x32_bf16 v[28:31], v[198:201], v[174:177], v[28:31]
	v_mfma_f32_16x16x32_bf16 v[24:27], v[206:209], v[174:177], v[24:27]
	v_mfma_f32_16x16x32_bf16 v[12:15], v[198:201], v[182:185], v[12:15]
	v_mfma_f32_16x16x32_bf16 v[8:11], v[206:209], v[182:185], v[8:11]
	v_mfma_f32_16x16x32_bf16 v[4:7], v[198:201], v[190:193], v[4:7]
	v_mfma_f32_16x16x32_bf16 v[0:3], v[206:209], v[190:193], v[0:3]
	v_mfma_f32_16x16x32_bf16 v[44:47], v[202:205], v[170:173], v[44:47]
	v_mfma_f32_16x16x32_bf16 v[40:43], v[210:213], v[170:173], v[40:43]
	v_mfma_f32_16x16x32_bf16 v[28:31], v[202:205], v[178:181], v[28:31]
	v_mfma_f32_16x16x32_bf16 v[24:27], v[210:213], v[178:181], v[24:27]
	v_mfma_f32_16x16x32_bf16 v[12:15], v[202:205], v[186:189], v[12:15]
	v_mfma_f32_16x16x32_bf16 v[8:11], v[210:213], v[186:189], v[8:11]
	v_mfma_f32_16x16x32_bf16 v[4:7], v[202:205], v[194:197], v[4:7]
	v_mfma_f32_16x16x32_bf16 v[0:3], v[210:213], v[194:197], v[0:3]
	s_add_i32 s73, s73, 2
	s_add_u32 s18, s18, 0x100
	s_addc_u32 s19, s19, 0
	s_add_u32 s29, s29, 0x100
	s_addc_u32 s72, s72, 0
	s_cmp_gt_u32 s73, 29
	s_barrier
	s_cbranch_scc0 .LBB0_243
	v_lshl_add_u32 v150, s66, 8, v142
	v_lshl_or_b32 v149, s0, 8, v145
	v_ashrrev_i32_e32 v151, 31, v150
	v_cvt_pk_bf16_f32 v124, v124, v125
	v_cvt_pk_bf16_f32 v125, v126, v127
	v_cvt_pk_bf16_f32 v127, v122, v123
	v_ashrrev_i32_e32 v122, 4, v149
	v_cvt_pk_bf16_f32 v126, v120, v121
	v_mad_i64_i32 v[120:121], s[18:19], v122, s65, v[150:151]
	v_lshlrev_b64 v[120:121], 5, v[120:121]
	v_lshl_add_u64 v[120:121], v[136:137], 0, v[120:121]
	global_store_dwordx4 v[120:121], v[124:127], off
	v_or_b32_e32 v120, 8, v122
	v_cvt_pk_bf16_f32 v112, v112, v113
	v_cvt_pk_bf16_f32 v113, v114, v115
	v_cvt_pk_bf16_f32 v114, v104, v105
	v_mad_i64_i32 v[104:105], s[18:19], v120, s65, v[150:151]
	v_lshlrev_b64 v[104:105], 5, v[104:105]
	v_cvt_pk_bf16_f32 v115, v106, v107
	v_lshl_add_u64 v[104:105], v[136:137], 0, v[104:105]
	global_store_dwordx4 v[104:105], v[112:115], off
	v_cvt_pk_bf16_f32 v92, v92, v93
	v_cvt_pk_bf16_f32 v93, v94, v95
	v_or_b32_e32 v112, 16, v150
	v_ashrrev_i32_e32 v113, 31, v112
	v_cvt_pk_bf16_f32 v94, v88, v89
	v_mad_i64_i32 v[88:89], s[18:19], v120, s65, v[112:113]
	v_lshlrev_b64 v[88:89], 5, v[88:89]
	v_cvt_pk_bf16_f32 v95, v90, v91
	v_lshl_add_u64 v[88:89], v[136:137], 0, v[88:89]
	global_store_dwordx4 v[88:89], v[92:95], off
	v_cvt_pk_bf16_f32 v76, v76, v77
	v_cvt_pk_bf16_f32 v77, v78, v79
	v_or_b32_e32 v92, 32, v150
	v_ashrrev_i32_e32 v93, 31, v92
	v_cvt_pk_bf16_f32 v78, v72, v73
	v_mad_i64_i32 v[72:73], s[18:19], v120, s65, v[92:93]
	v_lshlrev_b64 v[72:73], 5, v[72:73]
	v_cvt_pk_bf16_f32 v79, v74, v75
	v_lshl_add_u64 v[72:73], v[136:137], 0, v[72:73]
	global_store_dwordx4 v[72:73], v[76:79], off
	v_cvt_pk_bf16_f32 v68, v68, v69
	v_cvt_pk_bf16_f32 v69, v70, v71
	v_or_b32_e32 v76, 48, v150
	v_ashrrev_i32_e32 v77, 31, v76
	v_cvt_pk_bf16_f32 v70, v64, v65
	v_mad_i64_i32 v[64:65], s[18:19], v120, s65, v[76:77]
	v_lshlrev_b64 v[64:65], 5, v[64:65]
	v_cvt_pk_bf16_f32 v71, v66, v67
	v_lshl_add_u64 v[64:65], v[136:137], 0, v[64:65]
	global_store_dwordx4 v[64:65], v[68:71], off
	v_add_u32_e32 v64, 0x80, v150
	v_ashrrev_i32_e32 v65, 31, v64
	v_cvt_pk_bf16_f32 v44, v44, v45
	v_cvt_pk_bf16_f32 v45, v46, v47
	v_cvt_pk_bf16_f32 v46, v40, v41
	v_mad_i64_i32 v[40:41], s[18:19], v120, s65, v[64:65]
	v_lshlrev_b64 v[40:41], 5, v[40:41]
	v_cvt_pk_bf16_f32 v47, v42, v43
	v_lshl_add_u64 v[40:41], v[136:137], 0, v[40:41]
	global_store_dwordx4 v[40:41], v[44:47], off
	v_cvt_pk_bf16_f32 v106, v108, v109
	v_mad_i64_i32 v[108:109], s[18:19], v122, s65, v[112:113]
	v_add_u32_e32 v44, 0x90, v150
	v_ashrrev_i32_e32 v45, 31, v44
	v_cvt_pk_bf16_f32 v28, v28, v29
	v_cvt_pk_bf16_f32 v29, v30, v31
	v_cvt_pk_bf16_f32 v30, v24, v25
	v_mad_i64_i32 v[24:25], s[18:19], v120, s65, v[44:45]
	v_lshlrev_b64 v[108:109], 5, v[108:109]
	v_lshlrev_b64 v[24:25], 5, v[24:25]
	v_cvt_pk_bf16_f32 v104, v116, v117
	v_cvt_pk_bf16_f32 v105, v118, v119
	v_cvt_pk_bf16_f32 v107, v110, v111
	v_lshl_add_u64 v[108:109], v[136:137], 0, v[108:109]
	v_cvt_pk_bf16_f32 v31, v26, v27
	v_lshl_add_u64 v[24:25], v[136:137], 0, v[24:25]
	global_store_dwordx4 v[108:109], v[104:107], off
	global_store_dwordx4 v[24:25], v[28:31], off
	v_mad_i64_i32 v[94:95], s[18:19], v122, s65, v[92:93]
	s_nop 0
	v_add_u32_e32 v28, 0xa0, v150
	v_ashrrev_i32_e32 v29, 31, v28
	v_cvt_pk_bf16_f32 v12, v12, v13
	v_cvt_pk_bf16_f32 v13, v14, v15
	v_cvt_pk_bf16_f32 v14, v8, v9
	v_mad_i64_i32 v[8:9], s[18:19], v120, s65, v[28:29]
	v_lshlrev_b64 v[94:95], 5, v[94:95]
	v_lshlrev_b64 v[8:9], 5, v[8:9]
	v_cvt_pk_bf16_f32 v88, v100, v101
	v_cvt_pk_bf16_f32 v89, v102, v103
	v_cvt_pk_bf16_f32 v90, v96, v97
	v_cvt_pk_bf16_f32 v91, v98, v99
	v_lshl_add_u64 v[94:95], v[136:137], 0, v[94:95]
	v_cvt_pk_bf16_f32 v15, v10, v11
	v_lshl_add_u64 v[8:9], v[136:137], 0, v[8:9]
	global_store_dwordx4 v[94:95], v[88:91], off
	global_store_dwordx4 v[8:9], v[12:15], off
	v_mad_i64_i32 v[78:79], s[18:19], v122, s65, v[76:77]
	s_nop 0
	v_add_u32_e32 v12, 0xb0, v150
	v_ashrrev_i32_e32 v13, 31, v12
	v_cvt_pk_bf16_f32 v60, v60, v61
	v_cvt_pk_bf16_f32 v61, v62, v63
	v_cvt_pk_bf16_f32 v62, v56, v57
	v_mad_i64_i32 v[56:57], s[18:19], v122, s65, v[64:65]
	v_mad_i64_i32 v[46:47], s[18:19], v122, s65, v[44:45]
	v_mad_i64_i32 v[30:31], s[18:19], v122, s65, v[28:29]
	v_mad_i64_i32 v[14:15], s[18:19], v122, s65, v[12:13]
	v_cvt_pk_bf16_f32 v4, v4, v5
	v_cvt_pk_bf16_f32 v5, v6, v7
	v_cvt_pk_bf16_f32 v6, v0, v1
	v_mad_i64_i32 v[0:1], s[18:19], v120, s65, v[12:13]
	v_lshlrev_b64 v[78:79], 5, v[78:79]
	v_lshlrev_b64 v[56:57], 5, v[56:57]
	v_lshlrev_b64 v[46:47], 5, v[46:47]
	v_lshlrev_b64 v[30:31], 5, v[30:31]
	v_lshlrev_b64 v[14:15], 5, v[14:15]
	v_lshlrev_b64 v[0:1], 5, v[0:1]
	v_cvt_pk_bf16_f32 v72, v84, v85
	v_cvt_pk_bf16_f32 v73, v86, v87
	v_cvt_pk_bf16_f32 v74, v80, v81
	v_cvt_pk_bf16_f32 v75, v82, v83
	v_lshl_add_u64 v[78:79], v[136:137], 0, v[78:79]
	v_cvt_pk_bf16_f32 v63, v58, v59
	v_lshl_add_u64 v[56:57], v[136:137], 0, v[56:57]
	v_cvt_pk_bf16_f32 v40, v52, v53
	v_cvt_pk_bf16_f32 v41, v54, v55
	v_cvt_pk_bf16_f32 v42, v48, v49
	v_cvt_pk_bf16_f32 v43, v50, v51
	v_lshl_add_u64 v[46:47], v[136:137], 0, v[46:47]
	v_cvt_pk_bf16_f32 v24, v36, v37
	v_cvt_pk_bf16_f32 v25, v38, v39
	v_cvt_pk_bf16_f32 v26, v32, v33
	v_cvt_pk_bf16_f32 v27, v34, v35
	v_lshl_add_u64 v[30:31], v[136:137], 0, v[30:31]
	v_cvt_pk_bf16_f32 v8, v20, v21
	v_cvt_pk_bf16_f32 v9, v22, v23
	v_cvt_pk_bf16_f32 v10, v16, v17
	v_cvt_pk_bf16_f32 v11, v18, v19
	v_lshl_add_u64 v[14:15], v[136:137], 0, v[14:15]
	v_cvt_pk_bf16_f32 v7, v2, v3
	v_lshl_add_u64 v[0:1], v[136:137], 0, v[0:1]
	s_and_b64 vcc, exec, s[14:15]
	s_mov_b32 s0, s8
	s_mov_b32 s66, s10
	s_mov_b64 s[36:37], s[16:17]
	s_mov_b64 s[18:19], s[12:13]
	global_store_dwordx4 v[78:79], v[72:75], off
	global_store_dwordx4 v[56:57], v[60:63], off
	global_store_dwordx4 v[46:47], v[40:43], off
	global_store_dwordx4 v[30:31], v[24:27], off
	global_store_dwordx4 v[14:15], v[8:11], off
	global_store_dwordx4 v[0:1], v[4:7], off
	s_cbranch_vccz .LBB0_239
	s_waitcnt vmcnt(0)
	s_cmpk_gt_u32 s2, 0xff
	s_cbranch_scc1 .LBB0_247
	s_barrier

.LBB0_329:
	s_ashr_i32 s15, s14, 31
	s_xor_b64 s[16:17], s[28:29], -1
	s_lshl_b64 s[18:19], s[14:15], 20
	s_add_u32 s18, s58, s18
	s_addc_u32 s19, s59, s19
	s_and_b64 s[30:31], s[28:29], exec
	s_cselect_b32 s1, s19, s37
	s_cselect_b32 s15, s18, s36
	s_ashr_i32 s13, s12, 31
	s_lshl_b64 s[30:31], s[12:13], 20
	s_add_u32 s30, s22, s30
	s_addc_u32 s31, s23, s31
	s_and_b64 s[28:29], s[28:29], exec
	s_cselect_b32 s13, s31, s55
	s_cselect_b32 s28, s30, s54
	s_add_u32 s36, s36, 0x80080
	s_addc_u32 s37, s37, 0
	s_add_u32 s29, s54, 0x100
	s_addc_u32 s35, s55, 0
	s_mov_b32 s78, -2
	v_add_u32_e32 v244, 0x18000, v150
	v_add_u32_e32 v245, 0x1c000, v150
	ds_read_b128 v[146:149], v152
	ds_read_b128 v[156:159], v152 offset:1024
	ds_read_b128 v[160:163], v152 offset:2048
	ds_read_b128 v[164:167], v152 offset:3072
	s_add_u32 s54, s36, 0xfff80080
	s_addc_u32 s55, s37, -1
	s_cmp_eq_u32 s78, 28
	s_cselect_b32 s57, s1, s55
	s_cselect_b32 s56, s15, s54
	s_cselect_b32 s55, s13, s35
	s_cselect_b32 s54, s28, s29
	s_add_i32 m0, s61, 0xc000
	ds_read_b128 v[168:171], v153
	ds_read_b128 v[172:175], v153 offset:1024
	ds_read_b128 v[176:179], v153 offset:2048
	ds_read_b128 v[180:183], v153 offset:3072
	ds_read_b128 v[184:187], v153 offset:4096
	ds_read_b128 v[188:191], v153 offset:5120
	ds_read_b128 v[192:195], v153 offset:6144
	ds_read_b128 v[196:199], v153 offset:7168
	global_load_lds_dwordx4 v138, s[36:37]
	s_add_i32 m0, s61, 0xe000
	s_nop 0
	global_load_lds_dwordx4 v140, s[36:37]
	s_waitcnt lgkmcnt(8)
	s_barrier
	s_waitcnt lgkmcnt(0)
	v_mfma_f32_16x16x32_bf16 v[124:127], v[146:149], v[168:171], 0
	v_mfma_f32_16x16x32_bf16 v[120:123], v[160:163], v[168:171], 0
	v_mfma_f32_16x16x32_bf16 v[108:111], v[146:149], v[176:179], 0
	v_mfma_f32_16x16x32_bf16 v[104:107], v[160:163], v[176:179], 0
	v_mfma_f32_16x16x32_bf16 v[92:95], v[146:149], v[184:187], 0
	v_mfma_f32_16x16x32_bf16 v[88:91], v[160:163], v[184:187], 0
	v_mfma_f32_16x16x32_bf16 v[76:79], v[146:149], v[192:195], 0
	v_mfma_f32_16x16x32_bf16 v[72:75], v[160:163], v[192:195], 0
	v_mfma_f32_16x16x32_bf16 v[124:127], v[156:159], v[172:175], v[124:127]
	v_mfma_f32_16x16x32_bf16 v[120:123], v[164:167], v[172:175], v[120:123]
	v_mfma_f32_16x16x32_bf16 v[108:111], v[156:159], v[180:183], v[108:111]
	v_mfma_f32_16x16x32_bf16 v[104:107], v[164:167], v[180:183], v[104:107]
	v_mfma_f32_16x16x32_bf16 v[92:95], v[156:159], v[188:191], v[92:95]
	v_mfma_f32_16x16x32_bf16 v[88:91], v[164:167], v[188:191], v[88:91]
	v_mfma_f32_16x16x32_bf16 v[76:79], v[156:159], v[196:199], v[76:79]
	v_mfma_f32_16x16x32_bf16 v[72:75], v[164:167], v[196:199], v[72:75]
	s_barrier
	s_add_i32 s79, s75, s60
	s_add_u32 s98, s54, s10
	s_addc_u32 s99, s55, s11
	s_mov_b32 m0, s79
	ds_read_b128 v[200:203], v154
	ds_read_b128 v[204:207], v154 offset:1024
	ds_read_b128 v[208:211], v154 offset:2048
	ds_read_b128 v[212:215], v154 offset:3072
	global_load_lds_dwordx4 v130, s[54:55]
	s_add_i32 m0, s79, 0x2000
	s_nop 0
	global_load_lds_dwordx4 v134, s[54:55]
	s_barrier
	s_waitcnt lgkmcnt(0)
	v_mfma_f32_16x16x32_bf16 v[116:119], v[200:203], v[168:171], 0
	v_mfma_f32_16x16x32_bf16 v[112:115], v[208:211], v[168:171], 0
	v_mfma_f32_16x16x32_bf16 v[100:103], v[200:203], v[176:179], 0
	v_mfma_f32_16x16x32_bf16 v[96:99], v[208:211], v[176:179], 0
	v_mfma_f32_16x16x32_bf16 v[84:87], v[200:203], v[184:187], 0
	v_mfma_f32_16x16x32_bf16 v[80:83], v[208:211], v[184:187], 0
	v_mfma_f32_16x16x32_bf16 v[68:71], v[200:203], v[192:195], 0
	v_mfma_f32_16x16x32_bf16 v[64:67], v[208:211], v[192:195], 0
	v_mfma_f32_16x16x32_bf16 v[116:119], v[204:207], v[172:175], v[116:119]
	v_mfma_f32_16x16x32_bf16 v[112:115], v[212:215], v[172:175], v[112:115]
	v_mfma_f32_16x16x32_bf16 v[100:103], v[204:207], v[180:183], v[100:103]
	v_mfma_f32_16x16x32_bf16 v[96:99], v[212:215], v[180:183], v[96:99]
	v_mfma_f32_16x16x32_bf16 v[84:87], v[204:207], v[188:191], v[84:87]
	v_mfma_f32_16x16x32_bf16 v[80:83], v[212:215], v[188:191], v[80:83]
	v_mfma_f32_16x16x32_bf16 v[68:71], v[204:207], v[196:199], v[68:71]
	v_mfma_f32_16x16x32_bf16 v[64:67], v[212:215], v[196:199], v[64:67]
	s_mov_b32 m0, s61
	s_add_u32 s100, s56, s10
	s_addc_u32 s101, s57, s11
	s_barrier
	ds_read_b128 v[168:171], v153 offset:16384
	ds_read_b128 v[172:175], v153 offset:17408
	ds_read_b128 v[176:179], v153 offset:18432
	ds_read_b128 v[180:183], v153 offset:19456
	ds_read_b128 v[184:187], v153 offset:20480
	ds_read_b128 v[188:191], v153 offset:21504
	ds_read_b128 v[192:195], v153 offset:22528
	ds_read_b128 v[196:199], v153 offset:23552
	global_load_lds_dwordx4 v128, s[56:57]
	s_mov_b32 m0, s62
	s_nop 0
	global_load_lds_dwordx4 v132, s[56:57]
	s_barrier
	s_waitcnt lgkmcnt(0)
	v_mfma_f32_16x16x32_bf16 v[60:63], v[146:149], v[168:171], 0
	v_mfma_f32_16x16x32_bf16 v[56:59], v[160:163], v[168:171], 0
	v_mfma_f32_16x16x32_bf16 v[44:47], v[146:149], v[176:179], 0
	v_mfma_f32_16x16x32_bf16 v[40:43], v[160:163], v[176:179], 0
	v_mfma_f32_16x16x32_bf16 v[28:31], v[146:149], v[184:187], 0
	v_mfma_f32_16x16x32_bf16 v[24:27], v[160:163], v[184:187], 0
	v_mfma_f32_16x16x32_bf16 v[12:15], v[146:149], v[192:195], 0
	v_mfma_f32_16x16x32_bf16 v[8:11], v[160:163], v[192:195], 0
	v_mfma_f32_16x16x32_bf16 v[60:63], v[156:159], v[172:175], v[60:63]
	v_mfma_f32_16x16x32_bf16 v[56:59], v[164:167], v[172:175], v[56:59]
	v_mfma_f32_16x16x32_bf16 v[44:47], v[156:159], v[180:183], v[44:47]
	v_mfma_f32_16x16x32_bf16 v[40:43], v[164:167], v[180:183], v[40:43]
	v_mfma_f32_16x16x32_bf16 v[28:31], v[156:159], v[188:191], v[28:31]
	v_mfma_f32_16x16x32_bf16 v[24:27], v[164:167], v[188:191], v[24:27]
	v_mfma_f32_16x16x32_bf16 v[12:15], v[156:159], v[196:199], v[12:15]
	v_mfma_f32_16x16x32_bf16 v[8:11], v[164:167], v[196:199], v[8:11]
	s_barrier
	s_add_u32 s80, s54, 0x80000
	s_addc_u32 s81, s55, 0
	s_add_i32 s79, s76, s60
	s_mov_b32 m0, s79
	s_nop 0
	global_load_lds_dwordx4 v130, s[80:81]
	s_add_i32 m0, s79, 0x2000
	s_nop 0
	global_load_lds_dwordx4 v134, s[80:81]
	s_waitcnt vmcnt(6)
	s_barrier
	v_mfma_f32_16x16x32_bf16 v[52:55], v[200:203], v[168:171], 0
	v_mfma_f32_16x16x32_bf16 v[48:51], v[208:211], v[168:171], 0
	v_mfma_f32_16x16x32_bf16 v[36:39], v[200:203], v[176:179], 0
	v_mfma_f32_16x16x32_bf16 v[32:35], v[208:211], v[176:179], 0
	v_mfma_f32_16x16x32_bf16 v[20:23], v[200:203], v[184:187], 0
	v_mfma_f32_16x16x32_bf16 v[16:19], v[208:211], v[184:187], 0
	v_mfma_f32_16x16x32_bf16 v[4:7], v[200:203], v[192:195], 0
	v_mfma_f32_16x16x32_bf16 v[0:3], v[208:211], v[192:195], 0
	v_mfma_f32_16x16x32_bf16 v[52:55], v[204:207], v[172:175], v[52:55]
	v_mfma_f32_16x16x32_bf16 v[48:51], v[212:215], v[172:175], v[48:51]
	v_mfma_f32_16x16x32_bf16 v[36:39], v[204:207], v[180:183], v[36:39]
	v_mfma_f32_16x16x32_bf16 v[32:35], v[212:215], v[180:183], v[32:35]
	v_mfma_f32_16x16x32_bf16 v[20:23], v[204:207], v[188:191], v[20:23]
	v_mfma_f32_16x16x32_bf16 v[16:19], v[212:215], v[188:191], v[16:19]
	v_mfma_f32_16x16x32_bf16 v[4:7], v[204:207], v[196:199], v[4:7]
	v_mfma_f32_16x16x32_bf16 v[0:3], v[212:215], v[196:199], v[0:3]
	s_add_i32 s79, 0, 0x18000
	s_barrier
	ds_read_b128 v[146:149], v244
	ds_read_b128 v[156:159], v244 offset:1024
	ds_read_b128 v[160:163], v244 offset:2048
	ds_read_b128 v[164:167], v244 offset:3072
	s_add_u32 s56, s56, 0x80000
	s_addc_u32 s57, s57, 0
	s_mov_b32 m0, s63
	ds_read_b128 v[168:171], v153 offset:32768
	ds_read_b128 v[172:175], v153 offset:33792
	ds_read_b128 v[176:179], v153 offset:34816
	ds_read_b128 v[180:183], v153 offset:35840
	ds_read_b128 v[184:187], v153 offset:36864
	ds_read_b128 v[188:191], v153 offset:37888
	ds_read_b128 v[192:195], v153 offset:38912
	ds_read_b128 v[196:199], v153 offset:39936
	global_load_lds_dwordx4 v128, s[56:57]
	s_mov_b32 m0, s64
	s_nop 0
	global_load_lds_dwordx4 v132, s[56:57]
	s_waitcnt lgkmcnt(8)
	s_barrier
	s_waitcnt lgkmcnt(0)
	v_mfma_f32_16x16x32_bf16 v[124:127], v[146:149], v[168:171], v[124:127]
	v_mfma_f32_16x16x32_bf16 v[120:123], v[160:163], v[168:171], v[120:123]
	v_mfma_f32_16x16x32_bf16 v[108:111], v[146:149], v[176:179], v[108:111]
	v_mfma_f32_16x16x32_bf16 v[104:107], v[160:163], v[176:179], v[104:107]
	v_mfma_f32_16x16x32_bf16 v[92:95], v[146:149], v[184:187], v[92:95]
	v_mfma_f32_16x16x32_bf16 v[88:91], v[160:163], v[184:187], v[88:91]
	v_mfma_f32_16x16x32_bf16 v[76:79], v[146:149], v[192:195], v[76:79]
	v_mfma_f32_16x16x32_bf16 v[72:75], v[160:163], v[192:195], v[72:75]
	v_mfma_f32_16x16x32_bf16 v[124:127], v[156:159], v[172:175], v[124:127]
	v_mfma_f32_16x16x32_bf16 v[120:123], v[164:167], v[172:175], v[120:123]
	v_mfma_f32_16x16x32_bf16 v[108:111], v[156:159], v[180:183], v[108:111]
	v_mfma_f32_16x16x32_bf16 v[104:107], v[164:167], v[180:183], v[104:107]
	v_mfma_f32_16x16x32_bf16 v[92:95], v[156:159], v[188:191], v[92:95]
	v_mfma_f32_16x16x32_bf16 v[88:91], v[164:167], v[188:191], v[88:91]
	v_mfma_f32_16x16x32_bf16 v[76:79], v[156:159], v[196:199], v[76:79]
	v_mfma_f32_16x16x32_bf16 v[72:75], v[164:167], v[196:199], v[72:75]
	s_barrier
	s_add_i32 s56, 0, 0x1c000
	s_add_i32 s57, s79, s60
	s_mov_b32 m0, s57
	ds_read_b128 v[200:203], v245
	ds_read_b128 v[204:207], v245 offset:1024
	ds_read_b128 v[208:211], v245 offset:2048
	ds_read_b128 v[212:215], v245 offset:3072
	global_load_lds_dwordx4 v130, s[98:99]
	s_add_i32 m0, s57, 0x2000
	s_nop 0
	global_load_lds_dwordx4 v134, s[98:99]
	s_barrier
	s_waitcnt lgkmcnt(0)
	v_mfma_f32_16x16x32_bf16 v[116:119], v[200:203], v[168:171], v[116:119]
	v_mfma_f32_16x16x32_bf16 v[112:115], v[208:211], v[168:171], v[112:115]
	v_mfma_f32_16x16x32_bf16 v[100:103], v[200:203], v[176:179], v[100:103]
	v_mfma_f32_16x16x32_bf16 v[96:99], v[208:211], v[176:179], v[96:99]
	v_mfma_f32_16x16x32_bf16 v[84:87], v[200:203], v[184:187], v[84:87]
	v_mfma_f32_16x16x32_bf16 v[80:83], v[208:211], v[184:187], v[80:83]
	v_mfma_f32_16x16x32_bf16 v[68:71], v[200:203], v[192:195], v[68:71]
	v_mfma_f32_16x16x32_bf16 v[64:67], v[208:211], v[192:195], v[64:67]
	v_mfma_f32_16x16x32_bf16 v[116:119], v[204:207], v[172:175], v[116:119]
	v_mfma_f32_16x16x32_bf16 v[112:115], v[212:215], v[172:175], v[112:115]
	v_mfma_f32_16x16x32_bf16 v[100:103], v[204:207], v[180:183], v[100:103]
	v_mfma_f32_16x16x32_bf16 v[96:99], v[212:215], v[180:183], v[96:99]
	v_mfma_f32_16x16x32_bf16 v[84:87], v[204:207], v[188:191], v[84:87]
	v_mfma_f32_16x16x32_bf16 v[80:83], v[212:215], v[188:191], v[80:83]
	v_mfma_f32_16x16x32_bf16 v[68:71], v[204:207], v[196:199], v[68:71]
	v_mfma_f32_16x16x32_bf16 v[64:67], v[212:215], v[196:199], v[64:67]
	s_mov_b32 m0, s66
	s_barrier
	ds_read_b128 v[168:171], v153 offset:49152
	ds_read_b128 v[172:175], v153 offset:50176
	ds_read_b128 v[176:179], v153 offset:51200
	ds_read_b128 v[180:183], v153 offset:52224
	ds_read_b128 v[184:187], v153 offset:53248
	ds_read_b128 v[188:191], v153 offset:54272
	ds_read_b128 v[192:195], v153 offset:55296
	ds_read_b128 v[196:199], v153 offset:56320
	global_load_lds_dwordx4 v128, s[100:101]
	s_mov_b32 m0, s67
	s_nop 0
	global_load_lds_dwordx4 v132, s[100:101]
	s_barrier
	s_waitcnt lgkmcnt(0)
	v_mfma_f32_16x16x32_bf16 v[60:63], v[146:149], v[168:171], v[60:63]
	v_mfma_f32_16x16x32_bf16 v[56:59], v[160:163], v[168:171], v[56:59]
	v_mfma_f32_16x16x32_bf16 v[44:47], v[146:149], v[176:179], v[44:47]
	v_mfma_f32_16x16x32_bf16 v[40:43], v[160:163], v[176:179], v[40:43]
	v_mfma_f32_16x16x32_bf16 v[28:31], v[146:149], v[184:187], v[28:31]
	v_mfma_f32_16x16x32_bf16 v[24:27], v[160:163], v[184:187], v[24:27]
	v_mfma_f32_16x16x32_bf16 v[12:15], v[146:149], v[192:195], v[12:15]
	v_mfma_f32_16x16x32_bf16 v[8:11], v[160:163], v[192:195], v[8:11]
	v_mfma_f32_16x16x32_bf16 v[60:63], v[156:159], v[172:175], v[60:63]
	v_mfma_f32_16x16x32_bf16 v[56:59], v[164:167], v[172:175], v[56:59]
	v_mfma_f32_16x16x32_bf16 v[44:47], v[156:159], v[180:183], v[44:47]
	v_mfma_f32_16x16x32_bf16 v[40:43], v[164:167], v[180:183], v[40:43]
	v_mfma_f32_16x16x32_bf16 v[28:31], v[156:159], v[188:191], v[28:31]
	v_mfma_f32_16x16x32_bf16 v[24:27], v[164:167], v[188:191], v[24:27]
	v_mfma_f32_16x16x32_bf16 v[12:15], v[156:159], v[196:199], v[12:15]
	v_mfma_f32_16x16x32_bf16 v[8:11], v[164:167], v[196:199], v[8:11]
	s_barrier
	s_add_u32 s54, s54, 0x80080
	s_addc_u32 s55, s55, 0
	s_add_i32 s56, s56, s60
	s_mov_b32 m0, s56
	s_nop 0
	global_load_lds_dwordx4 v130, s[54:55]
	s_add_i32 m0, s56, 0x2000
	s_nop 0
	global_load_lds_dwordx4 v134, s[54:55]
	s_waitcnt vmcnt(6)
	s_barrier
	v_mfma_f32_16x16x32_bf16 v[52:55], v[200:203], v[168:171], v[52:55]
	v_mfma_f32_16x16x32_bf16 v[48:51], v[208:211], v[168:171], v[48:51]
	v_mfma_f32_16x16x32_bf16 v[36:39], v[200:203], v[176:179], v[36:39]
	v_mfma_f32_16x16x32_bf16 v[32:35], v[208:211], v[176:179], v[32:35]
	v_mfma_f32_16x16x32_bf16 v[20:23], v[200:203], v[184:187], v[20:23]
	v_mfma_f32_16x16x32_bf16 v[16:19], v[208:211], v[184:187], v[16:19]
	v_mfma_f32_16x16x32_bf16 v[4:7], v[200:203], v[192:195], v[4:7]
	v_mfma_f32_16x16x32_bf16 v[0:3], v[208:211], v[192:195], v[0:3]
	v_mfma_f32_16x16x32_bf16 v[52:55], v[204:207], v[172:175], v[52:55]
	v_mfma_f32_16x16x32_bf16 v[48:51], v[212:215], v[172:175], v[48:51]
	v_mfma_f32_16x16x32_bf16 v[36:39], v[204:207], v[180:183], v[36:39]
	v_mfma_f32_16x16x32_bf16 v[32:35], v[212:215], v[180:183], v[32:35]
	v_mfma_f32_16x16x32_bf16 v[20:23], v[204:207], v[188:191], v[20:23]
	v_mfma_f32_16x16x32_bf16 v[16:19], v[212:215], v[188:191], v[16:19]
	v_mfma_f32_16x16x32_bf16 v[4:7], v[204:207], v[196:199], v[4:7]
	v_mfma_f32_16x16x32_bf16 v[0:3], v[212:215], v[196:199], v[0:3]
	s_add_i32 s78, s78, 2
	s_add_u32 s36, s36, 0x100
	s_addc_u32 s37, s37, 0
	s_add_u32 s29, s29, 0x100
	s_addc_u32 s35, s35, 0
	s_cmp_gt_u32 s78, 29
	s_barrier
	s_cbranch_scc0 .LBB0_330
.LBB0_330:
	ds_read_b128 v[146:149], v152
	ds_read_b128 v[156:159], v152 offset:1024
	ds_read_b128 v[160:163], v152 offset:2048
	ds_read_b128 v[164:167], v152 offset:3072
	s_add_u32 s54, s36, 0xfff80080
	s_addc_u32 s55, s37, -1
	s_cmp_eq_u32 s78, 28
	s_cselect_b32 s57, s1, s55
	s_cselect_b32 s56, s15, s54
	s_cselect_b32 s55, s13, s35
	s_cselect_b32 s54, s28, s29
	s_add_i32 m0, s61, 0xc000
	ds_read_b128 v[168:171], v153
	ds_read_b128 v[172:175], v153 offset:1024
	ds_read_b128 v[176:179], v153 offset:2048
	ds_read_b128 v[180:183], v153 offset:3072
	ds_read_b128 v[184:187], v153 offset:4096
	ds_read_b128 v[188:191], v153 offset:5120
	ds_read_b128 v[192:195], v153 offset:6144
	ds_read_b128 v[196:199], v153 offset:7168
	global_load_lds_dwordx4 v138, s[36:37]
	s_add_i32 m0, s61, 0xe000
	s_nop 0
	global_load_lds_dwordx4 v140, s[36:37]
	s_waitcnt lgkmcnt(8)
	s_barrier
	s_waitcnt lgkmcnt(0)
	v_mfma_f32_16x16x32_bf16 v[124:127], v[146:149], v[168:171], v[124:127]
	v_mfma_f32_16x16x32_bf16 v[120:123], v[160:163], v[168:171], v[120:123]
	v_mfma_f32_16x16x32_bf16 v[108:111], v[146:149], v[176:179], v[108:111]
	v_mfma_f32_16x16x32_bf16 v[104:107], v[160:163], v[176:179], v[104:107]
	v_mfma_f32_16x16x32_bf16 v[92:95], v[146:149], v[184:187], v[92:95]
	v_mfma_f32_16x16x32_bf16 v[88:91], v[160:163], v[184:187], v[88:91]
	v_mfma_f32_16x16x32_bf16 v[76:79], v[146:149], v[192:195], v[76:79]
	v_mfma_f32_16x16x32_bf16 v[72:75], v[160:163], v[192:195], v[72:75]
	v_mfma_f32_16x16x32_bf16 v[124:127], v[156:159], v[172:175], v[124:127]
	v_mfma_f32_16x16x32_bf16 v[120:123], v[164:167], v[172:175], v[120:123]
	v_mfma_f32_16x16x32_bf16 v[108:111], v[156:159], v[180:183], v[108:111]
	v_mfma_f32_16x16x32_bf16 v[104:107], v[164:167], v[180:183], v[104:107]
	v_mfma_f32_16x16x32_bf16 v[92:95], v[156:159], v[188:191], v[92:95]
	v_mfma_f32_16x16x32_bf16 v[88:91], v[164:167], v[188:191], v[88:91]
	v_mfma_f32_16x16x32_bf16 v[76:79], v[156:159], v[196:199], v[76:79]
	v_mfma_f32_16x16x32_bf16 v[72:75], v[164:167], v[196:199], v[72:75]
	s_barrier
	s_add_i32 s79, s75, s60
	s_add_u32 s98, s54, s10
	s_addc_u32 s99, s55, s11
	s_mov_b32 m0, s79
	ds_read_b128 v[200:203], v154
	ds_read_b128 v[204:207], v154 offset:1024
	ds_read_b128 v[208:211], v154 offset:2048
	ds_read_b128 v[212:215], v154 offset:3072
	global_load_lds_dwordx4 v130, s[54:55]
	s_add_i32 m0, s79, 0x2000
	s_nop 0
	global_load_lds_dwordx4 v134, s[54:55]
	s_barrier
	s_waitcnt lgkmcnt(0)
	v_mfma_f32_16x16x32_bf16 v[116:119], v[200:203], v[168:171], v[116:119]
	v_mfma_f32_16x16x32_bf16 v[112:115], v[208:211], v[168:171], v[112:115]
	v_mfma_f32_16x16x32_bf16 v[100:103], v[200:203], v[176:179], v[100:103]
	v_mfma_f32_16x16x32_bf16 v[96:99], v[208:211], v[176:179], v[96:99]
	v_mfma_f32_16x16x32_bf16 v[84:87], v[200:203], v[184:187], v[84:87]
	v_mfma_f32_16x16x32_bf16 v[80:83], v[208:211], v[184:187], v[80:83]
	v_mfma_f32_16x16x32_bf16 v[68:71], v[200:203], v[192:195], v[68:71]
	v_mfma_f32_16x16x32_bf16 v[64:67], v[208:211], v[192:195], v[64:67]
	v_mfma_f32_16x16x32_bf16 v[116:119], v[204:207], v[172:175], v[116:119]
	v_mfma_f32_16x16x32_bf16 v[112:115], v[212:215], v[172:175], v[112:115]
	v_mfma_f32_16x16x32_bf16 v[100:103], v[204:207], v[180:183], v[100:103]
	v_mfma_f32_16x16x32_bf16 v[96:99], v[212:215], v[180:183], v[96:99]
	v_mfma_f32_16x16x32_bf16 v[84:87], v[204:207], v[188:191], v[84:87]
	v_mfma_f32_16x16x32_bf16 v[80:83], v[212:215], v[188:191], v[80:83]
	v_mfma_f32_16x16x32_bf16 v[68:71], v[204:207], v[196:199], v[68:71]
	v_mfma_f32_16x16x32_bf16 v[64:67], v[212:215], v[196:199], v[64:67]
	s_mov_b32 m0, s61
	s_add_u32 s100, s56, s10
	s_addc_u32 s101, s57, s11
	s_barrier
	ds_read_b128 v[168:171], v153 offset:16384
	ds_read_b128 v[172:175], v153 offset:17408
	ds_read_b128 v[176:179], v153 offset:18432
	ds_read_b128 v[180:183], v153 offset:19456
	ds_read_b128 v[184:187], v153 offset:20480
	ds_read_b128 v[188:191], v153 offset:21504
	ds_read_b128 v[192:195], v153 offset:22528
	ds_read_b128 v[196:199], v153 offset:23552
	global_load_lds_dwordx4 v128, s[56:57]
	s_mov_b32 m0, s62
	s_nop 0
	global_load_lds_dwordx4 v132, s[56:57]
	s_barrier
	s_waitcnt lgkmcnt(0)
	v_mfma_f32_16x16x32_bf16 v[60:63], v[146:149], v[168:171], v[60:63]
	v_mfma_f32_16x16x32_bf16 v[56:59], v[160:163], v[168:171], v[56:59]
	v_mfma_f32_16x16x32_bf16 v[44:47], v[146:149], v[176:179], v[44:47]
	v_mfma_f32_16x16x32_bf16 v[40:43], v[160:163], v[176:179], v[40:43]
	v_mfma_f32_16x16x32_bf16 v[28:31], v[146:149], v[184:187], v[28:31]
	v_mfma_f32_16x16x32_bf16 v[24:27], v[160:163], v[184:187], v[24:27]
	v_mfma_f32_16x16x32_bf16 v[12:15], v[146:149], v[192:195], v[12:15]
	v_mfma_f32_16x16x32_bf16 v[8:11], v[160:163], v[192:195], v[8:11]
	v_mfma_f32_16x16x32_bf16 v[60:63], v[156:159], v[172:175], v[60:63]
	v_mfma_f32_16x16x32_bf16 v[56:59], v[164:167], v[172:175], v[56:59]
	v_mfma_f32_16x16x32_bf16 v[44:47], v[156:159], v[180:183], v[44:47]
	v_mfma_f32_16x16x32_bf16 v[40:43], v[164:167], v[180:183], v[40:43]
	v_mfma_f32_16x16x32_bf16 v[28:31], v[156:159], v[188:191], v[28:31]
	v_mfma_f32_16x16x32_bf16 v[24:27], v[164:167], v[188:191], v[24:27]
	v_mfma_f32_16x16x32_bf16 v[12:15], v[156:159], v[196:199], v[12:15]
	v_mfma_f32_16x16x32_bf16 v[8:11], v[164:167], v[196:199], v[8:11]
	s_barrier
	s_add_u32 s80, s54, 0x80000
	s_addc_u32 s81, s55, 0
	s_add_i32 s79, s76, s60
	s_mov_b32 m0, s79
	s_nop 0
	global_load_lds_dwordx4 v130, s[80:81]
	s_add_i32 m0, s79, 0x2000
	s_nop 0
	global_load_lds_dwordx4 v134, s[80:81]
	s_waitcnt vmcnt(6)
	s_barrier
	v_mfma_f32_16x16x32_bf16 v[52:55], v[200:203], v[168:171], v[52:55]
	v_mfma_f32_16x16x32_bf16 v[48:51], v[208:211], v[168:171], v[48:51]
	v_mfma_f32_16x16x32_bf16 v[36:39], v[200:203], v[176:179], v[36:39]
	v_mfma_f32_16x16x32_bf16 v[32:35], v[208:211], v[176:179], v[32:35]
	v_mfma_f32_16x16x32_bf16 v[20:23], v[200:203], v[184:187], v[20:23]
	v_mfma_f32_16x16x32_bf16 v[16:19], v[208:211], v[184:187], v[16:19]
	v_mfma_f32_16x16x32_bf16 v[4:7], v[200:203], v[192:195], v[4:7]
	v_mfma_f32_16x16x32_bf16 v[0:3], v[208:211], v[192:195], v[0:3]
	v_mfma_f32_16x16x32_bf16 v[52:55], v[204:207], v[172:175], v[52:55]
	v_mfma_f32_16x16x32_bf16 v[48:51], v[212:215], v[172:175], v[48:51]
	v_mfma_f32_16x16x32_bf16 v[36:39], v[204:207], v[180:183], v[36:39]
	v_mfma_f32_16x16x32_bf16 v[32:35], v[212:215], v[180:183], v[32:35]
	v_mfma_f32_16x16x32_bf16 v[20:23], v[204:207], v[188:191], v[20:23]
	v_mfma_f32_16x16x32_bf16 v[16:19], v[212:215], v[188:191], v[16:19]
	v_mfma_f32_16x16x32_bf16 v[4:7], v[204:207], v[196:199], v[4:7]
	v_mfma_f32_16x16x32_bf16 v[0:3], v[212:215], v[196:199], v[0:3]
	s_add_i32 s79, 0, 0x18000
	s_barrier
	ds_read_b128 v[146:149], v244
	ds_read_b128 v[156:159], v244 offset:1024
	ds_read_b128 v[160:163], v244 offset:2048
	ds_read_b128 v[164:167], v244 offset:3072
	s_add_u32 s56, s56, 0x80000
	s_addc_u32 s57, s57, 0
	s_mov_b32 m0, s63
	ds_read_b128 v[168:171], v153 offset:32768
	ds_read_b128 v[172:175], v153 offset:33792
	ds_read_b128 v[176:179], v153 offset:34816
	ds_read_b128 v[180:183], v153 offset:35840
	ds_read_b128 v[184:187], v153 offset:36864
	ds_read_b128 v[188:191], v153 offset:37888
	ds_read_b128 v[192:195], v153 offset:38912
	ds_read_b128 v[196:199], v153 offset:39936
	global_load_lds_dwordx4 v128, s[56:57]
	s_mov_b32 m0, s64
	s_nop 0
	global_load_lds_dwordx4 v132, s[56:57]
	s_waitcnt lgkmcnt(8)
	s_barrier
	s_waitcnt lgkmcnt(0)
	v_mfma_f32_16x16x32_bf16 v[124:127], v[146:149], v[168:171], v[124:127]
	v_mfma_f32_16x16x32_bf16 v[120:123], v[160:163], v[168:171], v[120:123]
	v_mfma_f32_16x16x32_bf16 v[108:111], v[146:149], v[176:179], v[108:111]
	v_mfma_f32_16x16x32_bf16 v[104:107], v[160:163], v[176:179], v[104:107]
	v_mfma_f32_16x16x32_bf16 v[92:95], v[146:149], v[184:187], v[92:95]
	v_mfma_f32_16x16x32_bf16 v[88:91], v[160:163], v[184:187], v[88:91]
	v_mfma_f32_16x16x32_bf16 v[76:79], v[146:149], v[192:195], v[76:79]
	v_mfma_f32_16x16x32_bf16 v[72:75], v[160:163], v[192:195], v[72:75]
	v_mfma_f32_16x16x32_bf16 v[124:127], v[156:159], v[172:175], v[124:127]
	v_mfma_f32_16x16x32_bf16 v[120:123], v[164:167], v[172:175], v[120:123]
	v_mfma_f32_16x16x32_bf16 v[108:111], v[156:159], v[180:183], v[108:111]
	v_mfma_f32_16x16x32_bf16 v[104:107], v[164:167], v[180:183], v[104:107]
	v_mfma_f32_16x16x32_bf16 v[92:95], v[156:159], v[188:191], v[92:95]
	v_mfma_f32_16x16x32_bf16 v[88:91], v[164:167], v[188:191], v[88:91]
	v_mfma_f32_16x16x32_bf16 v[76:79], v[156:159], v[196:199], v[76:79]
	v_mfma_f32_16x16x32_bf16 v[72:75], v[164:167], v[196:199], v[72:75]
	s_barrier
	s_add_i32 s56, 0, 0x1c000
	s_add_i32 s57, s79, s60
	s_mov_b32 m0, s57
	ds_read_b128 v[200:203], v245
	ds_read_b128 v[204:207], v245 offset:1024
	ds_read_b128 v[208:211], v245 offset:2048
	ds_read_b128 v[212:215], v245 offset:3072
	global_load_lds_dwordx4 v130, s[98:99]
	s_add_i32 m0, s57, 0x2000
	s_nop 0
	global_load_lds_dwordx4 v134, s[98:99]
	s_barrier
	s_waitcnt lgkmcnt(0)
	v_mfma_f32_16x16x32_bf16 v[116:119], v[200:203], v[168:171], v[116:119]
	v_mfma_f32_16x16x32_bf16 v[112:115], v[208:211], v[168:171], v[112:115]
	v_mfma_f32_16x16x32_bf16 v[100:103], v[200:203], v[176:179], v[100:103]
	v_mfma_f32_16x16x32_bf16 v[96:99], v[208:211], v[176:179], v[96:99]
	v_mfma_f32_16x16x32_bf16 v[84:87], v[200:203], v[184:187], v[84:87]
	v_mfma_f32_16x16x32_bf16 v[80:83], v[208:211], v[184:187], v[80:83]
	v_mfma_f32_16x16x32_bf16 v[68:71], v[200:203], v[192:195], v[68:71]
	v_mfma_f32_16x16x32_bf16 v[64:67], v[208:211], v[192:195], v[64:67]
	v_mfma_f32_16x16x32_bf16 v[116:119], v[204:207], v[172:175], v[116:119]
	v_mfma_f32_16x16x32_bf16 v[112:115], v[212:215], v[172:175], v[112:115]
	v_mfma_f32_16x16x32_bf16 v[100:103], v[204:207], v[180:183], v[100:103]
	v_mfma_f32_16x16x32_bf16 v[96:99], v[212:215], v[180:183], v[96:99]
	v_mfma_f32_16x16x32_bf16 v[84:87], v[204:207], v[188:191], v[84:87]
	v_mfma_f32_16x16x32_bf16 v[80:83], v[212:215], v[188:191], v[80:83]
	v_mfma_f32_16x16x32_bf16 v[68:71], v[204:207], v[196:199], v[68:71]
	v_mfma_f32_16x16x32_bf16 v[64:67], v[212:215], v[196:199], v[64:67]
	s_mov_b32 m0, s66
	s_barrier
	ds_read_b128 v[168:171], v153 offset:49152
	ds_read_b128 v[172:175], v153 offset:50176
	ds_read_b128 v[176:179], v153 offset:51200
	ds_read_b128 v[180:183], v153 offset:52224
	ds_read_b128 v[184:187], v153 offset:53248
	ds_read_b128 v[188:191], v153 offset:54272
	ds_read_b128 v[192:195], v153 offset:55296
	ds_read_b128 v[196:199], v153 offset:56320
	global_load_lds_dwordx4 v128, s[100:101]
	s_mov_b32 m0, s67
	s_nop 0
	global_load_lds_dwordx4 v132, s[100:101]
	s_barrier
	s_waitcnt lgkmcnt(0)
	v_mfma_f32_16x16x32_bf16 v[60:63], v[146:149], v[168:171], v[60:63]
	v_mfma_f32_16x16x32_bf16 v[56:59], v[160:163], v[168:171], v[56:59]
	v_mfma_f32_16x16x32_bf16 v[44:47], v[146:149], v[176:179], v[44:47]
	v_mfma_f32_16x16x32_bf16 v[40:43], v[160:163], v[176:179], v[40:43]
	v_mfma_f32_16x16x32_bf16 v[28:31], v[146:149], v[184:187], v[28:31]
	v_mfma_f32_16x16x32_bf16 v[24:27], v[160:163], v[184:187], v[24:27]
	v_mfma_f32_16x16x32_bf16 v[12:15], v[146:149], v[192:195], v[12:15]
	v_mfma_f32_16x16x32_bf16 v[8:11], v[160:163], v[192:195], v[8:11]
	v_mfma_f32_16x16x32_bf16 v[60:63], v[156:159], v[172:175], v[60:63]
	v_mfma_f32_16x16x32_bf16 v[56:59], v[164:167], v[172:175], v[56:59]
	v_mfma_f32_16x16x32_bf16 v[44:47], v[156:159], v[180:183], v[44:47]
	v_mfma_f32_16x16x32_bf16 v[40:43], v[164:167], v[180:183], v[40:43]
	v_mfma_f32_16x16x32_bf16 v[28:31], v[156:159], v[188:191], v[28:31]
	v_mfma_f32_16x16x32_bf16 v[24:27], v[164:167], v[188:191], v[24:27]
	v_mfma_f32_16x16x32_bf16 v[12:15], v[156:159], v[196:199], v[12:15]
	v_mfma_f32_16x16x32_bf16 v[8:11], v[164:167], v[196:199], v[8:11]
	s_barrier
	s_add_u32 s54, s54, 0x80080
	s_addc_u32 s55, s55, 0
	s_add_i32 s56, s56, s60
	s_mov_b32 m0, s56
	s_nop 0
	global_load_lds_dwordx4 v130, s[54:55]
	s_add_i32 m0, s56, 0x2000
	s_nop 0
	global_load_lds_dwordx4 v134, s[54:55]
	s_waitcnt vmcnt(6)
	s_barrier
	v_mfma_f32_16x16x32_bf16 v[52:55], v[200:203], v[168:171], v[52:55]
	v_mfma_f32_16x16x32_bf16 v[48:51], v[208:211], v[168:171], v[48:51]
	v_mfma_f32_16x16x32_bf16 v[36:39], v[200:203], v[176:179], v[36:39]
	v_mfma_f32_16x16x32_bf16 v[32:35], v[208:211], v[176:179], v[32:35]
	v_mfma_f32_16x16x32_bf16 v[20:23], v[200:203], v[184:187], v[20:23]
	v_mfma_f32_16x16x32_bf16 v[16:19], v[208:211], v[184:187], v[16:19]
	v_mfma_f32_16x16x32_bf16 v[4:7], v[200:203], v[192:195], v[4:7]
	v_mfma_f32_16x16x32_bf16 v[0:3], v[208:211], v[192:195], v[0:3]
	v_mfma_f32_16x16x32_bf16 v[52:55], v[204:207], v[172:175], v[52:55]
	v_mfma_f32_16x16x32_bf16 v[48:51], v[212:215], v[172:175], v[48:51]
	v_mfma_f32_16x16x32_bf16 v[36:39], v[204:207], v[180:183], v[36:39]
	v_mfma_f32_16x16x32_bf16 v[32:35], v[212:215], v[180:183], v[32:35]
	v_mfma_f32_16x16x32_bf16 v[20:23], v[204:207], v[188:191], v[20:23]
	v_mfma_f32_16x16x32_bf16 v[16:19], v[212:215], v[188:191], v[16:19]
	v_mfma_f32_16x16x32_bf16 v[4:7], v[204:207], v[196:199], v[4:7]
	v_mfma_f32_16x16x32_bf16 v[0:3], v[212:215], v[196:199], v[0:3]
	s_add_i32 s78, s78, 2
	s_add_u32 s36, s36, 0x100
	s_addc_u32 s37, s37, 0
	s_add_u32 s29, s29, 0x100
	s_addc_u32 s35, s35, 0
	s_cmp_gt_u32 s78, 29
	s_barrier
	s_cbranch_scc0 .LBB0_330
	s_cmp_gt_i32 s34, 3
	v_lshl_add_u32 v146, s0, 8, v145
	v_lshl_or_b32 v148, s34, 8, v151
	s_cselect_b64 s[34:35], -1, 0
	v_ashrrev_i32_e32 v147, 31, v146
	s_mov_b64 s[0:1], -1
	s_and_b64 vcc, exec, s[34:35]
	v_ashrrev_i32_e32 v149, 31, v148
	s_cbranch_vccz .LBB0_333
	v_and_b32_e32 v160, 63, v144
	v_lshrrev_b32_e32 v161, 6, v144
	v_lshlrev_b32_e32 v162, 10, v161
	v_add_u32_e32 v162, 0x20000, v162
	v_lshrrev_b32_e32 v163, 4, v160
	v_and_b32_e32 v164, 15, v160
	v_lshlrev_b32_e32 v165, 8, v163
	v_lshl_add_u32 v165, v164, 1, v165
	v_add_u32_e32 v165, v162, v165
	v_lshl_add_u32 v166, v160, 4, v162
	v_sub_u32_e32 v167, v148, v151
	v_and_b32_e32 v168, 0x60, v151
	v_add_u32_e32 v167, v167, v168
	v_lshl_add_u32 v167, v163, 3, v167
	v_bfe_u32 v168, v160, 2, 2
	v_add_u32_e32 v167, v167, v168
	v_sub_u32_e32 v168, v146, v145
	v_and_b32_e32 v169, 0x40, v145
	v_add_u32_e32 v168, v168, v169
	v_and_b32_e32 v169, 3, v160
	v_lshl_add_u32 v168, v169, 3, v168
	v_mov_b32_e32 v170, v167
	v_mov_b32_e32 v171, 0
	v_lshlrev_b64 v[170:171], 15, v[170:171]
	v_lshl_add_u64 v[170:171], s[8:9], 0, v[170:171]
	v_lshlrev_b32_e32 v172, 1, v168
	v_mov_b32_e32 v173, 0
	v_lshl_add_u64 v[170:171], v[170:171], 0, v[172:173]
	s_mov_b32 s28, 0xfe000000
	s_mov_b32 s29, -1
	v_lshl_add_u64 v[170:171], v[170:171], 0, s[28:29]
	s_mov_b32 s29, 0
	v_cvt_pk_bf16_f32 v190, v124, v125
	v_cvt_pk_bf16_f32 v191, v126, v127
	v_lshrrev_b32_e32 v192, 16, v190
	v_lshrrev_b32_e32 v193, 16, v191
	ds_write_b16 v165, v190 offset:0
	ds_write_b16 v165, v192 offset:64
	ds_write_b16 v165, v191 offset:128
	ds_write_b16 v165, v193 offset:192
	v_cvt_pk_bf16_f32 v198, v108, v109
	v_cvt_pk_bf16_f32 v199, v110, v111
	v_lshrrev_b32_e32 v200, 16, v198
	v_lshrrev_b32_e32 v201, 16, v199
	ds_write_b16 v165, v198 offset:32
	ds_write_b16 v165, v200 offset:96
	ds_write_b16 v165, v199 offset:160
	ds_write_b16 v165, v201 offset:224
	ds_read_b128 v[180:183], v166
	s_waitcnt lgkmcnt(0)
	global_store_dwordx4 v[170:171], v[180:183], off
	v_cvt_pk_bf16_f32 v194, v92, v93
	v_cvt_pk_bf16_f32 v195, v94, v95
	v_lshrrev_b32_e32 v196, 16, v194
	v_lshrrev_b32_e32 v197, 16, v195
	ds_write_b16 v165, v194 offset:0
	ds_write_b16 v165, v196 offset:64
	ds_write_b16 v165, v195 offset:128
	ds_write_b16 v165, v197 offset:192
	v_cvt_pk_bf16_f32 v202, v76, v77
	v_cvt_pk_bf16_f32 v203, v78, v79
	v_lshrrev_b32_e32 v204, 16, v202
	v_lshrrev_b32_e32 v205, 16, v203
	ds_write_b16 v165, v202 offset:32
	ds_write_b16 v165, v204 offset:96
	ds_write_b16 v165, v203 offset:160
	ds_write_b16 v165, v205 offset:224
	ds_read_b128 v[184:187], v166
	s_waitcnt lgkmcnt(0)
	global_store_dwordx4 v[170:171], v[184:187], off offset:64
	v_cvt_pk_bf16_f32 v190, v60, v61
	v_cvt_pk_bf16_f32 v191, v62, v63
	v_lshrrev_b32_e32 v192, 16, v190
	v_lshrrev_b32_e32 v193, 16, v191
	ds_write_b16 v165, v190 offset:0
	ds_write_b16 v165, v192 offset:64
	ds_write_b16 v165, v191 offset:128
	ds_write_b16 v165, v193 offset:192
	v_cvt_pk_bf16_f32 v198, v44, v45
	v_cvt_pk_bf16_f32 v199, v46, v47
	v_lshrrev_b32_e32 v200, 16, v198
	v_lshrrev_b32_e32 v201, 16, v199
	ds_write_b16 v165, v198 offset:32
	ds_write_b16 v165, v200 offset:96
	ds_write_b16 v165, v199 offset:160
	ds_write_b16 v165, v201 offset:224
	ds_read_b128 v[180:183], v166
	s_waitcnt lgkmcnt(0)
	global_store_dwordx4 v[170:171], v[180:183], off offset:256
	v_cvt_pk_bf16_f32 v194, v28, v29
	v_cvt_pk_bf16_f32 v195, v30, v31
	v_lshrrev_b32_e32 v196, 16, v194
	v_lshrrev_b32_e32 v197, 16, v195
	ds_write_b16 v165, v194 offset:0
	ds_write_b16 v165, v196 offset:64
	ds_write_b16 v165, v195 offset:128
	ds_write_b16 v165, v197 offset:192
	v_cvt_pk_bf16_f32 v202, v12, v13
	v_cvt_pk_bf16_f32 v203, v14, v15
	v_lshrrev_b32_e32 v204, 16, v202
	v_lshrrev_b32_e32 v205, 16, v203
	ds_write_b16 v165, v202 offset:32
	ds_write_b16 v165, v204 offset:96
	ds_write_b16 v165, v203 offset:160
	ds_write_b16 v165, v205 offset:224
	ds_read_b128 v[184:187], v166
	s_waitcnt lgkmcnt(0)
	global_store_dwordx4 v[170:171], v[184:187], off offset:320
	s_mov_b32 s28, 0x20000
	v_lshl_add_u64 v[174:175], v[170:171], 0, s[28:29]
	v_cvt_pk_bf16_f32 v190, v120, v121
	v_cvt_pk_bf16_f32 v191, v122, v123
	v_lshrrev_b32_e32 v192, 16, v190
	v_lshrrev_b32_e32 v193, 16, v191
	ds_write_b16 v165, v190 offset:0
	ds_write_b16 v165, v192 offset:64
	ds_write_b16 v165, v191 offset:128
	ds_write_b16 v165, v193 offset:192
	v_cvt_pk_bf16_f32 v198, v104, v105
	v_cvt_pk_bf16_f32 v199, v106, v107
	v_lshrrev_b32_e32 v200, 16, v198
	v_lshrrev_b32_e32 v201, 16, v199
	ds_write_b16 v165, v198 offset:32
	ds_write_b16 v165, v200 offset:96
	ds_write_b16 v165, v199 offset:160
	ds_write_b16 v165, v201 offset:224
	ds_read_b128 v[180:183], v166
	s_waitcnt lgkmcnt(0)
	global_store_dwordx4 v[174:175], v[180:183], off
	v_cvt_pk_bf16_f32 v194, v88, v89
	v_cvt_pk_bf16_f32 v195, v90, v91
	v_lshrrev_b32_e32 v196, 16, v194
	v_lshrrev_b32_e32 v197, 16, v195
	ds_write_b16 v165, v194 offset:0
	ds_write_b16 v165, v196 offset:64
	ds_write_b16 v165, v195 offset:128
	ds_write_b16 v165, v197 offset:192
	v_cvt_pk_bf16_f32 v202, v72, v73
	v_cvt_pk_bf16_f32 v203, v74, v75
	v_lshrrev_b32_e32 v204, 16, v202
	v_lshrrev_b32_e32 v205, 16, v203
	ds_write_b16 v165, v202 offset:32
	ds_write_b16 v165, v204 offset:96
	ds_write_b16 v165, v203 offset:160
	ds_write_b16 v165, v205 offset:224
	ds_read_b128 v[184:187], v166
	s_waitcnt lgkmcnt(0)
	global_store_dwordx4 v[174:175], v[184:187], off offset:64
	v_cvt_pk_bf16_f32 v190, v56, v57
	v_cvt_pk_bf16_f32 v191, v58, v59
	v_lshrrev_b32_e32 v192, 16, v190
	v_lshrrev_b32_e32 v193, 16, v191
	ds_write_b16 v165, v190 offset:0
	ds_write_b16 v165, v192 offset:64
	ds_write_b16 v165, v191 offset:128
	ds_write_b16 v165, v193 offset:192
	v_cvt_pk_bf16_f32 v198, v40, v41
	v_cvt_pk_bf16_f32 v199, v42, v43
	v_lshrrev_b32_e32 v200, 16, v198
	v_lshrrev_b32_e32 v201, 16, v199
	ds_write_b16 v165, v198 offset:32
	ds_write_b16 v165, v200 offset:96
	ds_write_b16 v165, v199 offset:160
	ds_write_b16 v165, v201 offset:224
	ds_read_b128 v[180:183], v166
	s_waitcnt lgkmcnt(0)
	global_store_dwordx4 v[174:175], v[180:183], off offset:256
	v_cvt_pk_bf16_f32 v194, v24, v25
	v_cvt_pk_bf16_f32 v195, v26, v27
	v_lshrrev_b32_e32 v196, 16, v194
	v_lshrrev_b32_e32 v197, 16, v195
	ds_write_b16 v165, v194 offset:0
	ds_write_b16 v165, v196 offset:64
	ds_write_b16 v165, v195 offset:128
	ds_write_b16 v165, v197 offset:192
	v_cvt_pk_bf16_f32 v202, v8, v9
	v_cvt_pk_bf16_f32 v203, v10, v11
	v_lshrrev_b32_e32 v204, 16, v202
	v_lshrrev_b32_e32 v205, 16, v203
	ds_write_b16 v165, v202 offset:32
	ds_write_b16 v165, v204 offset:96
	ds_write_b16 v165, v203 offset:160
	ds_write_b16 v165, v205 offset:224
	ds_read_b128 v[184:187], v166
	s_waitcnt lgkmcnt(0)
	global_store_dwordx4 v[174:175], v[184:187], off offset:320
	s_mov_b32 s28, 0x400000
	v_lshl_add_u64 v[174:175], v[170:171], 0, s[28:29]
	v_cvt_pk_bf16_f32 v190, v116, v117
	v_cvt_pk_bf16_f32 v191, v118, v119
	v_lshrrev_b32_e32 v192, 16, v190
	v_lshrrev_b32_e32 v193, 16, v191
	ds_write_b16 v165, v190 offset:0
	ds_write_b16 v165, v192 offset:64
	ds_write_b16 v165, v191 offset:128
	ds_write_b16 v165, v193 offset:192
	v_cvt_pk_bf16_f32 v198, v100, v101
	v_cvt_pk_bf16_f32 v199, v102, v103
	v_lshrrev_b32_e32 v200, 16, v198
	v_lshrrev_b32_e32 v201, 16, v199
	ds_write_b16 v165, v198 offset:32
	ds_write_b16 v165, v200 offset:96
	ds_write_b16 v165, v199 offset:160
	ds_write_b16 v165, v201 offset:224
	ds_read_b128 v[180:183], v166
	s_waitcnt lgkmcnt(0)
	global_store_dwordx4 v[174:175], v[180:183], off
	v_cvt_pk_bf16_f32 v194, v84, v85
	v_cvt_pk_bf16_f32 v195, v86, v87
	v_lshrrev_b32_e32 v196, 16, v194
	v_lshrrev_b32_e32 v197, 16, v195
	ds_write_b16 v165, v194 offset:0
	ds_write_b16 v165, v196 offset:64
	ds_write_b16 v165, v195 offset:128
	ds_write_b16 v165, v197 offset:192
	v_cvt_pk_bf16_f32 v202, v68, v69
	v_cvt_pk_bf16_f32 v203, v70, v71
	v_lshrrev_b32_e32 v204, 16, v202
	v_lshrrev_b32_e32 v205, 16, v203
	ds_write_b16 v165, v202 offset:32
	ds_write_b16 v165, v204 offset:96
	ds_write_b16 v165, v203 offset:160
	ds_write_b16 v165, v205 offset:224
	ds_read_b128 v[184:187], v166
	s_waitcnt lgkmcnt(0)
	global_store_dwordx4 v[174:175], v[184:187], off offset:64
	v_cvt_pk_bf16_f32 v190, v52, v53
	v_cvt_pk_bf16_f32 v191, v54, v55
	v_lshrrev_b32_e32 v192, 16, v190
	v_lshrrev_b32_e32 v193, 16, v191
	ds_write_b16 v165, v190 offset:0
	ds_write_b16 v165, v192 offset:64
	ds_write_b16 v165, v191 offset:128
	ds_write_b16 v165, v193 offset:192
	v_cvt_pk_bf16_f32 v198, v36, v37
	v_cvt_pk_bf16_f32 v199, v38, v39
	v_lshrrev_b32_e32 v200, 16, v198
	v_lshrrev_b32_e32 v201, 16, v199
	ds_write_b16 v165, v198 offset:32
	ds_write_b16 v165, v200 offset:96
	ds_write_b16 v165, v199 offset:160
	ds_write_b16 v165, v201 offset:224
	ds_read_b128 v[180:183], v166
	s_waitcnt lgkmcnt(0)
	global_store_dwordx4 v[174:175], v[180:183], off offset:256
	v_cvt_pk_bf16_f32 v194, v20, v21
	v_cvt_pk_bf16_f32 v195, v22, v23
	v_lshrrev_b32_e32 v196, 16, v194
	v_lshrrev_b32_e32 v197, 16, v195
	ds_write_b16 v165, v194 offset:0
	ds_write_b16 v165, v196 offset:64
	ds_write_b16 v165, v195 offset:128
	ds_write_b16 v165, v197 offset:192
	v_cvt_pk_bf16_f32 v202, v4, v5
	v_cvt_pk_bf16_f32 v203, v6, v7
	v_lshrrev_b32_e32 v204, 16, v202
	v_lshrrev_b32_e32 v205, 16, v203
	ds_write_b16 v165, v202 offset:32
	ds_write_b16 v165, v204 offset:96
	ds_write_b16 v165, v203 offset:160
	ds_write_b16 v165, v205 offset:224
	ds_read_b128 v[184:187], v166
	s_waitcnt lgkmcnt(0)
	global_store_dwordx4 v[174:175], v[184:187], off offset:320
	s_mov_b32 s28, 0x420000
	v_lshl_add_u64 v[174:175], v[170:171], 0, s[28:29]
	v_cvt_pk_bf16_f32 v190, v112, v113
	v_cvt_pk_bf16_f32 v191, v114, v115
	v_lshrrev_b32_e32 v192, 16, v190
	v_lshrrev_b32_e32 v193, 16, v191
	ds_write_b16 v165, v190 offset:0
	ds_write_b16 v165, v192 offset:64
	ds_write_b16 v165, v191 offset:128
	ds_write_b16 v165, v193 offset:192
	v_cvt_pk_bf16_f32 v198, v96, v97
	v_cvt_pk_bf16_f32 v199, v98, v99
	v_lshrrev_b32_e32 v200, 16, v198
	v_lshrrev_b32_e32 v201, 16, v199
	ds_write_b16 v165, v198 offset:32
	ds_write_b16 v165, v200 offset:96
	ds_write_b16 v165, v199 offset:160
	ds_write_b16 v165, v201 offset:224
	ds_read_b128 v[180:183], v166
	s_waitcnt lgkmcnt(0)
	global_store_dwordx4 v[174:175], v[180:183], off
	v_cvt_pk_bf16_f32 v194, v80, v81
	v_cvt_pk_bf16_f32 v195, v82, v83
	v_lshrrev_b32_e32 v196, 16, v194
	v_lshrrev_b32_e32 v197, 16, v195
	ds_write_b16 v165, v194 offset:0
	ds_write_b16 v165, v196 offset:64
	ds_write_b16 v165, v195 offset:128
	ds_write_b16 v165, v197 offset:192
	v_cvt_pk_bf16_f32 v202, v64, v65
	v_cvt_pk_bf16_f32 v203, v66, v67
	v_lshrrev_b32_e32 v204, 16, v202
	v_lshrrev_b32_e32 v205, 16, v203
	ds_write_b16 v165, v202 offset:32
	ds_write_b16 v165, v204 offset:96
	ds_write_b16 v165, v203 offset:160
	ds_write_b16 v165, v205 offset:224
	ds_read_b128 v[184:187], v166
	s_waitcnt lgkmcnt(0)
	global_store_dwordx4 v[174:175], v[184:187], off offset:64
	v_cvt_pk_bf16_f32 v190, v48, v49
	v_cvt_pk_bf16_f32 v191, v50, v51
	v_lshrrev_b32_e32 v192, 16, v190
	v_lshrrev_b32_e32 v193, 16, v191
	ds_write_b16 v165, v190 offset:0
	ds_write_b16 v165, v192 offset:64
	ds_write_b16 v165, v191 offset:128
	ds_write_b16 v165, v193 offset:192
	v_cvt_pk_bf16_f32 v198, v32, v33
	v_cvt_pk_bf16_f32 v199, v34, v35
	v_lshrrev_b32_e32 v200, 16, v198
	v_lshrrev_b32_e32 v201, 16, v199
	ds_write_b16 v165, v198 offset:32
	ds_write_b16 v165, v200 offset:96
	ds_write_b16 v165, v199 offset:160
	ds_write_b16 v165, v201 offset:224
	ds_read_b128 v[180:183], v166
	s_waitcnt lgkmcnt(0)
	global_store_dwordx4 v[174:175], v[180:183], off offset:256
	v_cvt_pk_bf16_f32 v194, v16, v17
	v_cvt_pk_bf16_f32 v195, v18, v19
	v_lshrrev_b32_e32 v196, 16, v194
	v_lshrrev_b32_e32 v197, 16, v195
	ds_write_b16 v165, v194 offset:0
	ds_write_b16 v165, v196 offset:64
	ds_write_b16 v165, v195 offset:128
	ds_write_b16 v165, v197 offset:192
	v_cvt_pk_bf16_f32 v202, v0, v1
	v_cvt_pk_bf16_f32 v203, v2, v3
	v_lshrrev_b32_e32 v204, 16, v202
	v_lshrrev_b32_e32 v205, 16, v203
	ds_write_b16 v165, v202 offset:32
	ds_write_b16 v165, v204 offset:96
	ds_write_b16 v165, v203 offset:160
	ds_write_b16 v165, v205 offset:224
	ds_read_b128 v[184:187], v166
	s_waitcnt lgkmcnt(0)
	global_store_dwordx4 v[174:175], v[184:187], off offset:320
	s_branch .LBB0_319
	v_lshlrev_b64 v[156:157], 15, v[148:149]
	v_lshl_add_u64 v[156:157], s[8:9], 0, v[156:157]
	v_lshl_add_u64 v[156:157], v[146:147], 1, v[156:157]
	v_add_co_u32_e32 v158, vcc, 0xfe000000, v156
	v_cvt_pk_bf16_f32 v155, v124, s0
	s_nop 0
	v_addc_co_u32_e32 v159, vcc, -1, v157, vcc
	global_store_short v[158:159], v155, off
	v_add_co_u32_e32 v158, vcc, 0xfe020000, v156
	v_cvt_pk_bf16_f32 v155, v120, s0
	s_nop 0
	v_addc_co_u32_e32 v159, vcc, -1, v157, vcc
	global_store_short v[158:159], v155, off
	v_add_co_u32_e32 v158, vcc, 0xfe008000, v156
	v_cvt_pk_bf16_f32 v155, v125, s0
	s_nop 0
	v_addc_co_u32_e32 v159, vcc, -1, v157, vcc
	global_store_short v[158:159], v155, off
	v_add_co_u32_e32 v158, vcc, 0xfe028000, v156
	v_cvt_pk_bf16_f32 v155, v121, s0
	s_nop 0
	v_addc_co_u32_e32 v159, vcc, -1, v157, vcc
	global_store_short v[158:159], v155, off
	v_add_co_u32_e32 v158, vcc, 0xfe010000, v156
	v_cvt_pk_bf16_f32 v155, v126, s0
	s_nop 0
	v_addc_co_u32_e32 v159, vcc, -1, v157, vcc
	global_store_short v[158:159], v155, off
	v_add_co_u32_e32 v158, vcc, 0xfe030000, v156
	v_cvt_pk_bf16_f32 v155, v122, s0
	s_nop 0
	v_addc_co_u32_e32 v159, vcc, -1, v157, vcc
	global_store_short v[158:159], v155, off
	v_add_co_u32_e32 v158, vcc, 0xfe018000, v156
	v_cvt_pk_bf16_f32 v155, v127, s0
	s_nop 0
	v_addc_co_u32_e32 v159, vcc, -1, v157, vcc
	v_add_co_u32_e32 v156, vcc, 0xfe038000, v156
	global_store_short v[158:159], v155, off
	v_cvt_pk_bf16_f32 v155, v123, s0
	v_addc_co_u32_e32 v157, vcc, -1, v157, vcc
	global_store_short v[156:157], v155, off
	s_mov_b64 s[0:1], 0

.LBB0_931:
	s_ashr_i32 s15, s14, 31
	s_xor_b64 s[16:17], s[28:29], -1
	s_lshl_b64 s[18:19], s[14:15], 19
	s_add_u32 s18, s42, s18
	s_addc_u32 s19, s43, s19
	s_and_b64 s[30:31], s[28:29], exec
	s_cselect_b32 s15, s19, s37
	s_cselect_b32 s63, s18, s36
	s_ashr_i32 s13, s12, 31
	s_lshl_b64 s[30:31], s[12:13], 19
	s_add_u32 s30, s44, s30
	s_addc_u32 s31, s45, s31
	s_and_b64 s[28:29], s[28:29], exec
	s_cselect_b32 s13, s31, s39
	s_cselect_b32 s28, s30, s38
	s_add_u32 s36, s36, 0x40080
	s_addc_u32 s37, s37, 0
	s_add_u32 s29, s38, 0x100
	s_addc_u32 s64, s39, 0
	s_mov_b32 s65, -2
	v_add_u32_e32 v244, 0x18000, v167
	v_add_u32_e32 v245, 0x1c000, v167
	ds_read_b128 v[128:131], v169
	ds_read_b128 v[132:135], v169 offset:1024
	ds_read_b128 v[136:139], v169 offset:2048
	ds_read_b128 v[140:143], v169 offset:3072
	s_add_u32 s38, s36, 0xfffc0080
	s_addc_u32 s39, s37, -1
	s_cmp_eq_u32 s65, 12
	s_cselect_b32 s41, s15, s39
	s_cselect_b32 s40, s63, s38
	s_cselect_b32 s39, s13, s64
	s_cselect_b32 s38, s28, s29
	s_add_i32 m0, s35, 0xc000
	ds_read_b128 v[160:163], v170
	ds_read_b128 v[172:175], v170 offset:1024
	ds_read_b128 v[176:179], v170 offset:2048
	ds_read_b128 v[180:183], v170 offset:3072
	ds_read_b128 v[184:187], v170 offset:4096
	ds_read_b128 v[188:191], v170 offset:5120
	ds_read_b128 v[192:195], v170 offset:6144
	ds_read_b128 v[196:199], v170 offset:7168
	global_load_lds_dwordx4 v154, s[36:37]
	s_add_i32 m0, s35, 0xe000
	s_nop 0
	global_load_lds_dwordx4 v156, s[36:37]
	s_waitcnt lgkmcnt(8)
	s_barrier
	s_waitcnt lgkmcnt(0)
	v_mfma_f32_16x16x32_bf16 v[124:127], v[128:131], v[160:163], 0
	v_mfma_f32_16x16x32_bf16 v[120:123], v[136:139], v[160:163], 0
	v_mfma_f32_16x16x32_bf16 v[116:119], v[128:131], v[176:179], 0
	v_mfma_f32_16x16x32_bf16 v[100:103], v[136:139], v[176:179], 0
	v_mfma_f32_16x16x32_bf16 v[92:95], v[128:131], v[184:187], 0
	v_mfma_f32_16x16x32_bf16 v[84:87], v[136:139], v[184:187], 0
	v_mfma_f32_16x16x32_bf16 v[76:79], v[128:131], v[192:195], 0
	v_mfma_f32_16x16x32_bf16 v[68:71], v[136:139], v[192:195], 0
	v_mfma_f32_16x16x32_bf16 v[124:127], v[132:135], v[172:175], v[124:127]
	v_mfma_f32_16x16x32_bf16 v[120:123], v[140:143], v[172:175], v[120:123]
	v_mfma_f32_16x16x32_bf16 v[116:119], v[132:135], v[180:183], v[116:119]
	v_mfma_f32_16x16x32_bf16 v[100:103], v[140:143], v[180:183], v[100:103]
	v_mfma_f32_16x16x32_bf16 v[92:95], v[132:135], v[188:191], v[92:95]
	v_mfma_f32_16x16x32_bf16 v[84:87], v[140:143], v[188:191], v[84:87]
	v_mfma_f32_16x16x32_bf16 v[76:79], v[132:135], v[196:199], v[76:79]
	v_mfma_f32_16x16x32_bf16 v[68:71], v[140:143], v[196:199], v[68:71]
	s_barrier
	s_add_i32 s66, s57, s46
	s_add_u32 s98, s38, s8
	s_addc_u32 s99, s39, s9
	s_mov_b32 m0, s66
	ds_read_b128 v[200:203], v171
	ds_read_b128 v[204:207], v171 offset:1024
	ds_read_b128 v[208:211], v171 offset:2048
	ds_read_b128 v[212:215], v171 offset:3072
	global_load_lds_dwordx4 v148, s[38:39]
	s_add_i32 m0, s66, 0x2000
	s_nop 0
	global_load_lds_dwordx4 v152, s[38:39]
	s_barrier
	s_waitcnt lgkmcnt(0)
	v_mfma_f32_16x16x32_bf16 v[112:115], v[200:203], v[160:163], 0
	v_mfma_f32_16x16x32_bf16 v[108:111], v[208:211], v[160:163], 0
	v_mfma_f32_16x16x32_bf16 v[104:107], v[200:203], v[176:179], 0
	v_mfma_f32_16x16x32_bf16 v[96:99], v[208:211], v[176:179], 0
	v_mfma_f32_16x16x32_bf16 v[88:91], v[200:203], v[184:187], 0
	v_mfma_f32_16x16x32_bf16 v[80:83], v[208:211], v[184:187], 0
	v_mfma_f32_16x16x32_bf16 v[72:75], v[200:203], v[192:195], 0
	v_mfma_f32_16x16x32_bf16 v[64:67], v[208:211], v[192:195], 0
	v_mfma_f32_16x16x32_bf16 v[112:115], v[204:207], v[172:175], v[112:115]
	v_mfma_f32_16x16x32_bf16 v[108:111], v[212:215], v[172:175], v[108:111]
	v_mfma_f32_16x16x32_bf16 v[104:107], v[204:207], v[180:183], v[104:107]
	v_mfma_f32_16x16x32_bf16 v[96:99], v[212:215], v[180:183], v[96:99]
	v_mfma_f32_16x16x32_bf16 v[88:91], v[204:207], v[188:191], v[88:91]
	v_mfma_f32_16x16x32_bf16 v[80:83], v[212:215], v[188:191], v[80:83]
	v_mfma_f32_16x16x32_bf16 v[72:75], v[204:207], v[196:199], v[72:75]
	v_mfma_f32_16x16x32_bf16 v[64:67], v[212:215], v[196:199], v[64:67]
	s_mov_b32 m0, s35
	s_add_u32 s100, s40, s8
	s_addc_u32 s101, s41, s9
	s_barrier
	ds_read_b128 v[160:163], v170 offset:16384
	ds_read_b128 v[172:175], v170 offset:17408
	ds_read_b128 v[176:179], v170 offset:18432
	ds_read_b128 v[180:183], v170 offset:19456
	ds_read_b128 v[184:187], v170 offset:20480
	ds_read_b128 v[188:191], v170 offset:21504
	ds_read_b128 v[192:195], v170 offset:22528
	ds_read_b128 v[196:199], v170 offset:23552
	global_load_lds_dwordx4 v146, s[40:41]
	s_mov_b32 m0, s47
	s_nop 0
	global_load_lds_dwordx4 v150, s[40:41]
	s_barrier
	s_waitcnt lgkmcnt(0)
	v_mfma_f32_16x16x32_bf16 v[60:63], v[128:131], v[160:163], 0
	v_mfma_f32_16x16x32_bf16 v[52:55], v[136:139], v[160:163], 0
	v_mfma_f32_16x16x32_bf16 v[44:47], v[128:131], v[176:179], 0
	v_mfma_f32_16x16x32_bf16 v[36:39], v[136:139], v[176:179], 0
	v_mfma_f32_16x16x32_bf16 v[28:31], v[128:131], v[184:187], 0
	v_mfma_f32_16x16x32_bf16 v[20:23], v[136:139], v[184:187], 0
	v_mfma_f32_16x16x32_bf16 v[12:15], v[128:131], v[192:195], 0
	v_mfma_f32_16x16x32_bf16 v[4:7], v[136:139], v[192:195], 0
	v_mfma_f32_16x16x32_bf16 v[60:63], v[132:135], v[172:175], v[60:63]
	v_mfma_f32_16x16x32_bf16 v[52:55], v[140:143], v[172:175], v[52:55]
	v_mfma_f32_16x16x32_bf16 v[44:47], v[132:135], v[180:183], v[44:47]
	v_mfma_f32_16x16x32_bf16 v[36:39], v[140:143], v[180:183], v[36:39]
	v_mfma_f32_16x16x32_bf16 v[28:31], v[132:135], v[188:191], v[28:31]
	v_mfma_f32_16x16x32_bf16 v[20:23], v[140:143], v[188:191], v[20:23]
	v_mfma_f32_16x16x32_bf16 v[12:15], v[132:135], v[196:199], v[12:15]
	v_mfma_f32_16x16x32_bf16 v[4:7], v[140:143], v[196:199], v[4:7]
	s_barrier
	s_add_u32 s66, s38, 0x40000
	s_addc_u32 s67, s39, 0
	s_add_i32 s68, s58, s46
	s_mov_b32 m0, s68
	s_nop 0
	global_load_lds_dwordx4 v148, s[66:67]
	s_add_i32 m0, s68, 0x2000
	s_nop 0
	global_load_lds_dwordx4 v152, s[66:67]
	s_waitcnt vmcnt(6)
	s_barrier
	v_mfma_f32_16x16x32_bf16 v[56:59], v[200:203], v[160:163], 0
	v_mfma_f32_16x16x32_bf16 v[48:51], v[208:211], v[160:163], 0
	v_mfma_f32_16x16x32_bf16 v[40:43], v[200:203], v[176:179], 0
	v_mfma_f32_16x16x32_bf16 v[32:35], v[208:211], v[176:179], 0
	v_mfma_f32_16x16x32_bf16 v[24:27], v[200:203], v[184:187], 0
	v_mfma_f32_16x16x32_bf16 v[16:19], v[208:211], v[184:187], 0
	v_mfma_f32_16x16x32_bf16 v[8:11], v[200:203], v[192:195], 0
	v_mfma_f32_16x16x32_bf16 v[0:3], v[208:211], v[192:195], 0
	v_mfma_f32_16x16x32_bf16 v[56:59], v[204:207], v[172:175], v[56:59]
	v_mfma_f32_16x16x32_bf16 v[48:51], v[212:215], v[172:175], v[48:51]
	v_mfma_f32_16x16x32_bf16 v[40:43], v[204:207], v[180:183], v[40:43]
	v_mfma_f32_16x16x32_bf16 v[32:35], v[212:215], v[180:183], v[32:35]
	v_mfma_f32_16x16x32_bf16 v[24:27], v[204:207], v[188:191], v[24:27]
	v_mfma_f32_16x16x32_bf16 v[16:19], v[212:215], v[188:191], v[16:19]
	v_mfma_f32_16x16x32_bf16 v[8:11], v[204:207], v[196:199], v[8:11]
	v_mfma_f32_16x16x32_bf16 v[0:3], v[212:215], v[196:199], v[0:3]
	s_add_i32 s66, 0, 0x18000
	s_barrier
	ds_read_b128 v[128:131], v244
	ds_read_b128 v[132:135], v244 offset:1024
	ds_read_b128 v[136:139], v244 offset:2048
	ds_read_b128 v[140:143], v244 offset:3072
	s_add_u32 s40, s40, 0x40000
	s_addc_u32 s41, s41, 0
	s_mov_b32 m0, s48
	ds_read_b128 v[160:163], v170 offset:32768
	ds_read_b128 v[172:175], v170 offset:33792
	ds_read_b128 v[176:179], v170 offset:34816
	ds_read_b128 v[180:183], v170 offset:35840
	ds_read_b128 v[184:187], v170 offset:36864
	ds_read_b128 v[188:191], v170 offset:37888
	ds_read_b128 v[192:195], v170 offset:38912
	ds_read_b128 v[196:199], v170 offset:39936
	global_load_lds_dwordx4 v146, s[40:41]
	s_mov_b32 m0, s49
	s_nop 0
	global_load_lds_dwordx4 v150, s[40:41]
	s_waitcnt lgkmcnt(8)
	s_barrier
	s_waitcnt lgkmcnt(0)
	v_mfma_f32_16x16x32_bf16 v[124:127], v[128:131], v[160:163], v[124:127]
	v_mfma_f32_16x16x32_bf16 v[120:123], v[136:139], v[160:163], v[120:123]
	v_mfma_f32_16x16x32_bf16 v[116:119], v[128:131], v[176:179], v[116:119]
	v_mfma_f32_16x16x32_bf16 v[100:103], v[136:139], v[176:179], v[100:103]
	v_mfma_f32_16x16x32_bf16 v[92:95], v[128:131], v[184:187], v[92:95]
	v_mfma_f32_16x16x32_bf16 v[84:87], v[136:139], v[184:187], v[84:87]
	v_mfma_f32_16x16x32_bf16 v[76:79], v[128:131], v[192:195], v[76:79]
	v_mfma_f32_16x16x32_bf16 v[68:71], v[136:139], v[192:195], v[68:71]
	v_mfma_f32_16x16x32_bf16 v[124:127], v[132:135], v[172:175], v[124:127]
	v_mfma_f32_16x16x32_bf16 v[120:123], v[140:143], v[172:175], v[120:123]
	v_mfma_f32_16x16x32_bf16 v[116:119], v[132:135], v[180:183], v[116:119]
	v_mfma_f32_16x16x32_bf16 v[100:103], v[140:143], v[180:183], v[100:103]
	v_mfma_f32_16x16x32_bf16 v[92:95], v[132:135], v[188:191], v[92:95]
	v_mfma_f32_16x16x32_bf16 v[84:87], v[140:143], v[188:191], v[84:87]
	v_mfma_f32_16x16x32_bf16 v[76:79], v[132:135], v[196:199], v[76:79]
	v_mfma_f32_16x16x32_bf16 v[68:71], v[140:143], v[196:199], v[68:71]
	s_barrier
	s_add_i32 s40, 0, 0x1c000
	s_add_i32 s41, s66, s46
	s_mov_b32 m0, s41
	ds_read_b128 v[200:203], v245
	ds_read_b128 v[204:207], v245 offset:1024
	ds_read_b128 v[208:211], v245 offset:2048
	ds_read_b128 v[212:215], v245 offset:3072
	global_load_lds_dwordx4 v148, s[98:99]
	s_add_i32 m0, s41, 0x2000
	s_nop 0
	global_load_lds_dwordx4 v152, s[98:99]
	s_barrier
	s_waitcnt lgkmcnt(0)
	v_mfma_f32_16x16x32_bf16 v[112:115], v[200:203], v[160:163], v[112:115]
	v_mfma_f32_16x16x32_bf16 v[108:111], v[208:211], v[160:163], v[108:111]
	v_mfma_f32_16x16x32_bf16 v[104:107], v[200:203], v[176:179], v[104:107]
	v_mfma_f32_16x16x32_bf16 v[96:99], v[208:211], v[176:179], v[96:99]
	v_mfma_f32_16x16x32_bf16 v[88:91], v[200:203], v[184:187], v[88:91]
	v_mfma_f32_16x16x32_bf16 v[80:83], v[208:211], v[184:187], v[80:83]
	v_mfma_f32_16x16x32_bf16 v[72:75], v[200:203], v[192:195], v[72:75]
	v_mfma_f32_16x16x32_bf16 v[64:67], v[208:211], v[192:195], v[64:67]
	v_mfma_f32_16x16x32_bf16 v[112:115], v[204:207], v[172:175], v[112:115]
	v_mfma_f32_16x16x32_bf16 v[108:111], v[212:215], v[172:175], v[108:111]
	v_mfma_f32_16x16x32_bf16 v[104:107], v[204:207], v[180:183], v[104:107]
	v_mfma_f32_16x16x32_bf16 v[96:99], v[212:215], v[180:183], v[96:99]
	v_mfma_f32_16x16x32_bf16 v[88:91], v[204:207], v[188:191], v[88:91]
	v_mfma_f32_16x16x32_bf16 v[80:83], v[212:215], v[188:191], v[80:83]
	v_mfma_f32_16x16x32_bf16 v[72:75], v[204:207], v[196:199], v[72:75]
	v_mfma_f32_16x16x32_bf16 v[64:67], v[212:215], v[196:199], v[64:67]
	s_mov_b32 m0, s51
	s_barrier
	ds_read_b128 v[160:163], v170 offset:49152
	ds_read_b128 v[172:175], v170 offset:50176
	ds_read_b128 v[176:179], v170 offset:51200
	ds_read_b128 v[180:183], v170 offset:52224
	ds_read_b128 v[184:187], v170 offset:53248
	ds_read_b128 v[188:191], v170 offset:54272
	ds_read_b128 v[192:195], v170 offset:55296
	ds_read_b128 v[196:199], v170 offset:56320
	global_load_lds_dwordx4 v146, s[100:101]
	s_mov_b32 m0, s54
	s_nop 0
	global_load_lds_dwordx4 v150, s[100:101]
	s_barrier
	s_waitcnt lgkmcnt(0)
	v_mfma_f32_16x16x32_bf16 v[60:63], v[128:131], v[160:163], v[60:63]
	v_mfma_f32_16x16x32_bf16 v[52:55], v[136:139], v[160:163], v[52:55]
	v_mfma_f32_16x16x32_bf16 v[44:47], v[128:131], v[176:179], v[44:47]
	v_mfma_f32_16x16x32_bf16 v[36:39], v[136:139], v[176:179], v[36:39]
	v_mfma_f32_16x16x32_bf16 v[28:31], v[128:131], v[184:187], v[28:31]
	v_mfma_f32_16x16x32_bf16 v[20:23], v[136:139], v[184:187], v[20:23]
	v_mfma_f32_16x16x32_bf16 v[12:15], v[128:131], v[192:195], v[12:15]
	v_mfma_f32_16x16x32_bf16 v[4:7], v[136:139], v[192:195], v[4:7]
	v_mfma_f32_16x16x32_bf16 v[60:63], v[132:135], v[172:175], v[60:63]
	v_mfma_f32_16x16x32_bf16 v[52:55], v[140:143], v[172:175], v[52:55]
	v_mfma_f32_16x16x32_bf16 v[44:47], v[132:135], v[180:183], v[44:47]
	v_mfma_f32_16x16x32_bf16 v[36:39], v[140:143], v[180:183], v[36:39]
	v_mfma_f32_16x16x32_bf16 v[28:31], v[132:135], v[188:191], v[28:31]
	v_mfma_f32_16x16x32_bf16 v[20:23], v[140:143], v[188:191], v[20:23]
	v_mfma_f32_16x16x32_bf16 v[12:15], v[132:135], v[196:199], v[12:15]
	v_mfma_f32_16x16x32_bf16 v[4:7], v[140:143], v[196:199], v[4:7]
	s_barrier
	s_add_u32 s38, s38, 0x40080
	s_addc_u32 s39, s39, 0
	s_add_i32 s40, s40, s46
	s_mov_b32 m0, s40
	s_nop 0
	global_load_lds_dwordx4 v148, s[38:39]
	s_add_i32 m0, s40, 0x2000
	s_nop 0
	global_load_lds_dwordx4 v152, s[38:39]
	s_waitcnt vmcnt(6)
	s_barrier
	v_mfma_f32_16x16x32_bf16 v[56:59], v[200:203], v[160:163], v[56:59]
	v_mfma_f32_16x16x32_bf16 v[48:51], v[208:211], v[160:163], v[48:51]
	v_mfma_f32_16x16x32_bf16 v[40:43], v[200:203], v[176:179], v[40:43]
	v_mfma_f32_16x16x32_bf16 v[32:35], v[208:211], v[176:179], v[32:35]
	v_mfma_f32_16x16x32_bf16 v[24:27], v[200:203], v[184:187], v[24:27]
	v_mfma_f32_16x16x32_bf16 v[16:19], v[208:211], v[184:187], v[16:19]
	v_mfma_f32_16x16x32_bf16 v[8:11], v[200:203], v[192:195], v[8:11]
	v_mfma_f32_16x16x32_bf16 v[0:3], v[208:211], v[192:195], v[0:3]
	v_mfma_f32_16x16x32_bf16 v[56:59], v[204:207], v[172:175], v[56:59]
	v_mfma_f32_16x16x32_bf16 v[48:51], v[212:215], v[172:175], v[48:51]
	v_mfma_f32_16x16x32_bf16 v[40:43], v[204:207], v[180:183], v[40:43]
	v_mfma_f32_16x16x32_bf16 v[32:35], v[212:215], v[180:183], v[32:35]
	v_mfma_f32_16x16x32_bf16 v[24:27], v[204:207], v[188:191], v[24:27]
	v_mfma_f32_16x16x32_bf16 v[16:19], v[212:215], v[188:191], v[16:19]
	v_mfma_f32_16x16x32_bf16 v[8:11], v[204:207], v[196:199], v[8:11]
	v_mfma_f32_16x16x32_bf16 v[0:3], v[212:215], v[196:199], v[0:3]
	s_add_i32 s65, s65, 2
	s_add_u32 s36, s36, 0x100
	s_addc_u32 s37, s37, 0
	s_add_u32 s29, s29, 0x100
	s_addc_u32 s64, s64, 0
	s_cmp_gt_u32 s65, 13
	s_barrier
	s_cbranch_scc0 .LBB0_932
.LBB0_932:
	ds_read_b128 v[128:131], v169
	ds_read_b128 v[132:135], v169 offset:1024
	ds_read_b128 v[136:139], v169 offset:2048
	ds_read_b128 v[140:143], v169 offset:3072
	s_add_u32 s38, s36, 0xfffc0080
	s_addc_u32 s39, s37, -1
	s_cmp_eq_u32 s65, 12
	s_cselect_b32 s41, s15, s39
	s_cselect_b32 s40, s63, s38
	s_cselect_b32 s39, s13, s64
	s_cselect_b32 s38, s28, s29
	s_add_i32 m0, s35, 0xc000
	ds_read_b128 v[160:163], v170
	ds_read_b128 v[172:175], v170 offset:1024
	ds_read_b128 v[176:179], v170 offset:2048
	ds_read_b128 v[180:183], v170 offset:3072
	ds_read_b128 v[184:187], v170 offset:4096
	ds_read_b128 v[188:191], v170 offset:5120
	ds_read_b128 v[192:195], v170 offset:6144
	ds_read_b128 v[196:199], v170 offset:7168
	global_load_lds_dwordx4 v154, s[36:37]
	s_add_i32 m0, s35, 0xe000
	s_nop 0
	global_load_lds_dwordx4 v156, s[36:37]
	s_waitcnt lgkmcnt(8)
	s_barrier
	s_waitcnt lgkmcnt(0)
	v_mfma_f32_16x16x32_bf16 v[124:127], v[128:131], v[160:163], v[124:127]
	v_mfma_f32_16x16x32_bf16 v[120:123], v[136:139], v[160:163], v[120:123]
	v_mfma_f32_16x16x32_bf16 v[116:119], v[128:131], v[176:179], v[116:119]
	v_mfma_f32_16x16x32_bf16 v[100:103], v[136:139], v[176:179], v[100:103]
	v_mfma_f32_16x16x32_bf16 v[92:95], v[128:131], v[184:187], v[92:95]
	v_mfma_f32_16x16x32_bf16 v[84:87], v[136:139], v[184:187], v[84:87]
	v_mfma_f32_16x16x32_bf16 v[76:79], v[128:131], v[192:195], v[76:79]
	v_mfma_f32_16x16x32_bf16 v[68:71], v[136:139], v[192:195], v[68:71]
	v_mfma_f32_16x16x32_bf16 v[124:127], v[132:135], v[172:175], v[124:127]
	v_mfma_f32_16x16x32_bf16 v[120:123], v[140:143], v[172:175], v[120:123]
	v_mfma_f32_16x16x32_bf16 v[116:119], v[132:135], v[180:183], v[116:119]
	v_mfma_f32_16x16x32_bf16 v[100:103], v[140:143], v[180:183], v[100:103]
	v_mfma_f32_16x16x32_bf16 v[92:95], v[132:135], v[188:191], v[92:95]
	v_mfma_f32_16x16x32_bf16 v[84:87], v[140:143], v[188:191], v[84:87]
	v_mfma_f32_16x16x32_bf16 v[76:79], v[132:135], v[196:199], v[76:79]
	v_mfma_f32_16x16x32_bf16 v[68:71], v[140:143], v[196:199], v[68:71]
	s_barrier
	s_add_i32 s66, s57, s46
	s_add_u32 s98, s38, s8
	s_addc_u32 s99, s39, s9
	s_mov_b32 m0, s66
	ds_read_b128 v[200:203], v171
	ds_read_b128 v[204:207], v171 offset:1024
	ds_read_b128 v[208:211], v171 offset:2048
	ds_read_b128 v[212:215], v171 offset:3072
	global_load_lds_dwordx4 v148, s[38:39]
	s_add_i32 m0, s66, 0x2000
	s_nop 0
	global_load_lds_dwordx4 v152, s[38:39]
	s_barrier
	s_waitcnt lgkmcnt(0)
	v_mfma_f32_16x16x32_bf16 v[112:115], v[200:203], v[160:163], v[112:115]
	v_mfma_f32_16x16x32_bf16 v[108:111], v[208:211], v[160:163], v[108:111]
	v_mfma_f32_16x16x32_bf16 v[104:107], v[200:203], v[176:179], v[104:107]
	v_mfma_f32_16x16x32_bf16 v[96:99], v[208:211], v[176:179], v[96:99]
	v_mfma_f32_16x16x32_bf16 v[88:91], v[200:203], v[184:187], v[88:91]
	v_mfma_f32_16x16x32_bf16 v[80:83], v[208:211], v[184:187], v[80:83]
	v_mfma_f32_16x16x32_bf16 v[72:75], v[200:203], v[192:195], v[72:75]
	v_mfma_f32_16x16x32_bf16 v[64:67], v[208:211], v[192:195], v[64:67]
	v_mfma_f32_16x16x32_bf16 v[112:115], v[204:207], v[172:175], v[112:115]
	v_mfma_f32_16x16x32_bf16 v[108:111], v[212:215], v[172:175], v[108:111]
	v_mfma_f32_16x16x32_bf16 v[104:107], v[204:207], v[180:183], v[104:107]
	v_mfma_f32_16x16x32_bf16 v[96:99], v[212:215], v[180:183], v[96:99]
	v_mfma_f32_16x16x32_bf16 v[88:91], v[204:207], v[188:191], v[88:91]
	v_mfma_f32_16x16x32_bf16 v[80:83], v[212:215], v[188:191], v[80:83]
	v_mfma_f32_16x16x32_bf16 v[72:75], v[204:207], v[196:199], v[72:75]
	v_mfma_f32_16x16x32_bf16 v[64:67], v[212:215], v[196:199], v[64:67]
	s_mov_b32 m0, s35
	s_add_u32 s100, s40, s8
	s_addc_u32 s101, s41, s9
	s_barrier
	ds_read_b128 v[160:163], v170 offset:16384
	ds_read_b128 v[172:175], v170 offset:17408
	ds_read_b128 v[176:179], v170 offset:18432
	ds_read_b128 v[180:183], v170 offset:19456
	ds_read_b128 v[184:187], v170 offset:20480
	ds_read_b128 v[188:191], v170 offset:21504
	ds_read_b128 v[192:195], v170 offset:22528
	ds_read_b128 v[196:199], v170 offset:23552
	global_load_lds_dwordx4 v146, s[40:41]
	s_mov_b32 m0, s47
	s_nop 0
	global_load_lds_dwordx4 v150, s[40:41]
	s_barrier
	s_waitcnt lgkmcnt(0)
	v_mfma_f32_16x16x32_bf16 v[60:63], v[128:131], v[160:163], v[60:63]
	v_mfma_f32_16x16x32_bf16 v[52:55], v[136:139], v[160:163], v[52:55]
	v_mfma_f32_16x16x32_bf16 v[44:47], v[128:131], v[176:179], v[44:47]
	v_mfma_f32_16x16x32_bf16 v[36:39], v[136:139], v[176:179], v[36:39]
	v_mfma_f32_16x16x32_bf16 v[28:31], v[128:131], v[184:187], v[28:31]
	v_mfma_f32_16x16x32_bf16 v[20:23], v[136:139], v[184:187], v[20:23]
	v_mfma_f32_16x16x32_bf16 v[12:15], v[128:131], v[192:195], v[12:15]
	v_mfma_f32_16x16x32_bf16 v[4:7], v[136:139], v[192:195], v[4:7]
	v_mfma_f32_16x16x32_bf16 v[60:63], v[132:135], v[172:175], v[60:63]
	v_mfma_f32_16x16x32_bf16 v[52:55], v[140:143], v[172:175], v[52:55]
	v_mfma_f32_16x16x32_bf16 v[44:47], v[132:135], v[180:183], v[44:47]
	v_mfma_f32_16x16x32_bf16 v[36:39], v[140:143], v[180:183], v[36:39]
	v_mfma_f32_16x16x32_bf16 v[28:31], v[132:135], v[188:191], v[28:31]
	v_mfma_f32_16x16x32_bf16 v[20:23], v[140:143], v[188:191], v[20:23]
	v_mfma_f32_16x16x32_bf16 v[12:15], v[132:135], v[196:199], v[12:15]
	v_mfma_f32_16x16x32_bf16 v[4:7], v[140:143], v[196:199], v[4:7]
	s_barrier
	s_add_u32 s66, s38, 0x40000
	s_addc_u32 s67, s39, 0
	s_add_i32 s68, s58, s46
	s_mov_b32 m0, s68
	s_nop 0
	global_load_lds_dwordx4 v148, s[66:67]
	s_add_i32 m0, s68, 0x2000
	s_nop 0
	global_load_lds_dwordx4 v152, s[66:67]
	s_waitcnt vmcnt(6)
	s_barrier
	v_mfma_f32_16x16x32_bf16 v[56:59], v[200:203], v[160:163], v[56:59]
	v_mfma_f32_16x16x32_bf16 v[48:51], v[208:211], v[160:163], v[48:51]
	v_mfma_f32_16x16x32_bf16 v[40:43], v[200:203], v[176:179], v[40:43]
	v_mfma_f32_16x16x32_bf16 v[32:35], v[208:211], v[176:179], v[32:35]
	v_mfma_f32_16x16x32_bf16 v[24:27], v[200:203], v[184:187], v[24:27]
	v_mfma_f32_16x16x32_bf16 v[16:19], v[208:211], v[184:187], v[16:19]
	v_mfma_f32_16x16x32_bf16 v[8:11], v[200:203], v[192:195], v[8:11]
	v_mfma_f32_16x16x32_bf16 v[0:3], v[208:211], v[192:195], v[0:3]
	v_mfma_f32_16x16x32_bf16 v[56:59], v[204:207], v[172:175], v[56:59]
	v_mfma_f32_16x16x32_bf16 v[48:51], v[212:215], v[172:175], v[48:51]
	v_mfma_f32_16x16x32_bf16 v[40:43], v[204:207], v[180:183], v[40:43]
	v_mfma_f32_16x16x32_bf16 v[32:35], v[212:215], v[180:183], v[32:35]
	v_mfma_f32_16x16x32_bf16 v[24:27], v[204:207], v[188:191], v[24:27]
	v_mfma_f32_16x16x32_bf16 v[16:19], v[212:215], v[188:191], v[16:19]
	v_mfma_f32_16x16x32_bf16 v[8:11], v[204:207], v[196:199], v[8:11]
	v_mfma_f32_16x16x32_bf16 v[0:3], v[212:215], v[196:199], v[0:3]
	s_add_i32 s66, 0, 0x18000
	s_barrier
	ds_read_b128 v[128:131], v244
	ds_read_b128 v[132:135], v244 offset:1024
	ds_read_b128 v[136:139], v244 offset:2048
	ds_read_b128 v[140:143], v244 offset:3072
	s_add_u32 s40, s40, 0x40000
	s_addc_u32 s41, s41, 0
	s_mov_b32 m0, s48
	ds_read_b128 v[160:163], v170 offset:32768
	ds_read_b128 v[172:175], v170 offset:33792
	ds_read_b128 v[176:179], v170 offset:34816
	ds_read_b128 v[180:183], v170 offset:35840
	ds_read_b128 v[184:187], v170 offset:36864
	ds_read_b128 v[188:191], v170 offset:37888
	ds_read_b128 v[192:195], v170 offset:38912
	ds_read_b128 v[196:199], v170 offset:39936
	global_load_lds_dwordx4 v146, s[40:41]
	s_mov_b32 m0, s49
	s_nop 0
	global_load_lds_dwordx4 v150, s[40:41]
	s_waitcnt lgkmcnt(8)
	s_barrier
	s_waitcnt lgkmcnt(0)
	v_mfma_f32_16x16x32_bf16 v[124:127], v[128:131], v[160:163], v[124:127]
	v_mfma_f32_16x16x32_bf16 v[120:123], v[136:139], v[160:163], v[120:123]
	v_mfma_f32_16x16x32_bf16 v[116:119], v[128:131], v[176:179], v[116:119]
	v_mfma_f32_16x16x32_bf16 v[100:103], v[136:139], v[176:179], v[100:103]
	v_mfma_f32_16x16x32_bf16 v[92:95], v[128:131], v[184:187], v[92:95]
	v_mfma_f32_16x16x32_bf16 v[84:87], v[136:139], v[184:187], v[84:87]
	v_mfma_f32_16x16x32_bf16 v[76:79], v[128:131], v[192:195], v[76:79]
	v_mfma_f32_16x16x32_bf16 v[68:71], v[136:139], v[192:195], v[68:71]
	v_mfma_f32_16x16x32_bf16 v[124:127], v[132:135], v[172:175], v[124:127]
	v_mfma_f32_16x16x32_bf16 v[120:123], v[140:143], v[172:175], v[120:123]
	v_mfma_f32_16x16x32_bf16 v[116:119], v[132:135], v[180:183], v[116:119]
	v_mfma_f32_16x16x32_bf16 v[100:103], v[140:143], v[180:183], v[100:103]
	v_mfma_f32_16x16x32_bf16 v[92:95], v[132:135], v[188:191], v[92:95]
	v_mfma_f32_16x16x32_bf16 v[84:87], v[140:143], v[188:191], v[84:87]
	v_mfma_f32_16x16x32_bf16 v[76:79], v[132:135], v[196:199], v[76:79]
	v_mfma_f32_16x16x32_bf16 v[68:71], v[140:143], v[196:199], v[68:71]
	s_barrier
	s_add_i32 s40, 0, 0x1c000
	s_add_i32 s41, s66, s46
	s_mov_b32 m0, s41
	ds_read_b128 v[200:203], v245
	ds_read_b128 v[204:207], v245 offset:1024
	ds_read_b128 v[208:211], v245 offset:2048
	ds_read_b128 v[212:215], v245 offset:3072
	global_load_lds_dwordx4 v148, s[98:99]
	s_add_i32 m0, s41, 0x2000
	s_nop 0
	global_load_lds_dwordx4 v152, s[98:99]
	s_barrier
	s_waitcnt lgkmcnt(0)
	v_mfma_f32_16x16x32_bf16 v[112:115], v[200:203], v[160:163], v[112:115]
	v_mfma_f32_16x16x32_bf16 v[108:111], v[208:211], v[160:163], v[108:111]
	v_mfma_f32_16x16x32_bf16 v[104:107], v[200:203], v[176:179], v[104:107]
	v_mfma_f32_16x16x32_bf16 v[96:99], v[208:211], v[176:179], v[96:99]
	v_mfma_f32_16x16x32_bf16 v[88:91], v[200:203], v[184:187], v[88:91]
	v_mfma_f32_16x16x32_bf16 v[80:83], v[208:211], v[184:187], v[80:83]
	v_mfma_f32_16x16x32_bf16 v[72:75], v[200:203], v[192:195], v[72:75]
	v_mfma_f32_16x16x32_bf16 v[64:67], v[208:211], v[192:195], v[64:67]
	v_mfma_f32_16x16x32_bf16 v[112:115], v[204:207], v[172:175], v[112:115]
	v_mfma_f32_16x16x32_bf16 v[108:111], v[212:215], v[172:175], v[108:111]
	v_mfma_f32_16x16x32_bf16 v[104:107], v[204:207], v[180:183], v[104:107]
	v_mfma_f32_16x16x32_bf16 v[96:99], v[212:215], v[180:183], v[96:99]
	v_mfma_f32_16x16x32_bf16 v[88:91], v[204:207], v[188:191], v[88:91]
	v_mfma_f32_16x16x32_bf16 v[80:83], v[212:215], v[188:191], v[80:83]
	v_mfma_f32_16x16x32_bf16 v[72:75], v[204:207], v[196:199], v[72:75]
	v_mfma_f32_16x16x32_bf16 v[64:67], v[212:215], v[196:199], v[64:67]
	s_mov_b32 m0, s51
	s_barrier
	ds_read_b128 v[160:163], v170 offset:49152
	ds_read_b128 v[172:175], v170 offset:50176
	ds_read_b128 v[176:179], v170 offset:51200
	ds_read_b128 v[180:183], v170 offset:52224
	ds_read_b128 v[184:187], v170 offset:53248
	ds_read_b128 v[188:191], v170 offset:54272
	ds_read_b128 v[192:195], v170 offset:55296
	ds_read_b128 v[196:199], v170 offset:56320
	global_load_lds_dwordx4 v146, s[100:101]
	s_mov_b32 m0, s54
	s_nop 0
	global_load_lds_dwordx4 v150, s[100:101]
	s_barrier
	s_waitcnt lgkmcnt(0)
	v_mfma_f32_16x16x32_bf16 v[60:63], v[128:131], v[160:163], v[60:63]
	v_mfma_f32_16x16x32_bf16 v[52:55], v[136:139], v[160:163], v[52:55]
	v_mfma_f32_16x16x32_bf16 v[44:47], v[128:131], v[176:179], v[44:47]
	v_mfma_f32_16x16x32_bf16 v[36:39], v[136:139], v[176:179], v[36:39]
	v_mfma_f32_16x16x32_bf16 v[28:31], v[128:131], v[184:187], v[28:31]
	v_mfma_f32_16x16x32_bf16 v[20:23], v[136:139], v[184:187], v[20:23]
	v_mfma_f32_16x16x32_bf16 v[12:15], v[128:131], v[192:195], v[12:15]
	v_mfma_f32_16x16x32_bf16 v[4:7], v[136:139], v[192:195], v[4:7]
	v_mfma_f32_16x16x32_bf16 v[60:63], v[132:135], v[172:175], v[60:63]
	v_mfma_f32_16x16x32_bf16 v[52:55], v[140:143], v[172:175], v[52:55]
	v_mfma_f32_16x16x32_bf16 v[44:47], v[132:135], v[180:183], v[44:47]
	v_mfma_f32_16x16x32_bf16 v[36:39], v[140:143], v[180:183], v[36:39]
	v_mfma_f32_16x16x32_bf16 v[28:31], v[132:135], v[188:191], v[28:31]
	v_mfma_f32_16x16x32_bf16 v[20:23], v[140:143], v[188:191], v[20:23]
	v_mfma_f32_16x16x32_bf16 v[12:15], v[132:135], v[196:199], v[12:15]
	v_mfma_f32_16x16x32_bf16 v[4:7], v[140:143], v[196:199], v[4:7]
	s_barrier
	s_add_u32 s38, s38, 0x40080
	s_addc_u32 s39, s39, 0
	s_add_i32 s40, s40, s46
	s_mov_b32 m0, s40
	s_nop 0
	global_load_lds_dwordx4 v148, s[38:39]
	s_add_i32 m0, s40, 0x2000
	s_nop 0
	global_load_lds_dwordx4 v152, s[38:39]
	s_waitcnt vmcnt(6)
	s_barrier
	v_mfma_f32_16x16x32_bf16 v[56:59], v[200:203], v[160:163], v[56:59]
	v_mfma_f32_16x16x32_bf16 v[48:51], v[208:211], v[160:163], v[48:51]
	v_mfma_f32_16x16x32_bf16 v[40:43], v[200:203], v[176:179], v[40:43]
	v_mfma_f32_16x16x32_bf16 v[32:35], v[208:211], v[176:179], v[32:35]
	v_mfma_f32_16x16x32_bf16 v[24:27], v[200:203], v[184:187], v[24:27]
	v_mfma_f32_16x16x32_bf16 v[16:19], v[208:211], v[184:187], v[16:19]
	v_mfma_f32_16x16x32_bf16 v[8:11], v[200:203], v[192:195], v[8:11]
	v_mfma_f32_16x16x32_bf16 v[0:3], v[208:211], v[192:195], v[0:3]
	v_mfma_f32_16x16x32_bf16 v[56:59], v[204:207], v[172:175], v[56:59]
	v_mfma_f32_16x16x32_bf16 v[48:51], v[212:215], v[172:175], v[48:51]
	v_mfma_f32_16x16x32_bf16 v[40:43], v[204:207], v[180:183], v[40:43]
	v_mfma_f32_16x16x32_bf16 v[32:35], v[212:215], v[180:183], v[32:35]
	v_mfma_f32_16x16x32_bf16 v[24:27], v[204:207], v[188:191], v[24:27]
	v_mfma_f32_16x16x32_bf16 v[16:19], v[212:215], v[188:191], v[16:19]
	v_mfma_f32_16x16x32_bf16 v[8:11], v[204:207], v[196:199], v[8:11]
	v_mfma_f32_16x16x32_bf16 v[0:3], v[212:215], v[196:199], v[0:3]
	s_add_i32 s65, s65, 2
	s_add_u32 s36, s36, 0x100
	s_addc_u32 s37, s37, 0
	s_add_u32 s29, s29, 0x100
	s_addc_u32 s64, s64, 0
	s_cmp_gt_u32 s65, 13
	s_barrier
	s_cbranch_scc0 .LBB0_932
	v_lshl_or_b32 v160, s62, 7, v168
	v_ashrrev_i32_e32 v161, 31, v160
	v_lshlrev_b64 v[128:129], 2, v[160:161]
	v_readlane_b32 s64, v248, 24
	v_lshl_add_u64 v[130:131], s[10:11], 0, v[128:129]
	v_readlane_b32 s70, v248, 30
	v_readlane_b32 s71, v248, 31
	global_load_dwordx4 v[136:139], v[130:131], off
	v_lshl_add_u32 v162, s34, 8, v166
	v_lshl_add_u64 v[128:129], s[70:71], 0, v[128:129]
	global_load_dwordx4 v[140:143], v[128:129], off
	global_load_dwordx4 v[132:135], v[130:131], off offset:16
	s_nop 0
	global_load_dwordx4 v[128:131], v[128:129], off offset:16
	v_ashrrev_i32_e32 v163, 31, v162
	v_lshlrev_b64 v[172:173], 12, v[162:163]
	v_lshlrev_b64 v[164:165], 1, v[160:161]
	v_lshl_add_u64 v[160:161], s[6:7], 0, v[172:173]
	v_lshl_add_u64 v[160:161], v[160:161], 0, v[164:165]
	s_mov_b32 s62, s12
	s_mov_b32 s34, s14
	s_mov_b64 s[38:39], s[30:31]
	s_mov_b64 s[36:37], s[18:19]
	v_readlane_b32 s65, v248, 25
	v_readlane_b32 s66, v248, 26
	v_readlane_b32 s67, v248, 27
	v_readlane_b32 s68, v248, 28
	v_readlane_b32 s69, v248, 29
	v_readlane_b32 s72, v248, 32
	v_readlane_b32 s73, v248, 33
	v_readlane_b32 s74, v248, 34
	v_readlane_b32 s75, v248, 35
	v_readlane_b32 s76, v248, 36
	v_readlane_b32 s77, v248, 37
	v_readlane_b32 s78, v248, 38
	v_readlane_b32 s79, v248, 39
	s_waitcnt vmcnt(0)
	v_add_f32_e32 v163, v112, v136
	v_add_f32_e32 v172, v113, v137
	v_add_f32_e32 v48, v48, v132
	v_add_f32_e32 v49, v49, v133
	v_pk_add_f32 v[112:113], v[126:127], v[142:143]
	v_add_f32_e32 v126, v114, v138
	v_add_f32_e32 v127, v115, v139
	v_add_f32_e32 v173, v108, v132
	v_add_f32_e32 v174, v109, v133
	v_pk_add_f32 v[108:109], v[122:123], v[130:131]
	v_pk_add_f32 v[114:115], v[120:121], v[128:129]
	v_add_f32_e32 v120, v110, v134
	v_add_f32_e32 v121, v111, v135
	v_add_f32_e32 v122, v104, v136
	v_add_f32_e32 v123, v105, v137
	v_pk_add_f32 v[110:111], v[116:117], v[140:141]
	v_add_f32_e32 v106, v106, v138
	v_add_f32_e32 v107, v107, v139
	v_mul_f32_e32 v116, 0xbfb8aa3b, v163
	v_mul_f32_e32 v117, 0xbfb8aa3b, v172
	v_mul_f32_e32 v48, 0xbfb8aa3b, v48
	v_mul_f32_e32 v49, 0xbfb8aa3b, v49
	v_add_f32_e32 v50, v50, v134
	v_add_f32_e32 v51, v51, v135
	v_pk_add_f32 v[104:105], v[118:119], v[142:143]
	v_mul_f32_e32 v118, 0xbfb8aa3b, v126
	v_mul_f32_e32 v119, 0xbfb8aa3b, v127
	v_mul_f32_e32 v126, 0xbfb8aa3b, v173
	v_mul_f32_e32 v127, 0xbfb8aa3b, v174
	v_mul_f32_e32 v120, 0xbfb8aa3b, v120
	v_mul_f32_e32 v121, 0xbfb8aa3b, v121
	v_mul_f32_e32 v122, 0xbfb8aa3b, v122
	v_mul_f32_e32 v123, 0xbfb8aa3b, v123
	v_mul_f32_e32 v106, 0xbfb8aa3b, v106
	v_mul_f32_e32 v107, 0xbfb8aa3b, v107
	v_exp_f32_e32 v116, v116
	v_exp_f32_e32 v117, v117
	v_exp_f32_e32 v48, v48
	v_exp_f32_e32 v49, v49
	v_mul_f32_e32 v50, 0xbfb8aa3b, v50
	v_mul_f32_e32 v51, 0xbfb8aa3b, v51
	v_add_f32_e32 v32, v32, v132
	v_add_f32_e32 v33, v33, v133
	v_exp_f32_e32 v118, v118
	v_exp_f32_e32 v119, v119
	v_exp_f32_e32 v126, v126
	v_exp_f32_e32 v127, v127
	v_exp_f32_e32 v120, v120
	v_exp_f32_e32 v121, v121
	v_exp_f32_e32 v122, v122
	v_exp_f32_e32 v123, v123
	v_exp_f32_e32 v106, v106
	v_exp_f32_e32 v107, v107
	v_exp_f32_e32 v50, v50
	v_exp_f32_e32 v51, v51
	v_mul_f32_e32 v32, 0xbfb8aa3b, v32
	v_mul_f32_e32 v33, 0xbfb8aa3b, v33
	v_add_f32_e32 v34, v34, v134
	v_add_f32_e32 v35, v35, v135
	v_add_f32_e32 v96, v96, v132
	v_add_f32_e32 v97, v97, v133
	v_exp_f32_e32 v32, v32
	v_exp_f32_e32 v33, v33
	v_mul_f32_e32 v34, 0xbfb8aa3b, v34
	v_mul_f32_e32 v35, 0xbfb8aa3b, v35
	v_add_f32_e32 v16, v16, v132
	v_add_f32_e32 v17, v17, v133
	v_mul_f32_e32 v96, 0xbfb8aa3b, v96
	v_mul_f32_e32 v97, 0xbfb8aa3b, v97
	v_add_f32_e32 v88, v88, v136
	v_add_f32_e32 v89, v89, v137
	v_add_f32_e32 v72, v72, v136
	v_add_f32_e32 v73, v73, v137
	v_exp_f32_e32 v34, v34
	v_exp_f32_e32 v35, v35
	v_mul_f32_e32 v16, 0xbfb8aa3b, v16
	v_mul_f32_e32 v17, 0xbfb8aa3b, v17
	v_add_f32_e32 v18, v18, v134
	v_add_f32_e32 v19, v19, v135
	v_exp_f32_e32 v163, v96
	v_exp_f32_e32 v172, v97
	v_add_f32_e32 v96, 1.0, v116
	v_add_f32_e32 v97, 1.0, v117
	v_mul_f32_e32 v88, 0xbfb8aa3b, v88
	v_mul_f32_e32 v89, 0xbfb8aa3b, v89
	v_add_f32_e32 v80, v80, v132
	v_add_f32_e32 v81, v81, v133
	v_mul_f32_e32 v72, 0xbfb8aa3b, v72
	v_mul_f32_e32 v73, 0xbfb8aa3b, v73
	v_add_f32_e32 v64, v64, v132
	v_add_f32_e32 v65, v65, v133
	v_add_f32_e32 v48, 1.0, v48
	v_add_f32_e32 v49, 1.0, v49
	v_exp_f32_e32 v16, v16
	v_exp_f32_e32 v17, v17
	v_mul_f32_e32 v18, 0xbfb8aa3b, v18
	v_mul_f32_e32 v19, 0xbfb8aa3b, v19
	v_add_f32_e32 v0, v0, v132
	v_add_f32_e32 v1, v1, v133
	v_add_f32_e32 v116, 1.0, v118
	v_add_f32_e32 v117, 1.0, v119
	v_add_f32_e32 v118, 1.0, v126
	v_add_f32_e32 v119, 1.0, v127
	v_add_f32_e32 v120, 1.0, v120
	v_add_f32_e32 v121, 1.0, v121
	v_add_f32_e32 v122, 1.0, v122
	v_add_f32_e32 v123, 1.0, v123
	v_add_f32_e32 v126, 1.0, v106
	v_add_f32_e32 v127, 1.0, v107
	v_rcp_f32_e32 v96, v96
	v_rcp_f32_e32 v97, v97
	v_add_f32_e32 v98, v98, v134
	v_add_f32_e32 v99, v99, v135
	v_exp_f32_e32 v88, v88
	v_exp_f32_e32 v89, v89
	v_mul_f32_e32 v80, 0xbfb8aa3b, v80
	v_mul_f32_e32 v81, 0xbfb8aa3b, v81
	v_add_f32_e32 v82, v82, v134
	v_add_f32_e32 v83, v83, v135
	v_exp_f32_e32 v72, v72
	v_exp_f32_e32 v73, v73
	v_mul_f32_e32 v64, 0xbfb8aa3b, v64
	v_mul_f32_e32 v65, 0xbfb8aa3b, v65
	v_add_f32_e32 v66, v66, v134
	v_add_f32_e32 v67, v67, v135
	v_rcp_f32_e32 v48, v48
	v_rcp_f32_e32 v49, v49
	v_add_f32_e32 v50, 1.0, v50
	v_add_f32_e32 v51, 1.0, v51
	v_exp_f32_e32 v18, v18
	v_exp_f32_e32 v19, v19
	v_mul_f32_e32 v0, 0xbfb8aa3b, v0
	v_mul_f32_e32 v1, 0xbfb8aa3b, v1
	v_add_f32_e32 v2, v2, v134
	v_add_f32_e32 v3, v3, v135
	v_rcp_f32_e32 v106, v116
	v_rcp_f32_e32 v107, v117
	v_rcp_f32_e32 v116, v118
	v_rcp_f32_e32 v117, v119
	v_rcp_f32_e32 v118, v120
	v_rcp_f32_e32 v119, v121
	v_rcp_f32_e32 v120, v122
	v_rcp_f32_e32 v121, v123
	v_rcp_f32_e32 v122, v126
	v_rcp_f32_e32 v123, v127
	v_mul_f32_e32 v98, 0xbfb8aa3b, v98
	v_mul_f32_e32 v99, 0xbfb8aa3b, v99
	v_add_f32_e32 v90, v90, v138
	v_add_f32_e32 v91, v91, v139
	v_exp_f32_e32 v80, v80
	v_exp_f32_e32 v81, v81
	v_mul_f32_e32 v82, 0xbfb8aa3b, v82
	v_mul_f32_e32 v83, 0xbfb8aa3b, v83
	v_add_f32_e32 v74, v74, v138
	v_add_f32_e32 v75, v75, v139
	v_exp_f32_e32 v64, v64
	v_exp_f32_e32 v65, v65
	v_mul_f32_e32 v66, 0xbfb8aa3b, v66
	v_mul_f32_e32 v67, 0xbfb8aa3b, v67
	v_add_f32_e32 v56, v56, v136
	v_add_f32_e32 v57, v57, v137
	v_add_f32_e32 v58, v58, v138
	v_add_f32_e32 v59, v59, v139
	v_rcp_f32_e32 v50, v50
	v_rcp_f32_e32 v51, v51
	v_add_f32_e32 v40, v40, v136
	v_add_f32_e32 v41, v41, v137
	v_add_f32_e32 v42, v42, v138
	v_add_f32_e32 v43, v43, v139
	v_add_f32_e32 v32, 1.0, v32
	v_add_f32_e32 v33, 1.0, v33
	v_add_f32_e32 v24, v24, v136
	v_add_f32_e32 v25, v25, v137
	v_add_f32_e32 v26, v26, v138
	v_add_f32_e32 v27, v27, v139
	v_add_f32_e32 v8, v8, v136
	v_add_f32_e32 v9, v9, v137
	v_add_f32_e32 v10, v10, v138
	v_add_f32_e32 v11, v11, v139
	v_exp_f32_e32 v0, v0
	v_exp_f32_e32 v1, v1
	v_mul_f32_e32 v2, 0xbfb8aa3b, v2
	v_mul_f32_e32 v3, 0xbfb8aa3b, v3
	v_exp_f32_e32 v98, v98
	v_exp_f32_e32 v99, v99
	v_mul_f32_e32 v90, 0xbfb8aa3b, v90
	v_mul_f32_e32 v91, 0xbfb8aa3b, v91
	v_exp_f32_e32 v82, v82
	v_exp_f32_e32 v83, v83
	v_mul_f32_e32 v74, 0xbfb8aa3b, v74
	v_mul_f32_e32 v75, 0xbfb8aa3b, v75
	v_exp_f32_e32 v66, v66
	v_exp_f32_e32 v67, v67
	v_mul_f32_e32 v56, 0xbfb8aa3b, v56
	v_mul_f32_e32 v57, 0xbfb8aa3b, v57
	v_mul_f32_e32 v58, 0xbfb8aa3b, v58
	v_mul_f32_e32 v59, 0xbfb8aa3b, v59
	v_mul_f32_e32 v40, 0xbfb8aa3b, v40
	v_mul_f32_e32 v41, 0xbfb8aa3b, v41
	v_mul_f32_e32 v42, 0xbfb8aa3b, v42
	v_mul_f32_e32 v43, 0xbfb8aa3b, v43
	v_rcp_f32_e32 v32, v32
	v_rcp_f32_e32 v33, v33
	v_add_f32_e32 v34, 1.0, v34
	v_add_f32_e32 v35, 1.0, v35
	v_mul_f32_e32 v24, 0xbfb8aa3b, v24
	v_mul_f32_e32 v25, 0xbfb8aa3b, v25
	v_mul_f32_e32 v26, 0xbfb8aa3b, v26
	v_mul_f32_e32 v27, 0xbfb8aa3b, v27
	v_mul_f32_e32 v8, 0xbfb8aa3b, v8
	v_mul_f32_e32 v9, 0xbfb8aa3b, v9
	v_mul_f32_e32 v10, 0xbfb8aa3b, v10
	v_mul_f32_e32 v11, 0xbfb8aa3b, v11
	v_exp_f32_e32 v2, v2
	v_exp_f32_e32 v3, v3
	v_pk_add_f32 v[124:125], v[124:125], v[140:141]
	v_exp_f32_e32 v90, v90
	v_exp_f32_e32 v91, v91
	v_exp_f32_e32 v74, v74
	v_exp_f32_e32 v75, v75
	v_exp_f32_e32 v56, v56
	v_exp_f32_e32 v57, v57
	v_exp_f32_e32 v58, v58
	v_exp_f32_e32 v59, v59
	v_pk_add_f32 v[52:53], v[52:53], v[128:129]
	v_exp_f32_e32 v40, v40
	v_exp_f32_e32 v41, v41
	v_exp_f32_e32 v42, v42
	v_exp_f32_e32 v43, v43
	v_rcp_f32_e32 v34, v34
	v_rcp_f32_e32 v35, v35
	v_exp_f32_e32 v24, v24
	v_exp_f32_e32 v25, v25
	v_exp_f32_e32 v26, v26
	v_exp_f32_e32 v27, v27
	v_add_f32_e32 v16, 1.0, v16
	v_add_f32_e32 v17, 1.0, v17
	v_exp_f32_e32 v8, v8
	v_exp_f32_e32 v9, v9
	v_exp_f32_e32 v10, v10
	v_exp_f32_e32 v11, v11
	v_pk_mul_f32 v[96:97], v[124:125], v[96:97]
	v_add_f32_e32 v88, 1.0, v88
	v_add_f32_e32 v89, 1.0, v89
	v_add_f32_e32 v72, 1.0, v72
	v_add_f32_e32 v73, 1.0, v73
	v_pk_add_f32 v[54:55], v[54:55], v[130:131]
	v_pk_mul_f32 v[52:53], v[52:53], v[48:49]
	v_rcp_f32_e32 v16, v16
	v_rcp_f32_e32 v17, v17
	v_add_f32_e32 v18, 1.0, v18
	v_add_f32_e32 v19, 1.0, v19
	v_pk_mul_f32 v[106:107], v[112:113], v[106:107]
	v_pk_mul_f32 v[112:113], v[114:115], v[116:117]
	v_pk_mul_f32 v[114:115], v[104:105], v[122:123]
	v_cvt_pk_bf16_f32 v104, v96, v97
	v_add_f32_e32 v96, 1.0, v163
	v_add_f32_e32 v97, 1.0, v172
	v_rcp_f32_e32 v88, v88
	v_rcp_f32_e32 v89, v89
	v_add_f32_e32 v80, 1.0, v80
	v_add_f32_e32 v81, 1.0, v81
	v_rcp_f32_e32 v72, v72
	v_rcp_f32_e32 v73, v73
	v_add_f32_e32 v64, 1.0, v64
	v_add_f32_e32 v65, 1.0, v65
	v_pk_mul_f32 v[54:55], v[54:55], v[50:51]
	v_cvt_pk_bf16_f32 v50, v52, v53
	v_add_co_u32_e32 v52, vcc, s59, v160
	v_pk_add_f32 v[36:37], v[36:37], v[128:129]
	v_rcp_f32_e32 v18, v18
	v_rcp_f32_e32 v19, v19
	v_add_f32_e32 v0, 1.0, v0
	v_add_f32_e32 v1, 1.0, v1
	v_rcp_f32_e32 v96, v96
	v_rcp_f32_e32 v97, v97
	v_add_f32_e32 v98, 1.0, v98
	v_add_f32_e32 v99, 1.0, v99
	v_rcp_f32_e32 v80, v80
	v_rcp_f32_e32 v81, v81
	v_add_f32_e32 v82, 1.0, v82
	v_add_f32_e32 v83, 1.0, v83
	v_rcp_f32_e32 v64, v64
	v_rcp_f32_e32 v65, v65
	v_add_f32_e32 v66, 1.0, v66
	v_add_f32_e32 v67, 1.0, v67
	v_addc_co_u32_e32 v53, vcc, 0, v161, vcc
	v_pk_add_f32 v[38:39], v[38:39], v[130:131]
	v_pk_mul_f32 v[36:37], v[36:37], v[32:33]
	v_rcp_f32_e32 v0, v0
	v_rcp_f32_e32 v1, v1
	v_add_f32_e32 v2, 1.0, v2
	v_add_f32_e32 v3, 1.0, v3
	v_pk_mul_f32 v[108:109], v[108:109], v[118:119]
	v_rcp_f32_e32 v98, v98
	v_rcp_f32_e32 v99, v99
	v_add_f32_e32 v90, 1.0, v90
	v_add_f32_e32 v91, 1.0, v91
	v_rcp_f32_e32 v82, v82
	v_rcp_f32_e32 v83, v83
	v_add_f32_e32 v74, 1.0, v74
	v_add_f32_e32 v75, 1.0, v75
	v_rcp_f32_e32 v66, v66
	v_rcp_f32_e32 v67, v67
	v_add_f32_e32 v56, 1.0, v56
	v_add_f32_e32 v57, 1.0, v57
	v_add_f32_e32 v58, 1.0, v58
	v_add_f32_e32 v59, 1.0, v59
	v_add_f32_e32 v40, 1.0, v40
	v_add_f32_e32 v41, 1.0, v41
	v_add_f32_e32 v42, 1.0, v42
	v_add_f32_e32 v43, 1.0, v43
	v_pk_mul_f32 v[38:39], v[38:39], v[34:35]
	v_cvt_pk_bf16_f32 v34, v36, v37
	v_add_co_u32_e32 v36, vcc, s60, v160
	v_add_f32_e32 v24, 1.0, v24
	v_add_f32_e32 v25, 1.0, v25
	v_add_f32_e32 v26, 1.0, v26
	v_add_f32_e32 v27, 1.0, v27
	v_pk_add_f32 v[20:21], v[20:21], v[128:129]
	v_add_f32_e32 v8, 1.0, v8
	v_add_f32_e32 v9, 1.0, v9
	v_add_f32_e32 v10, 1.0, v10
	v_add_f32_e32 v11, 1.0, v11
	v_rcp_f32_e32 v2, v2
	v_rcp_f32_e32 v3, v3
	v_cvt_pk_bf16_f32 v105, v106, v107
	v_cvt_pk_bf16_f32 v106, v112, v113
	v_cvt_pk_bf16_f32 v107, v108, v109
	v_pk_add_f32 v[92:93], v[92:93], v[140:141]
	v_rcp_f32_e32 v90, v90
	v_rcp_f32_e32 v91, v91
	v_pk_add_f32 v[76:77], v[76:77], v[140:141]
	v_rcp_f32_e32 v74, v74
	v_rcp_f32_e32 v75, v75
	v_rcp_f32_e32 v56, v56
	v_rcp_f32_e32 v57, v57
	v_rcp_f32_e32 v58, v58
	v_rcp_f32_e32 v59, v59
	v_rcp_f32_e32 v40, v40
	v_rcp_f32_e32 v41, v41
	v_rcp_f32_e32 v42, v42
	v_rcp_f32_e32 v43, v43
	v_addc_co_u32_e32 v37, vcc, 0, v161, vcc
	v_rcp_f32_e32 v24, v24
	v_rcp_f32_e32 v25, v25
	v_rcp_f32_e32 v26, v26
	v_rcp_f32_e32 v27, v27
	v_pk_add_f32 v[22:23], v[22:23], v[130:131]
	v_pk_mul_f32 v[20:21], v[20:21], v[16:17]
	v_rcp_f32_e32 v8, v8
	v_rcp_f32_e32 v9, v9
	v_rcp_f32_e32 v10, v10
	v_rcp_f32_e32 v11, v11
	global_store_dwordx4 v[160:161], v[104:107], off
	v_pk_add_f32 v[100:101], v[100:101], v[128:129]
	v_pk_mul_f32 v[88:89], v[92:93], v[88:89]
	v_or_b32_e32 v104, 16, v162
	v_pk_add_f32 v[84:85], v[84:85], v[128:129]
	v_or_b32_e32 v92, 32, v162
	v_pk_mul_f32 v[72:73], v[76:77], v[72:73]
	v_pk_add_f32 v[68:69], v[68:69], v[128:129]
	v_or_b32_e32 v76, 48, v162
	v_pk_mul_f32 v[22:23], v[22:23], v[18:19]
	v_cvt_pk_bf16_f32 v18, v20, v21
	v_add_co_u32_e32 v20, vcc, s61, v160
	v_pk_add_f32 v[4:5], v[4:5], v[128:129]
	v_pk_add_f32 v[102:103], v[102:103], v[130:131]
	v_pk_mul_f32 v[100:101], v[100:101], v[96:97]
	v_ashrrev_i32_e32 v105, 31, v104
	v_pk_add_f32 v[86:87], v[86:87], v[130:131]
	v_pk_mul_f32 v[84:85], v[84:85], v[80:81]
	v_ashrrev_i32_e32 v93, 31, v92
	v_pk_add_f32 v[70:71], v[70:71], v[130:131]
	v_pk_mul_f32 v[68:69], v[68:69], v[64:65]
	v_ashrrev_i32_e32 v77, 31, v76
	v_addc_co_u32_e32 v21, vcc, 0, v161, vcc
	v_pk_add_f32 v[6:7], v[6:7], v[130:131]
	v_pk_mul_f32 v[4:5], v[4:5], v[0:1]
	v_pk_mul_f32 v[102:103], v[102:103], v[98:99]
	v_cvt_pk_bf16_f32 v98, v100, v101
	v_lshlrev_b64 v[100:101], 12, v[104:105]
	v_pk_add_f32 v[94:95], v[94:95], v[142:143]
	v_pk_mul_f32 v[86:87], v[86:87], v[82:83]
	v_cvt_pk_bf16_f32 v82, v84, v85
	v_lshlrev_b64 v[84:85], 12, v[92:93]
	v_pk_add_f32 v[78:79], v[78:79], v[142:143]
	v_pk_mul_f32 v[70:71], v[70:71], v[66:67]
	v_cvt_pk_bf16_f32 v66, v68, v69
	v_lshlrev_b64 v[68:69], 12, v[76:77]
	v_pk_add_f32 v[62:63], v[62:63], v[142:143]
	v_pk_add_f32 v[60:61], v[60:61], v[140:141]
	v_pk_add_f32 v[46:47], v[46:47], v[142:143]
	v_pk_add_f32 v[44:45], v[44:45], v[140:141]
	v_pk_add_f32 v[30:31], v[30:31], v[142:143]
	v_pk_add_f32 v[28:29], v[28:29], v[140:141]
	v_pk_add_f32 v[14:15], v[14:15], v[142:143]
	v_pk_add_f32 v[12:13], v[12:13], v[140:141]
	v_pk_mul_f32 v[6:7], v[6:7], v[2:3]
	v_cvt_pk_bf16_f32 v2, v4, v5
	v_add_co_u32_e32 v4, vcc, 0xb0000, v160
	v_pk_mul_f32 v[110:111], v[110:111], v[120:121]
	v_lshl_add_u64 v[100:101], s[6:7], 0, v[100:101]
	v_pk_mul_f32 v[90:91], v[94:95], v[90:91]
	v_lshl_add_u64 v[84:85], s[6:7], 0, v[84:85]
	v_pk_mul_f32 v[74:75], v[78:79], v[74:75]
	v_lshl_add_u64 v[68:69], s[6:7], 0, v[68:69]
	v_pk_mul_f32 v[56:57], v[60:61], v[56:57]
	v_pk_mul_f32 v[58:59], v[62:63], v[58:59]
	v_pk_mul_f32 v[40:41], v[44:45], v[40:41]
	v_pk_mul_f32 v[42:43], v[46:47], v[42:43]
	v_pk_mul_f32 v[24:25], v[28:29], v[24:25]
	v_pk_mul_f32 v[26:27], v[30:31], v[26:27]
	v_pk_mul_f32 v[8:9], v[12:13], v[8:9]
	v_pk_mul_f32 v[10:11], v[14:15], v[10:11]
	v_addc_co_u32_e32 v5, vcc, 0, v161, vcc
	v_cvt_pk_bf16_f32 v96, v110, v111
	v_cvt_pk_bf16_f32 v97, v114, v115
	v_cvt_pk_bf16_f32 v99, v102, v103
	v_lshl_add_u64 v[100:101], v[100:101], 0, v[164:165]
	v_cvt_pk_bf16_f32 v80, v88, v89
	v_cvt_pk_bf16_f32 v81, v90, v91
	v_cvt_pk_bf16_f32 v83, v86, v87
	v_lshl_add_u64 v[84:85], v[84:85], 0, v[164:165]
	v_cvt_pk_bf16_f32 v64, v72, v73
	v_cvt_pk_bf16_f32 v65, v74, v75
	v_cvt_pk_bf16_f32 v67, v70, v71
	v_lshl_add_u64 v[68:69], v[68:69], 0, v[164:165]
	v_cvt_pk_bf16_f32 v48, v56, v57
	v_cvt_pk_bf16_f32 v49, v58, v59
	v_cvt_pk_bf16_f32 v51, v54, v55
	v_cvt_pk_bf16_f32 v32, v40, v41
	v_cvt_pk_bf16_f32 v33, v42, v43
	v_cvt_pk_bf16_f32 v35, v38, v39
	v_cvt_pk_bf16_f32 v16, v24, v25
	v_cvt_pk_bf16_f32 v17, v26, v27
	v_cvt_pk_bf16_f32 v19, v22, v23
	v_cvt_pk_bf16_f32 v0, v8, v9
	v_cvt_pk_bf16_f32 v1, v10, v11
	v_cvt_pk_bf16_f32 v3, v6, v7
	s_and_b64 vcc, exec, s[16:17]
	global_store_dwordx4 v[100:101], v[96:99], off
	global_store_dwordx4 v[84:85], v[80:83], off
	global_store_dwordx4 v[68:69], v[64:67], off
	global_store_dwordx4 v[52:53], v[48:51], off
	global_store_dwordx4 v[36:37], v[32:35], off
	global_store_dwordx4 v[20:21], v[16:19], off
	global_store_dwordx4 v[4:5], v[0:3], off
	s_cbranch_vccz .LBB0_923
	s_branch .LBB0_935

.LBB0_1073:
	s_ashr_i32 s31, s30, 31
	s_xor_b64 s[34:35], s[28:29], -1
	s_lshl_b64 s[36:37], s[30:31], 20
	s_add_u32 s36, s48, s36
	s_addc_u32 s37, s49, s37
	s_and_b64 s[38:39], s[28:29], exec
	s_cselect_b32 s31, s37, s43
	s_cselect_b32 s68, s36, s42
	s_ashr_i32 s19, s18, 31
	s_lshl_b64 s[38:39], s[18:19], 20
	s_add_u32 s38, s50, s38
	s_addc_u32 s39, s51, s39
	s_and_b64 s[28:29], s[28:29], exec
	s_cselect_b32 s19, s39, s45
	s_cselect_b32 s28, s38, s44
	s_add_u32 s42, s42, 0x80080
	s_addc_u32 s43, s43, 0
	s_add_u32 s29, s44, 0x100
	s_addc_u32 s69, s45, 0
	s_mov_b32 s70, -2
	v_add_u32_e32 v244, 0x18000, v163
	v_add_u32_e32 v245, 0x1c000, v163
	ds_read_b128 v[128:131], v165
	ds_read_b128 v[132:135], v165 offset:1024
	ds_read_b128 v[136:139], v165 offset:2048
	ds_read_b128 v[140:143], v165 offset:3072
	s_add_u32 s44, s42, 0xfff80080
	s_addc_u32 s45, s43, -1
	s_cmp_eq_u32 s70, 28
	s_cselect_b32 s47, s31, s45
	s_cselect_b32 s46, s68, s44
	s_cselect_b32 s45, s19, s69
	s_cselect_b32 s44, s28, s29
	s_add_i32 m0, s41, 0xc000
	ds_read_b128 v[156:159], v166
	ds_read_b128 v[168:171], v166 offset:1024
	ds_read_b128 v[172:175], v166 offset:2048
	ds_read_b128 v[176:179], v166 offset:3072
	ds_read_b128 v[180:183], v166 offset:4096
	ds_read_b128 v[184:187], v166 offset:5120
	ds_read_b128 v[188:191], v166 offset:6144
	ds_read_b128 v[192:195], v166 offset:7168
	global_load_lds_dwordx4 v150, s[42:43]
	s_add_i32 m0, s41, 0xe000
	s_nop 0
	global_load_lds_dwordx4 v152, s[42:43]
	s_waitcnt lgkmcnt(8)
	s_barrier
	s_waitcnt lgkmcnt(0)
	v_mfma_f32_16x16x32_bf16 v[124:127], v[128:131], v[156:159], 0
	v_mfma_f32_16x16x32_bf16 v[120:123], v[136:139], v[156:159], 0
	v_mfma_f32_16x16x32_bf16 v[112:115], v[128:131], v[172:175], 0
	v_mfma_f32_16x16x32_bf16 v[104:107], v[136:139], v[172:175], 0
	v_mfma_f32_16x16x32_bf16 v[96:99], v[128:131], v[180:183], 0
	v_mfma_f32_16x16x32_bf16 v[88:91], v[136:139], v[180:183], 0
	v_mfma_f32_16x16x32_bf16 v[80:83], v[128:131], v[188:191], 0
	v_mfma_f32_16x16x32_bf16 v[72:75], v[136:139], v[188:191], 0
	v_mfma_f32_16x16x32_bf16 v[124:127], v[132:135], v[168:171], v[124:127]
	v_mfma_f32_16x16x32_bf16 v[120:123], v[140:143], v[168:171], v[120:123]
	v_mfma_f32_16x16x32_bf16 v[112:115], v[132:135], v[176:179], v[112:115]
	v_mfma_f32_16x16x32_bf16 v[104:107], v[140:143], v[176:179], v[104:107]
	v_mfma_f32_16x16x32_bf16 v[96:99], v[132:135], v[184:187], v[96:99]
	v_mfma_f32_16x16x32_bf16 v[88:91], v[140:143], v[184:187], v[88:91]
	v_mfma_f32_16x16x32_bf16 v[80:83], v[132:135], v[192:195], v[80:83]
	v_mfma_f32_16x16x32_bf16 v[72:75], v[140:143], v[192:195], v[72:75]
	s_barrier
	s_add_i32 s71, s65, s54
	s_add_u32 s98, s44, s8
	s_addc_u32 s99, s45, s9
	s_mov_b32 m0, s71
	ds_read_b128 v[196:199], v167
	ds_read_b128 v[200:203], v167 offset:1024
	ds_read_b128 v[204:207], v167 offset:2048
	ds_read_b128 v[208:211], v167 offset:3072
	global_load_lds_dwordx4 v146, s[44:45]
	s_add_i32 m0, s71, 0x2000
	s_nop 0
	global_load_lds_dwordx4 v148, s[44:45]
	s_barrier
	s_waitcnt lgkmcnt(0)
	v_mfma_f32_16x16x32_bf16 v[116:119], v[196:199], v[156:159], 0
	v_mfma_f32_16x16x32_bf16 v[108:111], v[204:207], v[156:159], 0
	v_mfma_f32_16x16x32_bf16 v[100:103], v[196:199], v[172:175], 0
	v_mfma_f32_16x16x32_bf16 v[92:95], v[204:207], v[172:175], 0
	v_mfma_f32_16x16x32_bf16 v[84:87], v[196:199], v[180:183], 0
	v_mfma_f32_16x16x32_bf16 v[76:79], v[204:207], v[180:183], 0
	v_mfma_f32_16x16x32_bf16 v[68:71], v[196:199], v[188:191], 0
	v_mfma_f32_16x16x32_bf16 v[64:67], v[204:207], v[188:191], 0
	v_mfma_f32_16x16x32_bf16 v[116:119], v[200:203], v[168:171], v[116:119]
	v_mfma_f32_16x16x32_bf16 v[108:111], v[208:211], v[168:171], v[108:111]
	v_mfma_f32_16x16x32_bf16 v[100:103], v[200:203], v[176:179], v[100:103]
	v_mfma_f32_16x16x32_bf16 v[92:95], v[208:211], v[176:179], v[92:95]
	v_mfma_f32_16x16x32_bf16 v[84:87], v[200:203], v[184:187], v[84:87]
	v_mfma_f32_16x16x32_bf16 v[76:79], v[208:211], v[184:187], v[76:79]
	v_mfma_f32_16x16x32_bf16 v[68:71], v[200:203], v[192:195], v[68:71]
	v_mfma_f32_16x16x32_bf16 v[64:67], v[208:211], v[192:195], v[64:67]
	s_mov_b32 m0, s41
	s_add_u32 s100, s46, s8
	s_addc_u32 s101, s47, s9
	s_barrier
	ds_read_b128 v[156:159], v166 offset:16384
	ds_read_b128 v[168:171], v166 offset:17408
	ds_read_b128 v[172:175], v166 offset:18432
	ds_read_b128 v[176:179], v166 offset:19456
	ds_read_b128 v[180:183], v166 offset:20480
	ds_read_b128 v[184:187], v166 offset:21504
	ds_read_b128 v[188:191], v166 offset:22528
	ds_read_b128 v[192:195], v166 offset:23552
	global_load_lds_dwordx4 v146, s[46:47]
	s_mov_b32 m0, s55
	s_nop 0
	global_load_lds_dwordx4 v148, s[46:47]
	s_barrier
	s_waitcnt lgkmcnt(0)
	v_mfma_f32_16x16x32_bf16 v[60:63], v[128:131], v[156:159], 0
	v_mfma_f32_16x16x32_bf16 v[56:59], v[136:139], v[156:159], 0
	v_mfma_f32_16x16x32_bf16 v[48:51], v[128:131], v[172:175], 0
	v_mfma_f32_16x16x32_bf16 v[40:43], v[136:139], v[172:175], 0
	v_mfma_f32_16x16x32_bf16 v[32:35], v[128:131], v[180:183], 0
	v_mfma_f32_16x16x32_bf16 v[24:27], v[136:139], v[180:183], 0
	v_mfma_f32_16x16x32_bf16 v[16:19], v[128:131], v[188:191], 0
	v_mfma_f32_16x16x32_bf16 v[8:11], v[136:139], v[188:191], 0
	v_mfma_f32_16x16x32_bf16 v[60:63], v[132:135], v[168:171], v[60:63]
	v_mfma_f32_16x16x32_bf16 v[56:59], v[140:143], v[168:171], v[56:59]
	v_mfma_f32_16x16x32_bf16 v[48:51], v[132:135], v[176:179], v[48:51]
	v_mfma_f32_16x16x32_bf16 v[40:43], v[140:143], v[176:179], v[40:43]
	v_mfma_f32_16x16x32_bf16 v[32:35], v[132:135], v[184:187], v[32:35]
	v_mfma_f32_16x16x32_bf16 v[24:27], v[140:143], v[184:187], v[24:27]
	v_mfma_f32_16x16x32_bf16 v[16:19], v[132:135], v[192:195], v[16:19]
	v_mfma_f32_16x16x32_bf16 v[8:11], v[140:143], v[192:195], v[8:11]
	s_barrier
	s_add_u32 s72, s44, 0x80000
	s_addc_u32 s73, s45, 0
	s_add_i32 s71, s66, s54
	s_mov_b32 m0, s71
	s_nop 0
	global_load_lds_dwordx4 v146, s[72:73]
	s_add_i32 m0, s71, 0x2000
	s_nop 0
	global_load_lds_dwordx4 v148, s[72:73]
	s_waitcnt vmcnt(6)
	s_barrier
	v_mfma_f32_16x16x32_bf16 v[52:55], v[196:199], v[156:159], 0
	v_mfma_f32_16x16x32_bf16 v[44:47], v[204:207], v[156:159], 0
	v_mfma_f32_16x16x32_bf16 v[36:39], v[196:199], v[172:175], 0
	v_mfma_f32_16x16x32_bf16 v[28:31], v[204:207], v[172:175], 0
	v_mfma_f32_16x16x32_bf16 v[20:23], v[196:199], v[180:183], 0
	v_mfma_f32_16x16x32_bf16 v[12:15], v[204:207], v[180:183], 0
	v_mfma_f32_16x16x32_bf16 v[4:7], v[196:199], v[188:191], 0
	v_mfma_f32_16x16x32_bf16 v[0:3], v[204:207], v[188:191], 0
	v_mfma_f32_16x16x32_bf16 v[52:55], v[200:203], v[168:171], v[52:55]
	v_mfma_f32_16x16x32_bf16 v[44:47], v[208:211], v[168:171], v[44:47]
	v_mfma_f32_16x16x32_bf16 v[36:39], v[200:203], v[176:179], v[36:39]
	v_mfma_f32_16x16x32_bf16 v[28:31], v[208:211], v[176:179], v[28:31]
	v_mfma_f32_16x16x32_bf16 v[20:23], v[200:203], v[184:187], v[20:23]
	v_mfma_f32_16x16x32_bf16 v[12:15], v[208:211], v[184:187], v[12:15]
	v_mfma_f32_16x16x32_bf16 v[4:7], v[200:203], v[192:195], v[4:7]
	v_mfma_f32_16x16x32_bf16 v[0:3], v[208:211], v[192:195], v[0:3]
	s_add_i32 s71, 0, 0x18000
	s_barrier
	ds_read_b128 v[128:131], v244
	ds_read_b128 v[132:135], v244 offset:1024
	ds_read_b128 v[136:139], v244 offset:2048
	ds_read_b128 v[140:143], v244 offset:3072
	s_add_u32 s46, s46, 0x80000
	s_addc_u32 s47, s47, 0
	s_mov_b32 m0, s56
	ds_read_b128 v[156:159], v166 offset:32768
	ds_read_b128 v[168:171], v166 offset:33792
	ds_read_b128 v[172:175], v166 offset:34816
	ds_read_b128 v[176:179], v166 offset:35840
	ds_read_b128 v[180:183], v166 offset:36864
	ds_read_b128 v[184:187], v166 offset:37888
	ds_read_b128 v[188:191], v166 offset:38912
	ds_read_b128 v[192:195], v166 offset:39936
	global_load_lds_dwordx4 v146, s[46:47]
	s_mov_b32 m0, s57
	s_nop 0
	global_load_lds_dwordx4 v148, s[46:47]
	s_waitcnt lgkmcnt(8)
	s_barrier
	s_waitcnt lgkmcnt(0)
	v_mfma_f32_16x16x32_bf16 v[124:127], v[128:131], v[156:159], v[124:127]
	v_mfma_f32_16x16x32_bf16 v[120:123], v[136:139], v[156:159], v[120:123]
	v_mfma_f32_16x16x32_bf16 v[112:115], v[128:131], v[172:175], v[112:115]
	v_mfma_f32_16x16x32_bf16 v[104:107], v[136:139], v[172:175], v[104:107]
	v_mfma_f32_16x16x32_bf16 v[96:99], v[128:131], v[180:183], v[96:99]
	v_mfma_f32_16x16x32_bf16 v[88:91], v[136:139], v[180:183], v[88:91]
	v_mfma_f32_16x16x32_bf16 v[80:83], v[128:131], v[188:191], v[80:83]
	v_mfma_f32_16x16x32_bf16 v[72:75], v[136:139], v[188:191], v[72:75]
	v_mfma_f32_16x16x32_bf16 v[124:127], v[132:135], v[168:171], v[124:127]
	v_mfma_f32_16x16x32_bf16 v[120:123], v[140:143], v[168:171], v[120:123]
	v_mfma_f32_16x16x32_bf16 v[112:115], v[132:135], v[176:179], v[112:115]
	v_mfma_f32_16x16x32_bf16 v[104:107], v[140:143], v[176:179], v[104:107]
	v_mfma_f32_16x16x32_bf16 v[96:99], v[132:135], v[184:187], v[96:99]
	v_mfma_f32_16x16x32_bf16 v[88:91], v[140:143], v[184:187], v[88:91]
	v_mfma_f32_16x16x32_bf16 v[80:83], v[132:135], v[192:195], v[80:83]
	v_mfma_f32_16x16x32_bf16 v[72:75], v[140:143], v[192:195], v[72:75]
	s_barrier
	s_add_i32 s46, 0, 0x1c000
	s_add_i32 s47, s71, s54
	s_mov_b32 m0, s47
	ds_read_b128 v[196:199], v245
	ds_read_b128 v[200:203], v245 offset:1024
	ds_read_b128 v[204:207], v245 offset:2048
	ds_read_b128 v[208:211], v245 offset:3072
	global_load_lds_dwordx4 v146, s[98:99]
	s_add_i32 m0, s47, 0x2000
	s_nop 0
	global_load_lds_dwordx4 v148, s[98:99]
	s_barrier
	s_waitcnt lgkmcnt(0)
	v_mfma_f32_16x16x32_bf16 v[116:119], v[196:199], v[156:159], v[116:119]
	v_mfma_f32_16x16x32_bf16 v[108:111], v[204:207], v[156:159], v[108:111]
	v_mfma_f32_16x16x32_bf16 v[100:103], v[196:199], v[172:175], v[100:103]
	v_mfma_f32_16x16x32_bf16 v[92:95], v[204:207], v[172:175], v[92:95]
	v_mfma_f32_16x16x32_bf16 v[84:87], v[196:199], v[180:183], v[84:87]
	v_mfma_f32_16x16x32_bf16 v[76:79], v[204:207], v[180:183], v[76:79]
	v_mfma_f32_16x16x32_bf16 v[68:71], v[196:199], v[188:191], v[68:71]
	v_mfma_f32_16x16x32_bf16 v[64:67], v[204:207], v[188:191], v[64:67]
	v_mfma_f32_16x16x32_bf16 v[116:119], v[200:203], v[168:171], v[116:119]
	v_mfma_f32_16x16x32_bf16 v[108:111], v[208:211], v[168:171], v[108:111]
	v_mfma_f32_16x16x32_bf16 v[100:103], v[200:203], v[176:179], v[100:103]
	v_mfma_f32_16x16x32_bf16 v[92:95], v[208:211], v[176:179], v[92:95]
	v_mfma_f32_16x16x32_bf16 v[84:87], v[200:203], v[184:187], v[84:87]
	v_mfma_f32_16x16x32_bf16 v[76:79], v[208:211], v[184:187], v[76:79]
	v_mfma_f32_16x16x32_bf16 v[68:71], v[200:203], v[192:195], v[68:71]
	v_mfma_f32_16x16x32_bf16 v[64:67], v[208:211], v[192:195], v[64:67]
	s_mov_b32 m0, s61
	s_barrier
	ds_read_b128 v[156:159], v166 offset:49152
	ds_read_b128 v[168:171], v166 offset:50176
	ds_read_b128 v[172:175], v166 offset:51200
	ds_read_b128 v[176:179], v166 offset:52224
	ds_read_b128 v[180:183], v166 offset:53248
	ds_read_b128 v[184:187], v166 offset:54272
	ds_read_b128 v[188:191], v166 offset:55296
	ds_read_b128 v[192:195], v166 offset:56320
	global_load_lds_dwordx4 v146, s[100:101]
	s_mov_b32 m0, s62
	s_nop 0
	global_load_lds_dwordx4 v148, s[100:101]
	s_barrier
	s_waitcnt lgkmcnt(0)
	v_mfma_f32_16x16x32_bf16 v[60:63], v[128:131], v[156:159], v[60:63]
	v_mfma_f32_16x16x32_bf16 v[56:59], v[136:139], v[156:159], v[56:59]
	v_mfma_f32_16x16x32_bf16 v[48:51], v[128:131], v[172:175], v[48:51]
	v_mfma_f32_16x16x32_bf16 v[40:43], v[136:139], v[172:175], v[40:43]
	v_mfma_f32_16x16x32_bf16 v[32:35], v[128:131], v[180:183], v[32:35]
	v_mfma_f32_16x16x32_bf16 v[24:27], v[136:139], v[180:183], v[24:27]
	v_mfma_f32_16x16x32_bf16 v[16:19], v[128:131], v[188:191], v[16:19]
	v_mfma_f32_16x16x32_bf16 v[8:11], v[136:139], v[188:191], v[8:11]
	v_mfma_f32_16x16x32_bf16 v[60:63], v[132:135], v[168:171], v[60:63]
	v_mfma_f32_16x16x32_bf16 v[56:59], v[140:143], v[168:171], v[56:59]
	v_mfma_f32_16x16x32_bf16 v[48:51], v[132:135], v[176:179], v[48:51]
	v_mfma_f32_16x16x32_bf16 v[40:43], v[140:143], v[176:179], v[40:43]
	v_mfma_f32_16x16x32_bf16 v[32:35], v[132:135], v[184:187], v[32:35]
	v_mfma_f32_16x16x32_bf16 v[24:27], v[140:143], v[184:187], v[24:27]
	v_mfma_f32_16x16x32_bf16 v[16:19], v[132:135], v[192:195], v[16:19]
	v_mfma_f32_16x16x32_bf16 v[8:11], v[140:143], v[192:195], v[8:11]
	s_barrier
	s_add_u32 s44, s44, 0x80080
	s_addc_u32 s45, s45, 0
	s_add_i32 s46, s46, s54
	s_mov_b32 m0, s46
	s_nop 0
	global_load_lds_dwordx4 v146, s[44:45]
	s_add_i32 m0, s46, 0x2000
	s_nop 0
	global_load_lds_dwordx4 v148, s[44:45]
	s_waitcnt vmcnt(6)
	s_barrier
	v_mfma_f32_16x16x32_bf16 v[52:55], v[196:199], v[156:159], v[52:55]
	v_mfma_f32_16x16x32_bf16 v[44:47], v[204:207], v[156:159], v[44:47]
	v_mfma_f32_16x16x32_bf16 v[36:39], v[196:199], v[172:175], v[36:39]
	v_mfma_f32_16x16x32_bf16 v[28:31], v[204:207], v[172:175], v[28:31]
	v_mfma_f32_16x16x32_bf16 v[20:23], v[196:199], v[180:183], v[20:23]
	v_mfma_f32_16x16x32_bf16 v[12:15], v[204:207], v[180:183], v[12:15]
	v_mfma_f32_16x16x32_bf16 v[4:7], v[196:199], v[188:191], v[4:7]
	v_mfma_f32_16x16x32_bf16 v[0:3], v[204:207], v[188:191], v[0:3]
	v_mfma_f32_16x16x32_bf16 v[52:55], v[200:203], v[168:171], v[52:55]
	v_mfma_f32_16x16x32_bf16 v[44:47], v[208:211], v[168:171], v[44:47]
	v_mfma_f32_16x16x32_bf16 v[36:39], v[200:203], v[176:179], v[36:39]
	v_mfma_f32_16x16x32_bf16 v[28:31], v[208:211], v[176:179], v[28:31]
	v_mfma_f32_16x16x32_bf16 v[20:23], v[200:203], v[184:187], v[20:23]
	v_mfma_f32_16x16x32_bf16 v[12:15], v[208:211], v[184:187], v[12:15]
	v_mfma_f32_16x16x32_bf16 v[4:7], v[200:203], v[192:195], v[4:7]
	v_mfma_f32_16x16x32_bf16 v[0:3], v[208:211], v[192:195], v[0:3]
	s_add_i32 s70, s70, 2
	s_add_u32 s42, s42, 0x100
	s_addc_u32 s43, s43, 0
	s_add_u32 s29, s29, 0x100
	s_addc_u32 s69, s69, 0
	s_cmp_gt_u32 s70, 29
	s_barrier
	s_cbranch_scc0 .LBB0_1074
.LBB0_1074:
	ds_read_b128 v[128:131], v165
	ds_read_b128 v[132:135], v165 offset:1024
	ds_read_b128 v[136:139], v165 offset:2048
	ds_read_b128 v[140:143], v165 offset:3072
	s_add_u32 s44, s42, 0xfff80080
	s_addc_u32 s45, s43, -1
	s_cmp_eq_u32 s70, 28
	s_cselect_b32 s47, s31, s45
	s_cselect_b32 s46, s68, s44
	s_cselect_b32 s45, s19, s69
	s_cselect_b32 s44, s28, s29
	s_add_i32 m0, s41, 0xc000
	ds_read_b128 v[156:159], v166
	ds_read_b128 v[168:171], v166 offset:1024
	ds_read_b128 v[172:175], v166 offset:2048
	ds_read_b128 v[176:179], v166 offset:3072
	ds_read_b128 v[180:183], v166 offset:4096
	ds_read_b128 v[184:187], v166 offset:5120
	ds_read_b128 v[188:191], v166 offset:6144
	ds_read_b128 v[192:195], v166 offset:7168
	global_load_lds_dwordx4 v150, s[42:43]
	s_add_i32 m0, s41, 0xe000
	s_nop 0
	global_load_lds_dwordx4 v152, s[42:43]
	s_waitcnt lgkmcnt(8)
	s_barrier
	s_waitcnt lgkmcnt(0)
	v_mfma_f32_16x16x32_bf16 v[124:127], v[128:131], v[156:159], v[124:127]
	v_mfma_f32_16x16x32_bf16 v[120:123], v[136:139], v[156:159], v[120:123]
	v_mfma_f32_16x16x32_bf16 v[112:115], v[128:131], v[172:175], v[112:115]
	v_mfma_f32_16x16x32_bf16 v[104:107], v[136:139], v[172:175], v[104:107]
	v_mfma_f32_16x16x32_bf16 v[96:99], v[128:131], v[180:183], v[96:99]
	v_mfma_f32_16x16x32_bf16 v[88:91], v[136:139], v[180:183], v[88:91]
	v_mfma_f32_16x16x32_bf16 v[80:83], v[128:131], v[188:191], v[80:83]
	v_mfma_f32_16x16x32_bf16 v[72:75], v[136:139], v[188:191], v[72:75]
	v_mfma_f32_16x16x32_bf16 v[124:127], v[132:135], v[168:171], v[124:127]
	v_mfma_f32_16x16x32_bf16 v[120:123], v[140:143], v[168:171], v[120:123]
	v_mfma_f32_16x16x32_bf16 v[112:115], v[132:135], v[176:179], v[112:115]
	v_mfma_f32_16x16x32_bf16 v[104:107], v[140:143], v[176:179], v[104:107]
	v_mfma_f32_16x16x32_bf16 v[96:99], v[132:135], v[184:187], v[96:99]
	v_mfma_f32_16x16x32_bf16 v[88:91], v[140:143], v[184:187], v[88:91]
	v_mfma_f32_16x16x32_bf16 v[80:83], v[132:135], v[192:195], v[80:83]
	v_mfma_f32_16x16x32_bf16 v[72:75], v[140:143], v[192:195], v[72:75]
	s_barrier
	s_add_i32 s71, s65, s54
	s_add_u32 s98, s44, s8
	s_addc_u32 s99, s45, s9
	s_mov_b32 m0, s71
	ds_read_b128 v[196:199], v167
	ds_read_b128 v[200:203], v167 offset:1024
	ds_read_b128 v[204:207], v167 offset:2048
	ds_read_b128 v[208:211], v167 offset:3072
	global_load_lds_dwordx4 v146, s[44:45]
	s_add_i32 m0, s71, 0x2000
	s_nop 0
	global_load_lds_dwordx4 v148, s[44:45]
	s_barrier
	s_waitcnt lgkmcnt(0)
	v_mfma_f32_16x16x32_bf16 v[116:119], v[196:199], v[156:159], v[116:119]
	v_mfma_f32_16x16x32_bf16 v[108:111], v[204:207], v[156:159], v[108:111]
	v_mfma_f32_16x16x32_bf16 v[100:103], v[196:199], v[172:175], v[100:103]
	v_mfma_f32_16x16x32_bf16 v[92:95], v[204:207], v[172:175], v[92:95]
	v_mfma_f32_16x16x32_bf16 v[84:87], v[196:199], v[180:183], v[84:87]
	v_mfma_f32_16x16x32_bf16 v[76:79], v[204:207], v[180:183], v[76:79]
	v_mfma_f32_16x16x32_bf16 v[68:71], v[196:199], v[188:191], v[68:71]
	v_mfma_f32_16x16x32_bf16 v[64:67], v[204:207], v[188:191], v[64:67]
	v_mfma_f32_16x16x32_bf16 v[116:119], v[200:203], v[168:171], v[116:119]
	v_mfma_f32_16x16x32_bf16 v[108:111], v[208:211], v[168:171], v[108:111]
	v_mfma_f32_16x16x32_bf16 v[100:103], v[200:203], v[176:179], v[100:103]
	v_mfma_f32_16x16x32_bf16 v[92:95], v[208:211], v[176:179], v[92:95]
	v_mfma_f32_16x16x32_bf16 v[84:87], v[200:203], v[184:187], v[84:87]
	v_mfma_f32_16x16x32_bf16 v[76:79], v[208:211], v[184:187], v[76:79]
	v_mfma_f32_16x16x32_bf16 v[68:71], v[200:203], v[192:195], v[68:71]
	v_mfma_f32_16x16x32_bf16 v[64:67], v[208:211], v[192:195], v[64:67]
	s_mov_b32 m0, s41
	s_add_u32 s100, s46, s8
	s_addc_u32 s101, s47, s9
	s_barrier
	ds_read_b128 v[156:159], v166 offset:16384
	ds_read_b128 v[168:171], v166 offset:17408
	ds_read_b128 v[172:175], v166 offset:18432
	ds_read_b128 v[176:179], v166 offset:19456
	ds_read_b128 v[180:183], v166 offset:20480
	ds_read_b128 v[184:187], v166 offset:21504
	ds_read_b128 v[188:191], v166 offset:22528
	ds_read_b128 v[192:195], v166 offset:23552
	global_load_lds_dwordx4 v146, s[46:47]
	s_mov_b32 m0, s55
	s_nop 0
	global_load_lds_dwordx4 v148, s[46:47]
	s_barrier
	s_waitcnt lgkmcnt(0)
	v_mfma_f32_16x16x32_bf16 v[60:63], v[128:131], v[156:159], v[60:63]
	v_mfma_f32_16x16x32_bf16 v[56:59], v[136:139], v[156:159], v[56:59]
	v_mfma_f32_16x16x32_bf16 v[48:51], v[128:131], v[172:175], v[48:51]
	v_mfma_f32_16x16x32_bf16 v[40:43], v[136:139], v[172:175], v[40:43]
	v_mfma_f32_16x16x32_bf16 v[32:35], v[128:131], v[180:183], v[32:35]
	v_mfma_f32_16x16x32_bf16 v[24:27], v[136:139], v[180:183], v[24:27]
	v_mfma_f32_16x16x32_bf16 v[16:19], v[128:131], v[188:191], v[16:19]
	v_mfma_f32_16x16x32_bf16 v[8:11], v[136:139], v[188:191], v[8:11]
	v_mfma_f32_16x16x32_bf16 v[60:63], v[132:135], v[168:171], v[60:63]
	v_mfma_f32_16x16x32_bf16 v[56:59], v[140:143], v[168:171], v[56:59]
	v_mfma_f32_16x16x32_bf16 v[48:51], v[132:135], v[176:179], v[48:51]
	v_mfma_f32_16x16x32_bf16 v[40:43], v[140:143], v[176:179], v[40:43]
	v_mfma_f32_16x16x32_bf16 v[32:35], v[132:135], v[184:187], v[32:35]
	v_mfma_f32_16x16x32_bf16 v[24:27], v[140:143], v[184:187], v[24:27]
	v_mfma_f32_16x16x32_bf16 v[16:19], v[132:135], v[192:195], v[16:19]
	v_mfma_f32_16x16x32_bf16 v[8:11], v[140:143], v[192:195], v[8:11]
	s_barrier
	s_add_u32 s72, s44, 0x80000
	s_addc_u32 s73, s45, 0
	s_add_i32 s71, s66, s54
	s_mov_b32 m0, s71
	s_nop 0
	global_load_lds_dwordx4 v146, s[72:73]
	s_add_i32 m0, s71, 0x2000
	s_nop 0
	global_load_lds_dwordx4 v148, s[72:73]
	s_waitcnt vmcnt(6)
	s_barrier
	v_mfma_f32_16x16x32_bf16 v[52:55], v[196:199], v[156:159], v[52:55]
	v_mfma_f32_16x16x32_bf16 v[44:47], v[204:207], v[156:159], v[44:47]
	v_mfma_f32_16x16x32_bf16 v[36:39], v[196:199], v[172:175], v[36:39]
	v_mfma_f32_16x16x32_bf16 v[28:31], v[204:207], v[172:175], v[28:31]
	v_mfma_f32_16x16x32_bf16 v[20:23], v[196:199], v[180:183], v[20:23]
	v_mfma_f32_16x16x32_bf16 v[12:15], v[204:207], v[180:183], v[12:15]
	v_mfma_f32_16x16x32_bf16 v[4:7], v[196:199], v[188:191], v[4:7]
	v_mfma_f32_16x16x32_bf16 v[0:3], v[204:207], v[188:191], v[0:3]
	v_mfma_f32_16x16x32_bf16 v[52:55], v[200:203], v[168:171], v[52:55]
	v_mfma_f32_16x16x32_bf16 v[44:47], v[208:211], v[168:171], v[44:47]
	v_mfma_f32_16x16x32_bf16 v[36:39], v[200:203], v[176:179], v[36:39]
	v_mfma_f32_16x16x32_bf16 v[28:31], v[208:211], v[176:179], v[28:31]
	v_mfma_f32_16x16x32_bf16 v[20:23], v[200:203], v[184:187], v[20:23]
	v_mfma_f32_16x16x32_bf16 v[12:15], v[208:211], v[184:187], v[12:15]
	v_mfma_f32_16x16x32_bf16 v[4:7], v[200:203], v[192:195], v[4:7]
	v_mfma_f32_16x16x32_bf16 v[0:3], v[208:211], v[192:195], v[0:3]
	s_add_i32 s71, 0, 0x18000
	s_barrier
	ds_read_b128 v[128:131], v244
	ds_read_b128 v[132:135], v244 offset:1024
	ds_read_b128 v[136:139], v244 offset:2048
	ds_read_b128 v[140:143], v244 offset:3072
	s_add_u32 s46, s46, 0x80000
	s_addc_u32 s47, s47, 0
	s_mov_b32 m0, s56
	ds_read_b128 v[156:159], v166 offset:32768
	ds_read_b128 v[168:171], v166 offset:33792
	ds_read_b128 v[172:175], v166 offset:34816
	ds_read_b128 v[176:179], v166 offset:35840
	ds_read_b128 v[180:183], v166 offset:36864
	ds_read_b128 v[184:187], v166 offset:37888
	ds_read_b128 v[188:191], v166 offset:38912
	ds_read_b128 v[192:195], v166 offset:39936
	global_load_lds_dwordx4 v146, s[46:47]
	s_mov_b32 m0, s57
	s_nop 0
	global_load_lds_dwordx4 v148, s[46:47]
	s_waitcnt lgkmcnt(8)
	s_barrier
	s_waitcnt lgkmcnt(0)
	v_mfma_f32_16x16x32_bf16 v[124:127], v[128:131], v[156:159], v[124:127]
	v_mfma_f32_16x16x32_bf16 v[120:123], v[136:139], v[156:159], v[120:123]
	v_mfma_f32_16x16x32_bf16 v[112:115], v[128:131], v[172:175], v[112:115]
	v_mfma_f32_16x16x32_bf16 v[104:107], v[136:139], v[172:175], v[104:107]
	v_mfma_f32_16x16x32_bf16 v[96:99], v[128:131], v[180:183], v[96:99]
	v_mfma_f32_16x16x32_bf16 v[88:91], v[136:139], v[180:183], v[88:91]
	v_mfma_f32_16x16x32_bf16 v[80:83], v[128:131], v[188:191], v[80:83]
	v_mfma_f32_16x16x32_bf16 v[72:75], v[136:139], v[188:191], v[72:75]
	v_mfma_f32_16x16x32_bf16 v[124:127], v[132:135], v[168:171], v[124:127]
	v_mfma_f32_16x16x32_bf16 v[120:123], v[140:143], v[168:171], v[120:123]
	v_mfma_f32_16x16x32_bf16 v[112:115], v[132:135], v[176:179], v[112:115]
	v_mfma_f32_16x16x32_bf16 v[104:107], v[140:143], v[176:179], v[104:107]
	v_mfma_f32_16x16x32_bf16 v[96:99], v[132:135], v[184:187], v[96:99]
	v_mfma_f32_16x16x32_bf16 v[88:91], v[140:143], v[184:187], v[88:91]
	v_mfma_f32_16x16x32_bf16 v[80:83], v[132:135], v[192:195], v[80:83]
	v_mfma_f32_16x16x32_bf16 v[72:75], v[140:143], v[192:195], v[72:75]
	s_barrier
	s_add_i32 s46, 0, 0x1c000
	s_add_i32 s47, s71, s54
	s_mov_b32 m0, s47
	ds_read_b128 v[196:199], v245
	ds_read_b128 v[200:203], v245 offset:1024
	ds_read_b128 v[204:207], v245 offset:2048
	ds_read_b128 v[208:211], v245 offset:3072
	global_load_lds_dwordx4 v146, s[98:99]
	s_add_i32 m0, s47, 0x2000
	s_nop 0
	global_load_lds_dwordx4 v148, s[98:99]
	s_barrier
	s_waitcnt lgkmcnt(0)
	v_mfma_f32_16x16x32_bf16 v[116:119], v[196:199], v[156:159], v[116:119]
	v_mfma_f32_16x16x32_bf16 v[108:111], v[204:207], v[156:159], v[108:111]
	v_mfma_f32_16x16x32_bf16 v[100:103], v[196:199], v[172:175], v[100:103]
	v_mfma_f32_16x16x32_bf16 v[92:95], v[204:207], v[172:175], v[92:95]
	v_mfma_f32_16x16x32_bf16 v[84:87], v[196:199], v[180:183], v[84:87]
	v_mfma_f32_16x16x32_bf16 v[76:79], v[204:207], v[180:183], v[76:79]
	v_mfma_f32_16x16x32_bf16 v[68:71], v[196:199], v[188:191], v[68:71]
	v_mfma_f32_16x16x32_bf16 v[64:67], v[204:207], v[188:191], v[64:67]
	v_mfma_f32_16x16x32_bf16 v[116:119], v[200:203], v[168:171], v[116:119]
	v_mfma_f32_16x16x32_bf16 v[108:111], v[208:211], v[168:171], v[108:111]
	v_mfma_f32_16x16x32_bf16 v[100:103], v[200:203], v[176:179], v[100:103]
	v_mfma_f32_16x16x32_bf16 v[92:95], v[208:211], v[176:179], v[92:95]
	v_mfma_f32_16x16x32_bf16 v[84:87], v[200:203], v[184:187], v[84:87]
	v_mfma_f32_16x16x32_bf16 v[76:79], v[208:211], v[184:187], v[76:79]
	v_mfma_f32_16x16x32_bf16 v[68:71], v[200:203], v[192:195], v[68:71]
	v_mfma_f32_16x16x32_bf16 v[64:67], v[208:211], v[192:195], v[64:67]
	s_mov_b32 m0, s61
	s_barrier
	ds_read_b128 v[156:159], v166 offset:49152
	ds_read_b128 v[168:171], v166 offset:50176
	ds_read_b128 v[172:175], v166 offset:51200
	ds_read_b128 v[176:179], v166 offset:52224
	ds_read_b128 v[180:183], v166 offset:53248
	ds_read_b128 v[184:187], v166 offset:54272
	ds_read_b128 v[188:191], v166 offset:55296
	ds_read_b128 v[192:195], v166 offset:56320
	global_load_lds_dwordx4 v146, s[100:101]
	s_mov_b32 m0, s62
	s_nop 0
	global_load_lds_dwordx4 v148, s[100:101]
	s_barrier
	s_waitcnt lgkmcnt(0)
	v_mfma_f32_16x16x32_bf16 v[60:63], v[128:131], v[156:159], v[60:63]
	v_mfma_f32_16x16x32_bf16 v[56:59], v[136:139], v[156:159], v[56:59]
	v_mfma_f32_16x16x32_bf16 v[48:51], v[128:131], v[172:175], v[48:51]
	v_mfma_f32_16x16x32_bf16 v[40:43], v[136:139], v[172:175], v[40:43]
	v_mfma_f32_16x16x32_bf16 v[32:35], v[128:131], v[180:183], v[32:35]
	v_mfma_f32_16x16x32_bf16 v[24:27], v[136:139], v[180:183], v[24:27]
	v_mfma_f32_16x16x32_bf16 v[16:19], v[128:131], v[188:191], v[16:19]
	v_mfma_f32_16x16x32_bf16 v[8:11], v[136:139], v[188:191], v[8:11]
	v_mfma_f32_16x16x32_bf16 v[60:63], v[132:135], v[168:171], v[60:63]
	v_mfma_f32_16x16x32_bf16 v[56:59], v[140:143], v[168:171], v[56:59]
	v_mfma_f32_16x16x32_bf16 v[48:51], v[132:135], v[176:179], v[48:51]
	v_mfma_f32_16x16x32_bf16 v[40:43], v[140:143], v[176:179], v[40:43]
	v_mfma_f32_16x16x32_bf16 v[32:35], v[132:135], v[184:187], v[32:35]
	v_mfma_f32_16x16x32_bf16 v[24:27], v[140:143], v[184:187], v[24:27]
	v_mfma_f32_16x16x32_bf16 v[16:19], v[132:135], v[192:195], v[16:19]
	v_mfma_f32_16x16x32_bf16 v[8:11], v[140:143], v[192:195], v[8:11]
	s_barrier
	s_add_u32 s44, s44, 0x80080
	s_addc_u32 s45, s45, 0
	s_add_i32 s46, s46, s54
	s_mov_b32 m0, s46
	s_nop 0
	global_load_lds_dwordx4 v146, s[44:45]
	s_add_i32 m0, s46, 0x2000
	s_nop 0
	global_load_lds_dwordx4 v148, s[44:45]
	s_waitcnt vmcnt(6)
	s_barrier
	v_mfma_f32_16x16x32_bf16 v[52:55], v[196:199], v[156:159], v[52:55]
	v_mfma_f32_16x16x32_bf16 v[44:47], v[204:207], v[156:159], v[44:47]
	v_mfma_f32_16x16x32_bf16 v[36:39], v[196:199], v[172:175], v[36:39]
	v_mfma_f32_16x16x32_bf16 v[28:31], v[204:207], v[172:175], v[28:31]
	v_mfma_f32_16x16x32_bf16 v[20:23], v[196:199], v[180:183], v[20:23]
	v_mfma_f32_16x16x32_bf16 v[12:15], v[204:207], v[180:183], v[12:15]
	v_mfma_f32_16x16x32_bf16 v[4:7], v[196:199], v[188:191], v[4:7]
	v_mfma_f32_16x16x32_bf16 v[0:3], v[204:207], v[188:191], v[0:3]
	v_mfma_f32_16x16x32_bf16 v[52:55], v[200:203], v[168:171], v[52:55]
	v_mfma_f32_16x16x32_bf16 v[44:47], v[208:211], v[168:171], v[44:47]
	v_mfma_f32_16x16x32_bf16 v[36:39], v[200:203], v[176:179], v[36:39]
	v_mfma_f32_16x16x32_bf16 v[28:31], v[208:211], v[176:179], v[28:31]
	v_mfma_f32_16x16x32_bf16 v[20:23], v[200:203], v[184:187], v[20:23]
	v_mfma_f32_16x16x32_bf16 v[12:15], v[208:211], v[184:187], v[12:15]
	v_mfma_f32_16x16x32_bf16 v[4:7], v[200:203], v[192:195], v[4:7]
	v_mfma_f32_16x16x32_bf16 v[0:3], v[208:211], v[192:195], v[0:3]
	s_add_i32 s70, s70, 2
	s_add_u32 s42, s42, 0x100
	s_addc_u32 s43, s43, 0
	s_add_u32 s29, s29, 0x100
	s_addc_u32 s69, s69, 0
	s_cmp_gt_u32 s70, 29
	s_barrier
	s_cbranch_scc0 .LBB0_1074
	s_ashr_i32 s19, s40, 3
	v_lshl_add_u32 v160, s40, 8, v162
	v_lshl_or_b32 v158, s67, 8, v164
	s_mul_hi_i32 s29, s19, 0xc000
	s_mul_i32 s19, s19, 0xc000
	v_ashrrev_i32_e32 v161, 31, v160
	s_add_u32 s28, s59, s19
	v_ashrrev_i32_e32 v159, 31, v158
	v_lshlrev_b64 v[130:131], 11, v[160:161]
	s_addc_u32 s29, s60, s29
	v_lshl_add_u64 v[156:157], v[130:131], 0, v[158:159]
	v_lshl_add_u64 v[128:129], v[158:159], 2, s[28:29]
	v_lshl_add_u64 v[172:173], v[156:157], 2, s[52:53]
	global_load_dwordx4 v[136:139], v[128:129], off
	v_lshlrev_b64 v[174:175], 1, v[156:157]
	v_lshl_add_u64 v[176:177], s[6:7], 0, v[174:175]
	global_load_dwordx4 v[140:143], v[128:129], off offset:64
	global_load_dwordx4 v[132:135], v[128:129], off offset:512
	s_nop 0
	global_load_dwordx4 v[128:131], v[128:129], off offset:576
	s_mov_b32 s67, s18
	s_mov_b32 s40, s30
	s_mov_b64 s[44:45], s[38:39]
	s_mov_b64 s[42:43], s[36:37]
	s_mov_b32 s29, 0
	global_load_dwordx4 v[180:183], v[172:173], off
	global_load_dwordx4 v[184:187], v[172:173], off offset:64
	global_load_dwordx4 v[188:191], v[172:173], off offset:512
	global_load_dwordx4 v[192:195], v[172:173], off offset:576
	s_mov_b32 s28, 0x20000
	v_lshl_add_u64 v[168:169], v[172:173], 0, s[28:29]
	global_load_dwordx4 v[196:199], v[168:169], off
	global_load_dwordx4 v[200:203], v[168:169], off offset:64
	global_load_dwordx4 v[204:207], v[168:169], off offset:512
	global_load_dwordx4 v[208:211], v[168:169], off offset:576
	s_mov_b32 s28, 0x40000
	v_lshl_add_u64 v[168:169], v[172:173], 0, s[28:29]
	global_load_dwordx4 v[212:215], v[168:169], off
	global_load_dwordx4 v[216:219], v[168:169], off offset:64
	global_load_dwordx4 v[220:223], v[168:169], off offset:512
	global_load_dwordx4 v[224:227], v[168:169], off offset:576
	s_mov_b32 s28, 0x60000
	v_lshl_add_u64 v[168:169], v[172:173], 0, s[28:29]
	global_load_dwordx4 v[228:231], v[168:169], off
	global_load_dwordx4 v[232:235], v[168:169], off offset:64
	global_load_dwordx4 v[236:239], v[168:169], off offset:512
	global_load_dwordx4 v[240:243], v[168:169], off offset:576
	s_mov_b32 s28, 0x100000
	v_lshl_add_u64 v[168:169], v[172:173], 0, s[28:29]
	s_waitcnt vmcnt(15)
	v_pk_fma_f32 v[124:125], v[124:125], v[136:137], v[180:181]
	v_pk_fma_f32 v[126:127], v[126:127], v[138:139], v[182:183]
	v_cvt_pk_bf16_f32 v124, v124, v125
	v_cvt_pk_bf16_f32 v125, v126, v127
	global_store_dwordx2 v[176:177], v[124:125], off
	global_load_dwordx4 v[180:183], v[168:169], off
	s_waitcnt vmcnt(16)
	v_pk_fma_f32 v[120:121], v[120:121], v[140:141], v[184:185]
	v_pk_fma_f32 v[122:123], v[122:123], v[142:143], v[186:187]
	v_cvt_pk_bf16_f32 v120, v120, v121
	v_cvt_pk_bf16_f32 v121, v122, v123
	global_store_dwordx2 v[176:177], v[120:121], off offset:32
	global_load_dwordx4 v[184:187], v[168:169], off offset:64
	s_waitcnt vmcnt(17)
	v_pk_fma_f32 v[116:117], v[116:117], v[132:133], v[188:189]
	v_pk_fma_f32 v[118:119], v[118:119], v[134:135], v[190:191]
	v_cvt_pk_bf16_f32 v116, v116, v117
	v_cvt_pk_bf16_f32 v117, v118, v119
	global_store_dwordx2 v[176:177], v[116:117], off offset:256
	global_load_dwordx4 v[188:191], v[168:169], off offset:512
	s_waitcnt vmcnt(18)
	v_pk_fma_f32 v[108:109], v[108:109], v[128:129], v[192:193]
	v_pk_fma_f32 v[110:111], v[110:111], v[130:131], v[194:195]
	v_cvt_pk_bf16_f32 v108, v108, v109
	v_cvt_pk_bf16_f32 v109, v110, v111
	global_store_dwordx2 v[176:177], v[108:109], off offset:288
	global_load_dwordx4 v[192:195], v[168:169], off offset:576
	s_mov_b32 s28, 0x10000
	v_lshl_add_u64 v[170:171], v[176:177], 0, s[28:29]
	s_mov_b32 s28, 0x120000
	v_lshl_add_u64 v[168:169], v[172:173], 0, s[28:29]
	s_waitcnt vmcnt(19)
	v_pk_fma_f32 v[112:113], v[112:113], v[136:137], v[196:197]
	v_pk_fma_f32 v[114:115], v[114:115], v[138:139], v[198:199]
	v_cvt_pk_bf16_f32 v112, v112, v113
	v_cvt_pk_bf16_f32 v113, v114, v115
	global_store_dwordx2 v[170:171], v[112:113], off
	global_load_dwordx4 v[196:199], v[168:169], off
	s_waitcnt vmcnt(20)
	v_pk_fma_f32 v[104:105], v[104:105], v[140:141], v[200:201]
	v_pk_fma_f32 v[106:107], v[106:107], v[142:143], v[202:203]
	v_cvt_pk_bf16_f32 v104, v104, v105
	v_cvt_pk_bf16_f32 v105, v106, v107
	global_store_dwordx2 v[170:171], v[104:105], off offset:32
	global_load_dwordx4 v[200:203], v[168:169], off offset:64
	s_waitcnt vmcnt(21)
	v_pk_fma_f32 v[100:101], v[100:101], v[132:133], v[204:205]
	v_pk_fma_f32 v[102:103], v[102:103], v[134:135], v[206:207]
	v_cvt_pk_bf16_f32 v100, v100, v101
	v_cvt_pk_bf16_f32 v101, v102, v103
	global_store_dwordx2 v[170:171], v[100:101], off offset:256
	global_load_dwordx4 v[204:207], v[168:169], off offset:512
	s_waitcnt vmcnt(22)
	v_pk_fma_f32 v[92:93], v[92:93], v[128:129], v[208:209]
	v_pk_fma_f32 v[94:95], v[94:95], v[130:131], v[210:211]
	v_cvt_pk_bf16_f32 v92, v92, v93
	v_cvt_pk_bf16_f32 v93, v94, v95
	global_store_dwordx2 v[170:171], v[92:93], off offset:288
	global_load_dwordx4 v[208:211], v[168:169], off offset:576
	s_mov_b32 s28, 0x20000
	v_lshl_add_u64 v[170:171], v[176:177], 0, s[28:29]
	s_mov_b32 s28, 0x140000
	v_lshl_add_u64 v[168:169], v[172:173], 0, s[28:29]
	s_waitcnt vmcnt(23)
	v_pk_fma_f32 v[96:97], v[96:97], v[136:137], v[212:213]
	v_pk_fma_f32 v[98:99], v[98:99], v[138:139], v[214:215]
	v_cvt_pk_bf16_f32 v96, v96, v97
	v_cvt_pk_bf16_f32 v97, v98, v99
	global_store_dwordx2 v[170:171], v[96:97], off
	global_load_dwordx4 v[212:215], v[168:169], off
	s_waitcnt vmcnt(24)
	v_pk_fma_f32 v[88:89], v[88:89], v[140:141], v[216:217]
	v_pk_fma_f32 v[90:91], v[90:91], v[142:143], v[218:219]
	v_cvt_pk_bf16_f32 v88, v88, v89
	v_cvt_pk_bf16_f32 v89, v90, v91
	global_store_dwordx2 v[170:171], v[88:89], off offset:32
	global_load_dwordx4 v[216:219], v[168:169], off offset:64
	s_waitcnt vmcnt(25)
	v_pk_fma_f32 v[84:85], v[84:85], v[132:133], v[220:221]
	v_pk_fma_f32 v[86:87], v[86:87], v[134:135], v[222:223]
	v_cvt_pk_bf16_f32 v84, v84, v85
	v_cvt_pk_bf16_f32 v85, v86, v87
	global_store_dwordx2 v[170:171], v[84:85], off offset:256
	global_load_dwordx4 v[220:223], v[168:169], off offset:512
	s_waitcnt vmcnt(26)
	v_pk_fma_f32 v[76:77], v[76:77], v[128:129], v[224:225]
	v_pk_fma_f32 v[78:79], v[78:79], v[130:131], v[226:227]
	v_cvt_pk_bf16_f32 v76, v76, v77
	v_cvt_pk_bf16_f32 v77, v78, v79
	global_store_dwordx2 v[170:171], v[76:77], off offset:288
	global_load_dwordx4 v[224:227], v[168:169], off offset:576
	s_mov_b32 s28, 0x30000
	v_lshl_add_u64 v[170:171], v[176:177], 0, s[28:29]
	s_mov_b32 s28, 0x160000
	v_lshl_add_u64 v[168:169], v[172:173], 0, s[28:29]
	s_waitcnt vmcnt(27)
	v_pk_fma_f32 v[80:81], v[80:81], v[136:137], v[228:229]
	v_pk_fma_f32 v[82:83], v[82:83], v[138:139], v[230:231]
	v_cvt_pk_bf16_f32 v80, v80, v81
	v_cvt_pk_bf16_f32 v81, v82, v83
	global_store_dwordx2 v[170:171], v[80:81], off
	global_load_dwordx4 v[228:231], v[168:169], off
	s_waitcnt vmcnt(28)
	v_pk_fma_f32 v[72:73], v[72:73], v[140:141], v[232:233]
	v_pk_fma_f32 v[74:75], v[74:75], v[142:143], v[234:235]
	v_cvt_pk_bf16_f32 v72, v72, v73
	v_cvt_pk_bf16_f32 v73, v74, v75
	global_store_dwordx2 v[170:171], v[72:73], off offset:32
	global_load_dwordx4 v[232:235], v[168:169], off offset:64
	s_waitcnt vmcnt(29)
	v_pk_fma_f32 v[68:69], v[68:69], v[132:133], v[236:237]
	v_pk_fma_f32 v[70:71], v[70:71], v[134:135], v[238:239]
	v_cvt_pk_bf16_f32 v68, v68, v69
	v_cvt_pk_bf16_f32 v69, v70, v71
	global_store_dwordx2 v[170:171], v[68:69], off offset:256
	global_load_dwordx4 v[236:239], v[168:169], off offset:512
	s_waitcnt vmcnt(30)
	v_pk_fma_f32 v[64:65], v[64:65], v[128:129], v[240:241]
	v_pk_fma_f32 v[66:67], v[66:67], v[130:131], v[242:243]
	v_cvt_pk_bf16_f32 v64, v64, v65
	v_cvt_pk_bf16_f32 v65, v66, v67
	global_store_dwordx2 v[170:171], v[64:65], off offset:288
	global_load_dwordx4 v[240:243], v[168:169], off offset:576
	s_mov_b32 s28, 0x80000
	v_lshl_add_u64 v[170:171], v[176:177], 0, s[28:29]
	s_waitcnt vmcnt(30)
	v_pk_fma_f32 v[60:61], v[60:61], v[136:137], v[180:181]
	v_pk_fma_f32 v[62:63], v[62:63], v[138:139], v[182:183]
	v_cvt_pk_bf16_f32 v60, v60, v61
	v_cvt_pk_bf16_f32 v61, v62, v63
	global_store_dwordx2 v[170:171], v[60:61], off
	s_waitcnt vmcnt(29)
	v_pk_fma_f32 v[56:57], v[56:57], v[140:141], v[184:185]
	v_pk_fma_f32 v[58:59], v[58:59], v[142:143], v[186:187]
	v_cvt_pk_bf16_f32 v56, v56, v57
	v_cvt_pk_bf16_f32 v57, v58, v59
	global_store_dwordx2 v[170:171], v[56:57], off offset:32
	s_waitcnt vmcnt(28)
	v_pk_fma_f32 v[52:53], v[52:53], v[132:133], v[188:189]
	v_pk_fma_f32 v[54:55], v[54:55], v[134:135], v[190:191]
	v_cvt_pk_bf16_f32 v52, v52, v53
	v_cvt_pk_bf16_f32 v53, v54, v55
	global_store_dwordx2 v[170:171], v[52:53], off offset:256
	s_waitcnt vmcnt(27)
	v_pk_fma_f32 v[44:45], v[44:45], v[128:129], v[192:193]
	v_pk_fma_f32 v[46:47], v[46:47], v[130:131], v[194:195]
	v_cvt_pk_bf16_f32 v44, v44, v45
	v_cvt_pk_bf16_f32 v45, v46, v47
	global_store_dwordx2 v[170:171], v[44:45], off offset:288
	s_mov_b32 s28, 0x90000
	v_lshl_add_u64 v[170:171], v[176:177], 0, s[28:29]
	s_waitcnt vmcnt(26)
	v_pk_fma_f32 v[48:49], v[48:49], v[136:137], v[196:197]
	v_pk_fma_f32 v[50:51], v[50:51], v[138:139], v[198:199]
	v_cvt_pk_bf16_f32 v48, v48, v49
	v_cvt_pk_bf16_f32 v49, v50, v51
	global_store_dwordx2 v[170:171], v[48:49], off
	s_waitcnt vmcnt(25)
	v_pk_fma_f32 v[40:41], v[40:41], v[140:141], v[200:201]
	v_pk_fma_f32 v[42:43], v[42:43], v[142:143], v[202:203]
	v_cvt_pk_bf16_f32 v40, v40, v41
	v_cvt_pk_bf16_f32 v41, v42, v43
	global_store_dwordx2 v[170:171], v[40:41], off offset:32
	s_waitcnt vmcnt(24)
	v_pk_fma_f32 v[36:37], v[36:37], v[132:133], v[204:205]
	v_pk_fma_f32 v[38:39], v[38:39], v[134:135], v[206:207]
	v_cvt_pk_bf16_f32 v36, v36, v37
	v_cvt_pk_bf16_f32 v37, v38, v39
	global_store_dwordx2 v[170:171], v[36:37], off offset:256
	s_waitcnt vmcnt(23)
	v_pk_fma_f32 v[28:29], v[28:29], v[128:129], v[208:209]
	v_pk_fma_f32 v[30:31], v[30:31], v[130:131], v[210:211]
	v_cvt_pk_bf16_f32 v28, v28, v29
	v_cvt_pk_bf16_f32 v29, v30, v31
	global_store_dwordx2 v[170:171], v[28:29], off offset:288
	s_mov_b32 s28, 0xa0000
	v_lshl_add_u64 v[170:171], v[176:177], 0, s[28:29]
	s_waitcnt vmcnt(22)
	v_pk_fma_f32 v[32:33], v[32:33], v[136:137], v[212:213]
	v_pk_fma_f32 v[34:35], v[34:35], v[138:139], v[214:215]
	v_cvt_pk_bf16_f32 v32, v32, v33
	v_cvt_pk_bf16_f32 v33, v34, v35
	global_store_dwordx2 v[170:171], v[32:33], off
	s_waitcnt vmcnt(21)
	v_pk_fma_f32 v[24:25], v[24:25], v[140:141], v[216:217]
	v_pk_fma_f32 v[26:27], v[26:27], v[142:143], v[218:219]
	v_cvt_pk_bf16_f32 v24, v24, v25
	v_cvt_pk_bf16_f32 v25, v26, v27
	global_store_dwordx2 v[170:171], v[24:25], off offset:32
	s_waitcnt vmcnt(20)
	v_pk_fma_f32 v[20:21], v[20:21], v[132:133], v[220:221]
	v_pk_fma_f32 v[22:23], v[22:23], v[134:135], v[222:223]
	v_cvt_pk_bf16_f32 v20, v20, v21
	v_cvt_pk_bf16_f32 v21, v22, v23
	global_store_dwordx2 v[170:171], v[20:21], off offset:256
	s_waitcnt vmcnt(19)
	v_pk_fma_f32 v[12:13], v[12:13], v[128:129], v[224:225]
	v_pk_fma_f32 v[14:15], v[14:15], v[130:131], v[226:227]
	v_cvt_pk_bf16_f32 v12, v12, v13
	v_cvt_pk_bf16_f32 v13, v14, v15
	global_store_dwordx2 v[170:171], v[12:13], off offset:288
	s_mov_b32 s28, 0xb0000
	v_lshl_add_u64 v[170:171], v[176:177], 0, s[28:29]
	s_waitcnt vmcnt(18)
	v_pk_fma_f32 v[16:17], v[16:17], v[136:137], v[228:229]
	v_pk_fma_f32 v[18:19], v[18:19], v[138:139], v[230:231]
	v_cvt_pk_bf16_f32 v16, v16, v17
	v_cvt_pk_bf16_f32 v17, v18, v19
	global_store_dwordx2 v[170:171], v[16:17], off
	s_waitcnt vmcnt(17)
	v_pk_fma_f32 v[8:9], v[8:9], v[140:141], v[232:233]
	v_pk_fma_f32 v[10:11], v[10:11], v[142:143], v[234:235]
	v_cvt_pk_bf16_f32 v8, v8, v9
	v_cvt_pk_bf16_f32 v9, v10, v11
	global_store_dwordx2 v[170:171], v[8:9], off offset:32
	s_waitcnt vmcnt(16)
	v_pk_fma_f32 v[4:5], v[4:5], v[132:133], v[236:237]
	v_pk_fma_f32 v[6:7], v[6:7], v[134:135], v[238:239]
	v_cvt_pk_bf16_f32 v4, v4, v5
	v_cvt_pk_bf16_f32 v5, v6, v7
	global_store_dwordx2 v[170:171], v[4:5], off offset:256
	s_waitcnt vmcnt(15)
	v_pk_fma_f32 v[0:1], v[0:1], v[128:129], v[240:241]
	v_pk_fma_f32 v[2:3], v[2:3], v[130:131], v[242:243]
	v_cvt_pk_bf16_f32 v0, v0, v1
	v_cvt_pk_bf16_f32 v1, v2, v3
	global_store_dwordx2 v[170:171], v[0:1], off offset:288
	s_and_b64 vcc, exec, s[34:35]
	s_cbranch_vccz .LBB0_1065
	s_branch .LBB0_1077

.LBB0_1202:
	s_ashr_i32 s13, s12, 31
	s_xor_b64 s[16:17], s[28:29], -1
	s_lshl_b64 s[14:15], s[12:13], 20
	s_add_u32 s14, s33, s14
	s_addc_u32 s15, s40, s15
	s_and_b64 s[18:19], s[28:29], exec
	s_cselect_b32 s13, s15, s35
	s_cselect_b32 s58, s14, s34
	s_ashr_i32 s11, s10, 31
	s_lshl_b64 s[18:19], s[10:11], 20
	s_add_u32 s18, s41, s18
	s_addc_u32 s19, s42, s19
	s_and_b64 s[28:29], s[28:29], exec
	s_cselect_b32 s11, s19, s37
	s_cselect_b32 s28, s18, s36
	s_add_u32 s34, s34, 0x80080
	s_addc_u32 s35, s35, 0
	s_add_u32 s29, s36, 0x100
	s_addc_u32 s59, s37, 0
	s_mov_b32 s60, -2
	v_add_u32_e32 v244, 0x18000, v143
	v_add_u32_e32 v245, 0x1c000, v143
	ds_read_b128 v[150:153], v147
	ds_read_b128 v[154:157], v147 offset:1024
	ds_read_b128 v[158:161], v147 offset:2048
	ds_read_b128 v[162:165], v147 offset:3072
	s_add_u32 s36, s34, 0xfff80080
	s_addc_u32 s37, s35, -1
	s_cmp_eq_u32 s60, 28
	s_cselect_b32 s39, s13, s37
	s_cselect_b32 s38, s58, s36
	s_cselect_b32 s37, s11, s59
	s_cselect_b32 s36, s28, s29
	s_add_i32 m0, s31, 0xc000
	ds_read_b128 v[166:169], v148
	ds_read_b128 v[170:173], v148 offset:1024
	ds_read_b128 v[174:177], v148 offset:2048
	ds_read_b128 v[178:181], v148 offset:3072
	ds_read_b128 v[182:185], v148 offset:4096
	ds_read_b128 v[186:189], v148 offset:5120
	ds_read_b128 v[190:193], v148 offset:6144
	ds_read_b128 v[194:197], v148 offset:7168
	global_load_lds_dwordx4 v136, s[34:35]
	s_add_i32 m0, s31, 0xe000
	s_nop 0
	global_load_lds_dwordx4 v138, s[34:35]
	s_waitcnt lgkmcnt(8)
	s_barrier
	s_waitcnt lgkmcnt(0)
	v_mfma_f32_16x16x32_bf16 v[124:127], v[150:153], v[166:169], 0
	v_mfma_f32_16x16x32_bf16 v[120:123], v[158:161], v[166:169], 0
	v_mfma_f32_16x16x32_bf16 v[108:111], v[150:153], v[174:177], 0
	v_mfma_f32_16x16x32_bf16 v[104:107], v[158:161], v[174:177], 0
	v_mfma_f32_16x16x32_bf16 v[92:95], v[150:153], v[182:185], 0
	v_mfma_f32_16x16x32_bf16 v[88:91], v[158:161], v[182:185], 0
	v_mfma_f32_16x16x32_bf16 v[76:79], v[150:153], v[190:193], 0
	v_mfma_f32_16x16x32_bf16 v[72:75], v[158:161], v[190:193], 0
	v_mfma_f32_16x16x32_bf16 v[124:127], v[154:157], v[170:173], v[124:127]
	v_mfma_f32_16x16x32_bf16 v[120:123], v[162:165], v[170:173], v[120:123]
	v_mfma_f32_16x16x32_bf16 v[108:111], v[154:157], v[178:181], v[108:111]
	v_mfma_f32_16x16x32_bf16 v[104:107], v[162:165], v[178:181], v[104:107]
	v_mfma_f32_16x16x32_bf16 v[92:95], v[154:157], v[186:189], v[92:95]
	v_mfma_f32_16x16x32_bf16 v[88:91], v[162:165], v[186:189], v[88:91]
	v_mfma_f32_16x16x32_bf16 v[76:79], v[154:157], v[194:197], v[76:79]
	v_mfma_f32_16x16x32_bf16 v[72:75], v[162:165], v[194:197], v[72:75]
	s_barrier
	s_add_i32 s61, s54, s43
	s_add_u32 s98, s36, s8
	s_addc_u32 s99, s37, s9
	s_mov_b32 m0, s61
	ds_read_b128 v[198:201], v149
	ds_read_b128 v[202:205], v149 offset:1024
	ds_read_b128 v[206:209], v149 offset:2048
	ds_read_b128 v[210:213], v149 offset:3072
	global_load_lds_dwordx4 v132, s[36:37]
	s_add_i32 m0, s61, 0x2000
	s_nop 0
	global_load_lds_dwordx4 v128, s[36:37]
	s_barrier
	s_waitcnt lgkmcnt(0)
	v_mfma_f32_16x16x32_bf16 v[116:119], v[198:201], v[166:169], 0
	v_mfma_f32_16x16x32_bf16 v[112:115], v[206:209], v[166:169], 0
	v_mfma_f32_16x16x32_bf16 v[100:103], v[198:201], v[174:177], 0
	v_mfma_f32_16x16x32_bf16 v[96:99], v[206:209], v[174:177], 0
	v_mfma_f32_16x16x32_bf16 v[84:87], v[198:201], v[182:185], 0
	v_mfma_f32_16x16x32_bf16 v[80:83], v[206:209], v[182:185], 0
	v_mfma_f32_16x16x32_bf16 v[68:71], v[198:201], v[190:193], 0
	v_mfma_f32_16x16x32_bf16 v[64:67], v[206:209], v[190:193], 0
	v_mfma_f32_16x16x32_bf16 v[116:119], v[202:205], v[170:173], v[116:119]
	v_mfma_f32_16x16x32_bf16 v[112:115], v[210:213], v[170:173], v[112:115]
	v_mfma_f32_16x16x32_bf16 v[100:103], v[202:205], v[178:181], v[100:103]
	v_mfma_f32_16x16x32_bf16 v[96:99], v[210:213], v[178:181], v[96:99]
	v_mfma_f32_16x16x32_bf16 v[84:87], v[202:205], v[186:189], v[84:87]
	v_mfma_f32_16x16x32_bf16 v[80:83], v[210:213], v[186:189], v[80:83]
	v_mfma_f32_16x16x32_bf16 v[68:71], v[202:205], v[194:197], v[68:71]
	v_mfma_f32_16x16x32_bf16 v[64:67], v[210:213], v[194:197], v[64:67]
	s_mov_b32 m0, s31
	s_add_u32 s100, s38, s8
	s_addc_u32 s101, s39, s9
	s_barrier
	ds_read_b128 v[166:169], v148 offset:16384
	ds_read_b128 v[170:173], v148 offset:17408
	ds_read_b128 v[174:177], v148 offset:18432
	ds_read_b128 v[178:181], v148 offset:19456
	ds_read_b128 v[182:185], v148 offset:20480
	ds_read_b128 v[186:189], v148 offset:21504
	ds_read_b128 v[190:193], v148 offset:22528
	ds_read_b128 v[194:197], v148 offset:23552
	global_load_lds_dwordx4 v134, s[38:39]
	s_mov_b32 m0, s46
	s_nop 0
	global_load_lds_dwordx4 v130, s[38:39]
	s_barrier
	s_waitcnt lgkmcnt(0)
	v_mfma_f32_16x16x32_bf16 v[60:63], v[150:153], v[166:169], 0
	v_mfma_f32_16x16x32_bf16 v[56:59], v[158:161], v[166:169], 0
	v_mfma_f32_16x16x32_bf16 v[44:47], v[150:153], v[174:177], 0
	v_mfma_f32_16x16x32_bf16 v[40:43], v[158:161], v[174:177], 0
	v_mfma_f32_16x16x32_bf16 v[28:31], v[150:153], v[182:185], 0
	v_mfma_f32_16x16x32_bf16 v[24:27], v[158:161], v[182:185], 0
	v_mfma_f32_16x16x32_bf16 v[12:15], v[150:153], v[190:193], 0
	v_mfma_f32_16x16x32_bf16 v[8:11], v[158:161], v[190:193], 0
	v_mfma_f32_16x16x32_bf16 v[60:63], v[154:157], v[170:173], v[60:63]
	v_mfma_f32_16x16x32_bf16 v[56:59], v[162:165], v[170:173], v[56:59]
	v_mfma_f32_16x16x32_bf16 v[44:47], v[154:157], v[178:181], v[44:47]
	v_mfma_f32_16x16x32_bf16 v[40:43], v[162:165], v[178:181], v[40:43]
	v_mfma_f32_16x16x32_bf16 v[28:31], v[154:157], v[186:189], v[28:31]
	v_mfma_f32_16x16x32_bf16 v[24:27], v[162:165], v[186:189], v[24:27]
	v_mfma_f32_16x16x32_bf16 v[12:15], v[154:157], v[194:197], v[12:15]
	v_mfma_f32_16x16x32_bf16 v[8:11], v[162:165], v[194:197], v[8:11]
	s_barrier
	s_add_u32 s62, s36, 0x80000
	s_addc_u32 s63, s37, 0
	s_add_i32 s61, s55, s43
	s_mov_b32 m0, s61
	s_nop 0
	global_load_lds_dwordx4 v132, s[62:63]
	s_add_i32 m0, s61, 0x2000
	s_nop 0
	global_load_lds_dwordx4 v128, s[62:63]
	s_waitcnt vmcnt(6)
	s_barrier
	v_mfma_f32_16x16x32_bf16 v[52:55], v[198:201], v[166:169], 0
	v_mfma_f32_16x16x32_bf16 v[48:51], v[206:209], v[166:169], 0
	v_mfma_f32_16x16x32_bf16 v[36:39], v[198:201], v[174:177], 0
	v_mfma_f32_16x16x32_bf16 v[32:35], v[206:209], v[174:177], 0
	v_mfma_f32_16x16x32_bf16 v[20:23], v[198:201], v[182:185], 0
	v_mfma_f32_16x16x32_bf16 v[16:19], v[206:209], v[182:185], 0
	v_mfma_f32_16x16x32_bf16 v[4:7], v[198:201], v[190:193], 0
	v_mfma_f32_16x16x32_bf16 v[0:3], v[206:209], v[190:193], 0
	v_mfma_f32_16x16x32_bf16 v[52:55], v[202:205], v[170:173], v[52:55]
	v_mfma_f32_16x16x32_bf16 v[48:51], v[210:213], v[170:173], v[48:51]
	v_mfma_f32_16x16x32_bf16 v[36:39], v[202:205], v[178:181], v[36:39]
	v_mfma_f32_16x16x32_bf16 v[32:35], v[210:213], v[178:181], v[32:35]
	v_mfma_f32_16x16x32_bf16 v[20:23], v[202:205], v[186:189], v[20:23]
	v_mfma_f32_16x16x32_bf16 v[16:19], v[210:213], v[186:189], v[16:19]
	v_mfma_f32_16x16x32_bf16 v[4:7], v[202:205], v[194:197], v[4:7]
	v_mfma_f32_16x16x32_bf16 v[0:3], v[210:213], v[194:197], v[0:3]
	s_add_i32 s61, 0, 0x18000
	s_barrier
	ds_read_b128 v[150:153], v244
	ds_read_b128 v[154:157], v244 offset:1024
	ds_read_b128 v[158:161], v244 offset:2048
	ds_read_b128 v[162:165], v244 offset:3072
	s_add_u32 s38, s38, 0x80000
	s_addc_u32 s39, s39, 0
	s_mov_b32 m0, s47
	ds_read_b128 v[166:169], v148 offset:32768
	ds_read_b128 v[170:173], v148 offset:33792
	ds_read_b128 v[174:177], v148 offset:34816
	ds_read_b128 v[178:181], v148 offset:35840
	ds_read_b128 v[182:185], v148 offset:36864
	ds_read_b128 v[186:189], v148 offset:37888
	ds_read_b128 v[190:193], v148 offset:38912
	ds_read_b128 v[194:197], v148 offset:39936
	global_load_lds_dwordx4 v134, s[38:39]
	s_mov_b32 m0, s48
	s_nop 0
	global_load_lds_dwordx4 v130, s[38:39]
	s_waitcnt lgkmcnt(8)
	s_barrier
	s_waitcnt lgkmcnt(0)
	v_mfma_f32_16x16x32_bf16 v[124:127], v[150:153], v[166:169], v[124:127]
	v_mfma_f32_16x16x32_bf16 v[120:123], v[158:161], v[166:169], v[120:123]
	v_mfma_f32_16x16x32_bf16 v[108:111], v[150:153], v[174:177], v[108:111]
	v_mfma_f32_16x16x32_bf16 v[104:107], v[158:161], v[174:177], v[104:107]
	v_mfma_f32_16x16x32_bf16 v[92:95], v[150:153], v[182:185], v[92:95]
	v_mfma_f32_16x16x32_bf16 v[88:91], v[158:161], v[182:185], v[88:91]
	v_mfma_f32_16x16x32_bf16 v[76:79], v[150:153], v[190:193], v[76:79]
	v_mfma_f32_16x16x32_bf16 v[72:75], v[158:161], v[190:193], v[72:75]
	v_mfma_f32_16x16x32_bf16 v[124:127], v[154:157], v[170:173], v[124:127]
	v_mfma_f32_16x16x32_bf16 v[120:123], v[162:165], v[170:173], v[120:123]
	v_mfma_f32_16x16x32_bf16 v[108:111], v[154:157], v[178:181], v[108:111]
	v_mfma_f32_16x16x32_bf16 v[104:107], v[162:165], v[178:181], v[104:107]
	v_mfma_f32_16x16x32_bf16 v[92:95], v[154:157], v[186:189], v[92:95]
	v_mfma_f32_16x16x32_bf16 v[88:91], v[162:165], v[186:189], v[88:91]
	v_mfma_f32_16x16x32_bf16 v[76:79], v[154:157], v[194:197], v[76:79]
	v_mfma_f32_16x16x32_bf16 v[72:75], v[162:165], v[194:197], v[72:75]
	s_barrier
	s_add_i32 s38, 0, 0x1c000
	s_add_i32 s39, s61, s43
	s_mov_b32 m0, s39
	ds_read_b128 v[198:201], v245
	ds_read_b128 v[202:205], v245 offset:1024
	ds_read_b128 v[206:209], v245 offset:2048
	ds_read_b128 v[210:213], v245 offset:3072
	global_load_lds_dwordx4 v132, s[98:99]
	s_add_i32 m0, s39, 0x2000
	s_nop 0
	global_load_lds_dwordx4 v128, s[98:99]
	s_barrier
	s_waitcnt lgkmcnt(0)
	v_mfma_f32_16x16x32_bf16 v[116:119], v[198:201], v[166:169], v[116:119]
	v_mfma_f32_16x16x32_bf16 v[112:115], v[206:209], v[166:169], v[112:115]
	v_mfma_f32_16x16x32_bf16 v[100:103], v[198:201], v[174:177], v[100:103]
	v_mfma_f32_16x16x32_bf16 v[96:99], v[206:209], v[174:177], v[96:99]
	v_mfma_f32_16x16x32_bf16 v[84:87], v[198:201], v[182:185], v[84:87]
	v_mfma_f32_16x16x32_bf16 v[80:83], v[206:209], v[182:185], v[80:83]
	v_mfma_f32_16x16x32_bf16 v[68:71], v[198:201], v[190:193], v[68:71]
	v_mfma_f32_16x16x32_bf16 v[64:67], v[206:209], v[190:193], v[64:67]
	v_mfma_f32_16x16x32_bf16 v[116:119], v[202:205], v[170:173], v[116:119]
	v_mfma_f32_16x16x32_bf16 v[112:115], v[210:213], v[170:173], v[112:115]
	v_mfma_f32_16x16x32_bf16 v[100:103], v[202:205], v[178:181], v[100:103]
	v_mfma_f32_16x16x32_bf16 v[96:99], v[210:213], v[178:181], v[96:99]
	v_mfma_f32_16x16x32_bf16 v[84:87], v[202:205], v[186:189], v[84:87]
	v_mfma_f32_16x16x32_bf16 v[80:83], v[210:213], v[186:189], v[80:83]
	v_mfma_f32_16x16x32_bf16 v[68:71], v[202:205], v[194:197], v[68:71]
	v_mfma_f32_16x16x32_bf16 v[64:67], v[210:213], v[194:197], v[64:67]
	s_mov_b32 m0, s50
	s_barrier
	ds_read_b128 v[166:169], v148 offset:49152
	ds_read_b128 v[170:173], v148 offset:50176
	ds_read_b128 v[174:177], v148 offset:51200
	ds_read_b128 v[178:181], v148 offset:52224
	ds_read_b128 v[182:185], v148 offset:53248
	ds_read_b128 v[186:189], v148 offset:54272
	ds_read_b128 v[190:193], v148 offset:55296
	ds_read_b128 v[194:197], v148 offset:56320
	global_load_lds_dwordx4 v134, s[100:101]
	s_mov_b32 m0, s51
	s_nop 0
	global_load_lds_dwordx4 v130, s[100:101]
	s_barrier
	s_waitcnt lgkmcnt(0)
	v_mfma_f32_16x16x32_bf16 v[60:63], v[150:153], v[166:169], v[60:63]
	v_mfma_f32_16x16x32_bf16 v[56:59], v[158:161], v[166:169], v[56:59]
	v_mfma_f32_16x16x32_bf16 v[44:47], v[150:153], v[174:177], v[44:47]
	v_mfma_f32_16x16x32_bf16 v[40:43], v[158:161], v[174:177], v[40:43]
	v_mfma_f32_16x16x32_bf16 v[28:31], v[150:153], v[182:185], v[28:31]
	v_mfma_f32_16x16x32_bf16 v[24:27], v[158:161], v[182:185], v[24:27]
	v_mfma_f32_16x16x32_bf16 v[12:15], v[150:153], v[190:193], v[12:15]
	v_mfma_f32_16x16x32_bf16 v[8:11], v[158:161], v[190:193], v[8:11]
	v_mfma_f32_16x16x32_bf16 v[60:63], v[154:157], v[170:173], v[60:63]
	v_mfma_f32_16x16x32_bf16 v[56:59], v[162:165], v[170:173], v[56:59]
	v_mfma_f32_16x16x32_bf16 v[44:47], v[154:157], v[178:181], v[44:47]
	v_mfma_f32_16x16x32_bf16 v[40:43], v[162:165], v[178:181], v[40:43]
	v_mfma_f32_16x16x32_bf16 v[28:31], v[154:157], v[186:189], v[28:31]
	v_mfma_f32_16x16x32_bf16 v[24:27], v[162:165], v[186:189], v[24:27]
	v_mfma_f32_16x16x32_bf16 v[12:15], v[154:157], v[194:197], v[12:15]
	v_mfma_f32_16x16x32_bf16 v[8:11], v[162:165], v[194:197], v[8:11]
	s_barrier
	s_add_u32 s36, s36, 0x80080
	s_addc_u32 s37, s37, 0
	s_add_i32 s38, s38, s43
	s_mov_b32 m0, s38
	s_nop 0
	global_load_lds_dwordx4 v132, s[36:37]
	s_add_i32 m0, s38, 0x2000
	s_nop 0
	global_load_lds_dwordx4 v128, s[36:37]
	s_waitcnt vmcnt(6)
	s_barrier
	v_mfma_f32_16x16x32_bf16 v[52:55], v[198:201], v[166:169], v[52:55]
	v_mfma_f32_16x16x32_bf16 v[48:51], v[206:209], v[166:169], v[48:51]
	v_mfma_f32_16x16x32_bf16 v[36:39], v[198:201], v[174:177], v[36:39]
	v_mfma_f32_16x16x32_bf16 v[32:35], v[206:209], v[174:177], v[32:35]
	v_mfma_f32_16x16x32_bf16 v[20:23], v[198:201], v[182:185], v[20:23]
	v_mfma_f32_16x16x32_bf16 v[16:19], v[206:209], v[182:185], v[16:19]
	v_mfma_f32_16x16x32_bf16 v[4:7], v[198:201], v[190:193], v[4:7]
	v_mfma_f32_16x16x32_bf16 v[0:3], v[206:209], v[190:193], v[0:3]
	v_mfma_f32_16x16x32_bf16 v[52:55], v[202:205], v[170:173], v[52:55]
	v_mfma_f32_16x16x32_bf16 v[48:51], v[210:213], v[170:173], v[48:51]
	v_mfma_f32_16x16x32_bf16 v[36:39], v[202:205], v[178:181], v[36:39]
	v_mfma_f32_16x16x32_bf16 v[32:35], v[210:213], v[178:181], v[32:35]
	v_mfma_f32_16x16x32_bf16 v[20:23], v[202:205], v[186:189], v[20:23]
	v_mfma_f32_16x16x32_bf16 v[16:19], v[210:213], v[186:189], v[16:19]
	v_mfma_f32_16x16x32_bf16 v[4:7], v[202:205], v[194:197], v[4:7]
	v_mfma_f32_16x16x32_bf16 v[0:3], v[210:213], v[194:197], v[0:3]
	s_add_i32 s60, s60, 2
	s_add_u32 s34, s34, 0x100
	s_addc_u32 s35, s35, 0
	s_add_u32 s29, s29, 0x100
	s_addc_u32 s59, s59, 0
	s_cmp_gt_u32 s60, 29
	s_barrier
	s_cbranch_scc0 .LBB0_1203
.LBB0_1203:
	ds_read_b128 v[150:153], v147
	ds_read_b128 v[154:157], v147 offset:1024
	ds_read_b128 v[158:161], v147 offset:2048
	ds_read_b128 v[162:165], v147 offset:3072
	s_add_u32 s36, s34, 0xfff80080
	s_addc_u32 s37, s35, -1
	s_cmp_eq_u32 s60, 28
	s_cselect_b32 s39, s13, s37
	s_cselect_b32 s38, s58, s36
	s_cselect_b32 s37, s11, s59
	s_cselect_b32 s36, s28, s29
	s_add_i32 m0, s31, 0xc000
	ds_read_b128 v[166:169], v148
	ds_read_b128 v[170:173], v148 offset:1024
	ds_read_b128 v[174:177], v148 offset:2048
	ds_read_b128 v[178:181], v148 offset:3072
	ds_read_b128 v[182:185], v148 offset:4096
	ds_read_b128 v[186:189], v148 offset:5120
	ds_read_b128 v[190:193], v148 offset:6144
	ds_read_b128 v[194:197], v148 offset:7168
	global_load_lds_dwordx4 v136, s[34:35]
	s_add_i32 m0, s31, 0xe000
	s_nop 0
	global_load_lds_dwordx4 v138, s[34:35]
	s_waitcnt lgkmcnt(8)
	s_barrier
	s_waitcnt lgkmcnt(0)
	v_mfma_f32_16x16x32_bf16 v[124:127], v[150:153], v[166:169], v[124:127]
	v_mfma_f32_16x16x32_bf16 v[120:123], v[158:161], v[166:169], v[120:123]
	v_mfma_f32_16x16x32_bf16 v[108:111], v[150:153], v[174:177], v[108:111]
	v_mfma_f32_16x16x32_bf16 v[104:107], v[158:161], v[174:177], v[104:107]
	v_mfma_f32_16x16x32_bf16 v[92:95], v[150:153], v[182:185], v[92:95]
	v_mfma_f32_16x16x32_bf16 v[88:91], v[158:161], v[182:185], v[88:91]
	v_mfma_f32_16x16x32_bf16 v[76:79], v[150:153], v[190:193], v[76:79]
	v_mfma_f32_16x16x32_bf16 v[72:75], v[158:161], v[190:193], v[72:75]
	v_mfma_f32_16x16x32_bf16 v[124:127], v[154:157], v[170:173], v[124:127]
	v_mfma_f32_16x16x32_bf16 v[120:123], v[162:165], v[170:173], v[120:123]
	v_mfma_f32_16x16x32_bf16 v[108:111], v[154:157], v[178:181], v[108:111]
	v_mfma_f32_16x16x32_bf16 v[104:107], v[162:165], v[178:181], v[104:107]
	v_mfma_f32_16x16x32_bf16 v[92:95], v[154:157], v[186:189], v[92:95]
	v_mfma_f32_16x16x32_bf16 v[88:91], v[162:165], v[186:189], v[88:91]
	v_mfma_f32_16x16x32_bf16 v[76:79], v[154:157], v[194:197], v[76:79]
	v_mfma_f32_16x16x32_bf16 v[72:75], v[162:165], v[194:197], v[72:75]
	s_barrier
	s_add_i32 s61, s54, s43
	s_add_u32 s98, s36, s8
	s_addc_u32 s99, s37, s9
	s_mov_b32 m0, s61
	ds_read_b128 v[198:201], v149
	ds_read_b128 v[202:205], v149 offset:1024
	ds_read_b128 v[206:209], v149 offset:2048
	ds_read_b128 v[210:213], v149 offset:3072
	global_load_lds_dwordx4 v132, s[36:37]
	s_add_i32 m0, s61, 0x2000
	s_nop 0
	global_load_lds_dwordx4 v128, s[36:37]
	s_barrier
	s_waitcnt lgkmcnt(0)
	v_mfma_f32_16x16x32_bf16 v[116:119], v[198:201], v[166:169], v[116:119]
	v_mfma_f32_16x16x32_bf16 v[112:115], v[206:209], v[166:169], v[112:115]
	v_mfma_f32_16x16x32_bf16 v[100:103], v[198:201], v[174:177], v[100:103]
	v_mfma_f32_16x16x32_bf16 v[96:99], v[206:209], v[174:177], v[96:99]
	v_mfma_f32_16x16x32_bf16 v[84:87], v[198:201], v[182:185], v[84:87]
	v_mfma_f32_16x16x32_bf16 v[80:83], v[206:209], v[182:185], v[80:83]
	v_mfma_f32_16x16x32_bf16 v[68:71], v[198:201], v[190:193], v[68:71]
	v_mfma_f32_16x16x32_bf16 v[64:67], v[206:209], v[190:193], v[64:67]
	v_mfma_f32_16x16x32_bf16 v[116:119], v[202:205], v[170:173], v[116:119]
	v_mfma_f32_16x16x32_bf16 v[112:115], v[210:213], v[170:173], v[112:115]
	v_mfma_f32_16x16x32_bf16 v[100:103], v[202:205], v[178:181], v[100:103]
	v_mfma_f32_16x16x32_bf16 v[96:99], v[210:213], v[178:181], v[96:99]
	v_mfma_f32_16x16x32_bf16 v[84:87], v[202:205], v[186:189], v[84:87]
	v_mfma_f32_16x16x32_bf16 v[80:83], v[210:213], v[186:189], v[80:83]
	v_mfma_f32_16x16x32_bf16 v[68:71], v[202:205], v[194:197], v[68:71]
	v_mfma_f32_16x16x32_bf16 v[64:67], v[210:213], v[194:197], v[64:67]
	s_mov_b32 m0, s31
	s_add_u32 s100, s38, s8
	s_addc_u32 s101, s39, s9
	s_barrier
	ds_read_b128 v[166:169], v148 offset:16384
	ds_read_b128 v[170:173], v148 offset:17408
	ds_read_b128 v[174:177], v148 offset:18432
	ds_read_b128 v[178:181], v148 offset:19456
	ds_read_b128 v[182:185], v148 offset:20480
	ds_read_b128 v[186:189], v148 offset:21504
	ds_read_b128 v[190:193], v148 offset:22528
	ds_read_b128 v[194:197], v148 offset:23552
	global_load_lds_dwordx4 v134, s[38:39]
	s_mov_b32 m0, s46
	s_nop 0
	global_load_lds_dwordx4 v130, s[38:39]
	s_barrier
	s_waitcnt lgkmcnt(0)
	v_mfma_f32_16x16x32_bf16 v[60:63], v[150:153], v[166:169], v[60:63]
	v_mfma_f32_16x16x32_bf16 v[56:59], v[158:161], v[166:169], v[56:59]
	v_mfma_f32_16x16x32_bf16 v[44:47], v[150:153], v[174:177], v[44:47]
	v_mfma_f32_16x16x32_bf16 v[40:43], v[158:161], v[174:177], v[40:43]
	v_mfma_f32_16x16x32_bf16 v[28:31], v[150:153], v[182:185], v[28:31]
	v_mfma_f32_16x16x32_bf16 v[24:27], v[158:161], v[182:185], v[24:27]
	v_mfma_f32_16x16x32_bf16 v[12:15], v[150:153], v[190:193], v[12:15]
	v_mfma_f32_16x16x32_bf16 v[8:11], v[158:161], v[190:193], v[8:11]
	v_mfma_f32_16x16x32_bf16 v[60:63], v[154:157], v[170:173], v[60:63]
	v_mfma_f32_16x16x32_bf16 v[56:59], v[162:165], v[170:173], v[56:59]
	v_mfma_f32_16x16x32_bf16 v[44:47], v[154:157], v[178:181], v[44:47]
	v_mfma_f32_16x16x32_bf16 v[40:43], v[162:165], v[178:181], v[40:43]
	v_mfma_f32_16x16x32_bf16 v[28:31], v[154:157], v[186:189], v[28:31]
	v_mfma_f32_16x16x32_bf16 v[24:27], v[162:165], v[186:189], v[24:27]
	v_mfma_f32_16x16x32_bf16 v[12:15], v[154:157], v[194:197], v[12:15]
	v_mfma_f32_16x16x32_bf16 v[8:11], v[162:165], v[194:197], v[8:11]
	s_barrier
	s_add_u32 s62, s36, 0x80000
	s_addc_u32 s63, s37, 0
	s_add_i32 s61, s55, s43
	s_mov_b32 m0, s61
	s_nop 0
	global_load_lds_dwordx4 v132, s[62:63]
	s_add_i32 m0, s61, 0x2000
	s_nop 0
	global_load_lds_dwordx4 v128, s[62:63]
	s_waitcnt vmcnt(6)
	s_barrier
	v_mfma_f32_16x16x32_bf16 v[52:55], v[198:201], v[166:169], v[52:55]
	v_mfma_f32_16x16x32_bf16 v[48:51], v[206:209], v[166:169], v[48:51]
	v_mfma_f32_16x16x32_bf16 v[36:39], v[198:201], v[174:177], v[36:39]
	v_mfma_f32_16x16x32_bf16 v[32:35], v[206:209], v[174:177], v[32:35]
	v_mfma_f32_16x16x32_bf16 v[20:23], v[198:201], v[182:185], v[20:23]
	v_mfma_f32_16x16x32_bf16 v[16:19], v[206:209], v[182:185], v[16:19]
	v_mfma_f32_16x16x32_bf16 v[4:7], v[198:201], v[190:193], v[4:7]
	v_mfma_f32_16x16x32_bf16 v[0:3], v[206:209], v[190:193], v[0:3]
	v_mfma_f32_16x16x32_bf16 v[52:55], v[202:205], v[170:173], v[52:55]
	v_mfma_f32_16x16x32_bf16 v[48:51], v[210:213], v[170:173], v[48:51]
	v_mfma_f32_16x16x32_bf16 v[36:39], v[202:205], v[178:181], v[36:39]
	v_mfma_f32_16x16x32_bf16 v[32:35], v[210:213], v[178:181], v[32:35]
	v_mfma_f32_16x16x32_bf16 v[20:23], v[202:205], v[186:189], v[20:23]
	v_mfma_f32_16x16x32_bf16 v[16:19], v[210:213], v[186:189], v[16:19]
	v_mfma_f32_16x16x32_bf16 v[4:7], v[202:205], v[194:197], v[4:7]
	v_mfma_f32_16x16x32_bf16 v[0:3], v[210:213], v[194:197], v[0:3]
	s_add_i32 s61, 0, 0x18000
	s_barrier
	ds_read_b128 v[150:153], v244
	ds_read_b128 v[154:157], v244 offset:1024
	ds_read_b128 v[158:161], v244 offset:2048
	ds_read_b128 v[162:165], v244 offset:3072
	s_add_u32 s38, s38, 0x80000
	s_addc_u32 s39, s39, 0
	s_mov_b32 m0, s47
	ds_read_b128 v[166:169], v148 offset:32768
	ds_read_b128 v[170:173], v148 offset:33792
	ds_read_b128 v[174:177], v148 offset:34816
	ds_read_b128 v[178:181], v148 offset:35840
	ds_read_b128 v[182:185], v148 offset:36864
	ds_read_b128 v[186:189], v148 offset:37888
	ds_read_b128 v[190:193], v148 offset:38912
	ds_read_b128 v[194:197], v148 offset:39936
	global_load_lds_dwordx4 v134, s[38:39]
	s_mov_b32 m0, s48
	s_nop 0
	global_load_lds_dwordx4 v130, s[38:39]
	s_waitcnt lgkmcnt(8)
	s_barrier
	s_waitcnt lgkmcnt(0)
	v_mfma_f32_16x16x32_bf16 v[124:127], v[150:153], v[166:169], v[124:127]
	v_mfma_f32_16x16x32_bf16 v[120:123], v[158:161], v[166:169], v[120:123]
	v_mfma_f32_16x16x32_bf16 v[108:111], v[150:153], v[174:177], v[108:111]
	v_mfma_f32_16x16x32_bf16 v[104:107], v[158:161], v[174:177], v[104:107]
	v_mfma_f32_16x16x32_bf16 v[92:95], v[150:153], v[182:185], v[92:95]
	v_mfma_f32_16x16x32_bf16 v[88:91], v[158:161], v[182:185], v[88:91]
	v_mfma_f32_16x16x32_bf16 v[76:79], v[150:153], v[190:193], v[76:79]
	v_mfma_f32_16x16x32_bf16 v[72:75], v[158:161], v[190:193], v[72:75]
	v_mfma_f32_16x16x32_bf16 v[124:127], v[154:157], v[170:173], v[124:127]
	v_mfma_f32_16x16x32_bf16 v[120:123], v[162:165], v[170:173], v[120:123]
	v_mfma_f32_16x16x32_bf16 v[108:111], v[154:157], v[178:181], v[108:111]
	v_mfma_f32_16x16x32_bf16 v[104:107], v[162:165], v[178:181], v[104:107]
	v_mfma_f32_16x16x32_bf16 v[92:95], v[154:157], v[186:189], v[92:95]
	v_mfma_f32_16x16x32_bf16 v[88:91], v[162:165], v[186:189], v[88:91]
	v_mfma_f32_16x16x32_bf16 v[76:79], v[154:157], v[194:197], v[76:79]
	v_mfma_f32_16x16x32_bf16 v[72:75], v[162:165], v[194:197], v[72:75]
	s_barrier
	s_add_i32 s38, 0, 0x1c000
	s_add_i32 s39, s61, s43
	s_mov_b32 m0, s39
	ds_read_b128 v[198:201], v245
	ds_read_b128 v[202:205], v245 offset:1024
	ds_read_b128 v[206:209], v245 offset:2048
	ds_read_b128 v[210:213], v245 offset:3072
	global_load_lds_dwordx4 v132, s[98:99]
	s_add_i32 m0, s39, 0x2000
	s_nop 0
	global_load_lds_dwordx4 v128, s[98:99]
	s_barrier
	s_waitcnt lgkmcnt(0)
	v_mfma_f32_16x16x32_bf16 v[116:119], v[198:201], v[166:169], v[116:119]
	v_mfma_f32_16x16x32_bf16 v[112:115], v[206:209], v[166:169], v[112:115]
	v_mfma_f32_16x16x32_bf16 v[100:103], v[198:201], v[174:177], v[100:103]
	v_mfma_f32_16x16x32_bf16 v[96:99], v[206:209], v[174:177], v[96:99]
	v_mfma_f32_16x16x32_bf16 v[84:87], v[198:201], v[182:185], v[84:87]
	v_mfma_f32_16x16x32_bf16 v[80:83], v[206:209], v[182:185], v[80:83]
	v_mfma_f32_16x16x32_bf16 v[68:71], v[198:201], v[190:193], v[68:71]
	v_mfma_f32_16x16x32_bf16 v[64:67], v[206:209], v[190:193], v[64:67]
	v_mfma_f32_16x16x32_bf16 v[116:119], v[202:205], v[170:173], v[116:119]
	v_mfma_f32_16x16x32_bf16 v[112:115], v[210:213], v[170:173], v[112:115]
	v_mfma_f32_16x16x32_bf16 v[100:103], v[202:205], v[178:181], v[100:103]
	v_mfma_f32_16x16x32_bf16 v[96:99], v[210:213], v[178:181], v[96:99]
	v_mfma_f32_16x16x32_bf16 v[84:87], v[202:205], v[186:189], v[84:87]
	v_mfma_f32_16x16x32_bf16 v[80:83], v[210:213], v[186:189], v[80:83]
	v_mfma_f32_16x16x32_bf16 v[68:71], v[202:205], v[194:197], v[68:71]
	v_mfma_f32_16x16x32_bf16 v[64:67], v[210:213], v[194:197], v[64:67]
	s_mov_b32 m0, s50
	s_barrier
	ds_read_b128 v[166:169], v148 offset:49152
	ds_read_b128 v[170:173], v148 offset:50176
	ds_read_b128 v[174:177], v148 offset:51200
	ds_read_b128 v[178:181], v148 offset:52224
	ds_read_b128 v[182:185], v148 offset:53248
	ds_read_b128 v[186:189], v148 offset:54272
	ds_read_b128 v[190:193], v148 offset:55296
	ds_read_b128 v[194:197], v148 offset:56320
	global_load_lds_dwordx4 v134, s[100:101]
	s_mov_b32 m0, s51
	s_nop 0
	global_load_lds_dwordx4 v130, s[100:101]
	s_barrier
	s_waitcnt lgkmcnt(0)
	v_mfma_f32_16x16x32_bf16 v[60:63], v[150:153], v[166:169], v[60:63]
	v_mfma_f32_16x16x32_bf16 v[56:59], v[158:161], v[166:169], v[56:59]
	v_mfma_f32_16x16x32_bf16 v[44:47], v[150:153], v[174:177], v[44:47]
	v_mfma_f32_16x16x32_bf16 v[40:43], v[158:161], v[174:177], v[40:43]
	v_mfma_f32_16x16x32_bf16 v[28:31], v[150:153], v[182:185], v[28:31]
	v_mfma_f32_16x16x32_bf16 v[24:27], v[158:161], v[182:185], v[24:27]
	v_mfma_f32_16x16x32_bf16 v[12:15], v[150:153], v[190:193], v[12:15]
	v_mfma_f32_16x16x32_bf16 v[8:11], v[158:161], v[190:193], v[8:11]
	v_mfma_f32_16x16x32_bf16 v[60:63], v[154:157], v[170:173], v[60:63]
	v_mfma_f32_16x16x32_bf16 v[56:59], v[162:165], v[170:173], v[56:59]
	v_mfma_f32_16x16x32_bf16 v[44:47], v[154:157], v[178:181], v[44:47]
	v_mfma_f32_16x16x32_bf16 v[40:43], v[162:165], v[178:181], v[40:43]
	v_mfma_f32_16x16x32_bf16 v[28:31], v[154:157], v[186:189], v[28:31]
	v_mfma_f32_16x16x32_bf16 v[24:27], v[162:165], v[186:189], v[24:27]
	v_mfma_f32_16x16x32_bf16 v[12:15], v[154:157], v[194:197], v[12:15]
	v_mfma_f32_16x16x32_bf16 v[8:11], v[162:165], v[194:197], v[8:11]
	s_barrier
	s_add_u32 s36, s36, 0x80080
	s_addc_u32 s37, s37, 0
	s_add_i32 s38, s38, s43
	s_mov_b32 m0, s38
	s_nop 0
	global_load_lds_dwordx4 v132, s[36:37]
	s_add_i32 m0, s38, 0x2000
	s_nop 0
	global_load_lds_dwordx4 v128, s[36:37]
	s_waitcnt vmcnt(6)
	s_barrier
	v_mfma_f32_16x16x32_bf16 v[52:55], v[198:201], v[166:169], v[52:55]
	v_mfma_f32_16x16x32_bf16 v[48:51], v[206:209], v[166:169], v[48:51]
	v_mfma_f32_16x16x32_bf16 v[36:39], v[198:201], v[174:177], v[36:39]
	v_mfma_f32_16x16x32_bf16 v[32:35], v[206:209], v[174:177], v[32:35]
	v_mfma_f32_16x16x32_bf16 v[20:23], v[198:201], v[182:185], v[20:23]
	v_mfma_f32_16x16x32_bf16 v[16:19], v[206:209], v[182:185], v[16:19]
	v_mfma_f32_16x16x32_bf16 v[4:7], v[198:201], v[190:193], v[4:7]
	v_mfma_f32_16x16x32_bf16 v[0:3], v[206:209], v[190:193], v[0:3]
	v_mfma_f32_16x16x32_bf16 v[52:55], v[202:205], v[170:173], v[52:55]
	v_mfma_f32_16x16x32_bf16 v[48:51], v[210:213], v[170:173], v[48:51]
	v_mfma_f32_16x16x32_bf16 v[36:39], v[202:205], v[178:181], v[36:39]
	v_mfma_f32_16x16x32_bf16 v[32:35], v[210:213], v[178:181], v[32:35]
	v_mfma_f32_16x16x32_bf16 v[20:23], v[202:205], v[186:189], v[20:23]
	v_mfma_f32_16x16x32_bf16 v[16:19], v[210:213], v[186:189], v[16:19]
	v_mfma_f32_16x16x32_bf16 v[4:7], v[202:205], v[194:197], v[4:7]
	v_mfma_f32_16x16x32_bf16 v[0:3], v[210:213], v[194:197], v[0:3]
	s_add_i32 s60, s60, 2
	s_add_u32 s34, s34, 0x100
	s_addc_u32 s35, s35, 0
	s_add_u32 s29, s29, 0x100
	s_addc_u32 s59, s59, 0
	s_cmp_gt_u32 s60, 29
	s_barrier
	s_cbranch_scc0 .LBB0_1203
	v_pk_add_f32 v[124:125], v[124:125], 0 op_sel_hi:[1,0]
	v_pk_add_f32 v[126:127], v[126:127], 0 op_sel_hi:[1,0]
	v_mul_f32_e32 v151, 0xbfb8aa3b, v124
	v_exp_f32_e32 v151, v151
	v_mul_f32_e32 v154, 0xbfb8aa3b, v125
	v_exp_f32_e32 v155, v154
	v_pk_add_f32 v[116:117], v[116:117], 0 op_sel_hi:[1,0]
	v_add_f32_e32 v151, 1.0, v151
	v_rcp_f32_e32 v154, v151
	v_add_f32_e32 v151, 1.0, v155
	v_mul_f32_e32 v155, 0xbfb8aa3b, v126
	v_exp_f32_e32 v156, v155
	v_mul_f32_e32 v155, 0xbfb8aa3b, v127
	v_exp_f32_e32 v157, v155
	v_rcp_f32_e32 v155, v151
	v_add_f32_e32 v151, 1.0, v156
	v_rcp_f32_e32 v156, v151
	v_add_f32_e32 v151, 1.0, v157
	v_rcp_f32_e32 v157, v151
	v_pk_mul_f32 v[124:125], v[124:125], v[154:155]
	v_pk_add_f32 v[120:121], v[120:121], 0 op_sel_hi:[1,0]
	v_pk_mul_f32 v[116:117], v[124:125], v[116:117]
	v_pk_mul_f32 v[124:125], v[126:127], v[156:157]
	v_mul_f32_e32 v126, 0xbfb8aa3b, v120
	v_exp_f32_e32 v126, v126
	v_pk_add_f32 v[118:119], v[118:119], 0 op_sel_hi:[1,0]
	v_pk_add_f32 v[122:123], v[122:123], 0 op_sel_hi:[1,0]
	v_pk_mul_f32 v[118:119], v[124:125], v[118:119]
	v_mul_f32_e32 v124, 0xbfb8aa3b, v121
	v_exp_f32_e32 v125, v124
	v_add_f32_e32 v124, 1.0, v126
	v_mul_f32_e32 v126, 0xbfb8aa3b, v122
	v_mul_f32_e32 v127, 0xbfb8aa3b, v123
	v_exp_f32_e32 v126, v126
	v_exp_f32_e32 v127, v127
	v_add_f32_e32 v125, 1.0, v125
	v_rcp_f32_e32 v124, v124
	v_rcp_f32_e32 v125, v125
	v_add_f32_e32 v126, 1.0, v126
	v_add_f32_e32 v127, 1.0, v127
	v_rcp_f32_e32 v126, v126
	v_rcp_f32_e32 v127, v127
	v_pk_add_f32 v[112:113], v[112:113], 0 op_sel_hi:[1,0]
	v_pk_mul_f32 v[120:121], v[120:121], v[124:125]
	v_lshl_or_b32 v152, s57, 7, v146
	v_pk_mul_f32 v[112:113], v[120:121], v[112:113]
	v_pk_add_f32 v[114:115], v[114:115], 0 op_sel_hi:[1,0]
	v_pk_mul_f32 v[120:121], v[122:123], v[126:127]
	v_lshl_add_u32 v150, s30, 8, v142
	v_ashrrev_i32_e32 v153, 31, v152
	v_pk_mul_f32 v[114:115], v[120:121], v[114:115]
	v_cvt_pk_bf16_f32 v116, v116, v117
	v_cvt_pk_bf16_f32 v117, v118, v119
	v_cvt_pk_bf16_f32 v118, v112, v113
	v_mov_b64_e32 v[112:113], s[6:7]
	v_cvt_pk_bf16_f32 v119, v114, v115
	v_mad_i64_i32 v[120:121], s[28:29], v150, s56, v[112:113]
	v_lshlrev_b64 v[114:115], 1, v[152:153]
	v_lshl_add_u64 v[120:121], v[120:121], 0, v[114:115]
	v_pk_add_f32 v[108:109], v[108:109], 0 op_sel_hi:[1,0]
	global_store_dwordx4 v[120:121], v[116:119], off sc0 sc1
	v_mul_f32_e32 v122, 0xbfb8aa3b, v108
	v_pk_add_f32 v[110:111], v[110:111], 0 op_sel_hi:[1,0]
	v_mul_f32_e32 v116, 0xbfb8aa3b, v109
	v_exp_f32_e32 v122, v122
	v_exp_f32_e32 v117, v116
	v_mul_f32_e32 v118, 0xbfb8aa3b, v110
	v_mul_f32_e32 v119, 0xbfb8aa3b, v111
	v_exp_f32_e32 v118, v118
	v_exp_f32_e32 v119, v119
	v_add_f32_e32 v116, 1.0, v122
	v_add_f32_e32 v117, 1.0, v117
	v_rcp_f32_e32 v116, v116
	v_rcp_f32_e32 v117, v117
	v_add_f32_e32 v118, 1.0, v118
	v_add_f32_e32 v119, 1.0, v119
	v_rcp_f32_e32 v118, v118
	v_rcp_f32_e32 v119, v119
	v_pk_add_f32 v[100:101], v[100:101], 0 op_sel_hi:[1,0]
	v_pk_mul_f32 v[108:109], v[108:109], v[116:117]
	v_pk_add_f32 v[104:105], v[104:105], 0 op_sel_hi:[1,0]
	v_pk_mul_f32 v[100:101], v[108:109], v[100:101]
	v_pk_mul_f32 v[108:109], v[110:111], v[118:119]
	v_mul_f32_e32 v110, 0xbfb8aa3b, v104
	v_exp_f32_e32 v110, v110
	v_pk_add_f32 v[102:103], v[102:103], 0 op_sel_hi:[1,0]
	v_pk_add_f32 v[106:107], v[106:107], 0 op_sel_hi:[1,0]
	v_pk_mul_f32 v[102:103], v[108:109], v[102:103]
	v_mul_f32_e32 v108, 0xbfb8aa3b, v105
	v_exp_f32_e32 v109, v108
	v_add_f32_e32 v108, 1.0, v110
	v_mul_f32_e32 v110, 0xbfb8aa3b, v106
	v_mul_f32_e32 v111, 0xbfb8aa3b, v107
	v_exp_f32_e32 v110, v110
	v_exp_f32_e32 v111, v111
	v_add_f32_e32 v109, 1.0, v109
	v_rcp_f32_e32 v108, v108
	v_rcp_f32_e32 v109, v109
	v_add_f32_e32 v110, 1.0, v110
	v_add_f32_e32 v111, 1.0, v111
	v_rcp_f32_e32 v110, v110
	v_rcp_f32_e32 v111, v111
	v_pk_add_f32 v[96:97], v[96:97], 0 op_sel_hi:[1,0]
	v_pk_mul_f32 v[104:105], v[104:105], v[108:109]
	v_or_b32_e32 v108, 16, v150
	v_pk_mul_f32 v[104:105], v[104:105], v[96:97]
	v_pk_add_f32 v[96:97], v[98:99], 0 op_sel_hi:[1,0]
	v_pk_mul_f32 v[98:99], v[106:107], v[110:111]
	v_pk_add_f32 v[92:93], v[92:93], 0 op_sel_hi:[1,0]
	v_pk_mul_f32 v[106:107], v[98:99], v[96:97]
	v_cvt_pk_bf16_f32 v96, v100, v101
	v_mad_i64_i32 v[100:101], s[28:29], v108, s56, v[112:113]
	v_cvt_pk_bf16_f32 v97, v102, v103
	v_cvt_pk_bf16_f32 v98, v104, v105
	v_cvt_pk_bf16_f32 v99, v106, v107
	v_lshl_add_u64 v[100:101], v[100:101], 0, v[114:115]
	v_mul_f32_e32 v102, 0xbfb8aa3b, v92
	global_store_dwordx4 v[100:101], v[96:99], off sc0 sc1
	v_pk_add_f32 v[94:95], v[94:95], 0 op_sel_hi:[1,0]
	v_exp_f32_e32 v102, v102
	v_mul_f32_e32 v96, 0xbfb8aa3b, v93
	v_exp_f32_e32 v97, v96
	v_mul_f32_e32 v98, 0xbfb8aa3b, v94
	v_mul_f32_e32 v99, 0xbfb8aa3b, v95
	v_exp_f32_e32 v98, v98
	v_exp_f32_e32 v99, v99
	v_add_f32_e32 v96, 1.0, v102
	v_add_f32_e32 v97, 1.0, v97
	v_rcp_f32_e32 v96, v96
	v_rcp_f32_e32 v97, v97
	v_add_f32_e32 v98, 1.0, v98
	v_add_f32_e32 v99, 1.0, v99
	v_rcp_f32_e32 v98, v98
	v_rcp_f32_e32 v99, v99
	v_pk_add_f32 v[84:85], v[84:85], 0 op_sel_hi:[1,0]
	v_pk_mul_f32 v[92:93], v[92:93], v[96:97]
	v_pk_add_f32 v[88:89], v[88:89], 0 op_sel_hi:[1,0]
	v_pk_mul_f32 v[84:85], v[92:93], v[84:85]
	v_pk_mul_f32 v[92:93], v[94:95], v[98:99]
	v_mul_f32_e32 v94, 0xbfb8aa3b, v88
	v_exp_f32_e32 v94, v94
	v_pk_add_f32 v[86:87], v[86:87], 0 op_sel_hi:[1,0]
	v_pk_add_f32 v[90:91], v[90:91], 0 op_sel_hi:[1,0]
	v_pk_mul_f32 v[86:87], v[92:93], v[86:87]
	v_mul_f32_e32 v92, 0xbfb8aa3b, v89
	v_exp_f32_e32 v93, v92
	v_add_f32_e32 v92, 1.0, v94
	v_mul_f32_e32 v94, 0xbfb8aa3b, v90
	v_mul_f32_e32 v95, 0xbfb8aa3b, v91
	v_exp_f32_e32 v94, v94
	v_exp_f32_e32 v95, v95
	v_add_f32_e32 v93, 1.0, v93
	v_rcp_f32_e32 v92, v92
	v_rcp_f32_e32 v93, v93
	v_add_f32_e32 v94, 1.0, v94
	v_add_f32_e32 v95, 1.0, v95
	v_rcp_f32_e32 v94, v94
	v_rcp_f32_e32 v95, v95
	v_pk_add_f32 v[80:81], v[80:81], 0 op_sel_hi:[1,0]
	v_pk_mul_f32 v[88:89], v[88:89], v[92:93]
	v_or_b32_e32 v92, 32, v150
	v_pk_mul_f32 v[88:89], v[88:89], v[80:81]
	v_pk_add_f32 v[80:81], v[82:83], 0 op_sel_hi:[1,0]
	v_pk_mul_f32 v[82:83], v[90:91], v[94:95]
	v_pk_add_f32 v[76:77], v[76:77], 0 op_sel_hi:[1,0]
	v_pk_mul_f32 v[90:91], v[82:83], v[80:81]
	v_cvt_pk_bf16_f32 v80, v84, v85
	v_mad_i64_i32 v[84:85], s[28:29], v92, s56, v[112:113]
	v_cvt_pk_bf16_f32 v81, v86, v87
	v_cvt_pk_bf16_f32 v82, v88, v89
	v_cvt_pk_bf16_f32 v83, v90, v91
	v_lshl_add_u64 v[84:85], v[84:85], 0, v[114:115]
	v_mul_f32_e32 v86, 0xbfb8aa3b, v76
	global_store_dwordx4 v[84:85], v[80:83], off sc0 sc1
	v_pk_add_f32 v[78:79], v[78:79], 0 op_sel_hi:[1,0]
	v_exp_f32_e32 v86, v86
	v_mul_f32_e32 v80, 0xbfb8aa3b, v77
	v_exp_f32_e32 v81, v80
	v_mul_f32_e32 v82, 0xbfb8aa3b, v78
	v_mul_f32_e32 v83, 0xbfb8aa3b, v79
	v_exp_f32_e32 v82, v82
	v_exp_f32_e32 v83, v83
	v_add_f32_e32 v80, 1.0, v86
	v_add_f32_e32 v81, 1.0, v81
	v_rcp_f32_e32 v80, v80
	v_rcp_f32_e32 v81, v81
	v_add_f32_e32 v82, 1.0, v82
	v_add_f32_e32 v83, 1.0, v83
	v_rcp_f32_e32 v82, v82
	v_rcp_f32_e32 v83, v83
	v_pk_add_f32 v[68:69], v[68:69], 0 op_sel_hi:[1,0]
	v_pk_mul_f32 v[76:77], v[76:77], v[80:81]
	v_pk_add_f32 v[72:73], v[72:73], 0 op_sel_hi:[1,0]
	v_pk_mul_f32 v[68:69], v[76:77], v[68:69]
	v_pk_mul_f32 v[76:77], v[78:79], v[82:83]
	v_mul_f32_e32 v78, 0xbfb8aa3b, v72
	v_exp_f32_e32 v78, v78
	v_pk_add_f32 v[70:71], v[70:71], 0 op_sel_hi:[1,0]
	v_pk_add_f32 v[74:75], v[74:75], 0 op_sel_hi:[1,0]
	v_pk_mul_f32 v[70:71], v[76:77], v[70:71]
	v_mul_f32_e32 v76, 0xbfb8aa3b, v73
	v_exp_f32_e32 v77, v76
	v_add_f32_e32 v76, 1.0, v78
	v_mul_f32_e32 v78, 0xbfb8aa3b, v74
	v_mul_f32_e32 v79, 0xbfb8aa3b, v75
	v_exp_f32_e32 v78, v78
	v_exp_f32_e32 v79, v79
	v_add_f32_e32 v77, 1.0, v77
	v_rcp_f32_e32 v76, v76
	v_rcp_f32_e32 v77, v77
	v_add_f32_e32 v78, 1.0, v78
	v_add_f32_e32 v79, 1.0, v79
	v_rcp_f32_e32 v78, v78
	v_rcp_f32_e32 v79, v79
	v_pk_add_f32 v[64:65], v[64:65], 0 op_sel_hi:[1,0]
	v_pk_mul_f32 v[72:73], v[72:73], v[76:77]
	v_or_b32_e32 v76, 48, v150
	v_pk_mul_f32 v[72:73], v[72:73], v[64:65]
	v_pk_add_f32 v[64:65], v[66:67], 0 op_sel_hi:[1,0]
	v_pk_mul_f32 v[66:67], v[74:75], v[78:79]
	v_pk_add_f32 v[60:61], v[60:61], 0 op_sel_hi:[1,0]
	v_pk_mul_f32 v[74:75], v[66:67], v[64:65]
	v_cvt_pk_bf16_f32 v64, v68, v69
	v_mad_i64_i32 v[68:69], s[28:29], v76, s56, v[112:113]
	v_cvt_pk_bf16_f32 v65, v70, v71
	v_cvt_pk_bf16_f32 v66, v72, v73
	v_cvt_pk_bf16_f32 v67, v74, v75
	v_lshl_add_u64 v[68:69], v[68:69], 0, v[114:115]
	global_store_dwordx4 v[68:69], v[64:67], off sc0 sc1
	v_pk_add_f32 v[62:63], v[62:63], 0 op_sel_hi:[1,0]
	v_pk_add_f32 v[52:53], v[52:53], 0 op_sel_hi:[1,0]
	v_mul_f32_e32 v64, 0xbfb8aa3b, v60
	v_mul_f32_e32 v65, 0xbfb8aa3b, v61
	v_exp_f32_e32 v64, v64
	v_exp_f32_e32 v65, v65
	v_mul_f32_e32 v66, 0xbfb8aa3b, v62
	v_mul_f32_e32 v67, 0xbfb8aa3b, v63
	v_exp_f32_e32 v66, v66
	v_exp_f32_e32 v67, v67
	v_add_f32_e32 v64, 1.0, v64
	v_add_f32_e32 v65, 1.0, v65
	v_rcp_f32_e32 v64, v64
	v_rcp_f32_e32 v65, v65
	v_add_f32_e32 v66, 1.0, v66
	v_add_f32_e32 v67, 1.0, v67
	v_rcp_f32_e32 v66, v66
	v_rcp_f32_e32 v67, v67
	v_pk_mul_f32 v[60:61], v[60:61], v[64:65]
	v_pk_add_f32 v[56:57], v[56:57], 0 op_sel_hi:[1,0]
	v_pk_mul_f32 v[52:53], v[60:61], v[52:53]
	v_pk_mul_f32 v[60:61], v[62:63], v[66:67]
	v_mul_f32_e32 v62, 0xbfb8aa3b, v56
	v_exp_f32_e32 v62, v62
	v_pk_add_f32 v[54:55], v[54:55], 0 op_sel_hi:[1,0]
	v_pk_add_f32 v[58:59], v[58:59], 0 op_sel_hi:[1,0]
	v_pk_mul_f32 v[54:55], v[60:61], v[54:55]
	v_mul_f32_e32 v60, 0xbfb8aa3b, v57
	v_exp_f32_e32 v61, v60
	v_add_f32_e32 v60, 1.0, v62
	v_mul_f32_e32 v62, 0xbfb8aa3b, v58
	v_mul_f32_e32 v63, 0xbfb8aa3b, v59
	v_exp_f32_e32 v62, v62
	v_exp_f32_e32 v63, v63
	v_add_f32_e32 v61, 1.0, v61
	v_rcp_f32_e32 v60, v60
	v_rcp_f32_e32 v61, v61
	v_add_f32_e32 v62, 1.0, v62
	v_add_f32_e32 v63, 1.0, v63
	v_rcp_f32_e32 v62, v62
	v_rcp_f32_e32 v63, v63
	v_pk_add_f32 v[48:49], v[48:49], 0 op_sel_hi:[1,0]
	v_pk_mul_f32 v[56:57], v[56:57], v[60:61]
	v_add_u32_e32 v68, 0x80, v150
	v_pk_mul_f32 v[56:57], v[56:57], v[48:49]
	v_pk_add_f32 v[48:49], v[50:51], 0 op_sel_hi:[1,0]
	v_pk_mul_f32 v[50:51], v[58:59], v[62:63]
	v_pk_add_f32 v[44:45], v[44:45], 0 op_sel_hi:[1,0]
	v_pk_mul_f32 v[58:59], v[50:51], v[48:49]
	v_cvt_pk_bf16_f32 v48, v52, v53
	v_mad_i64_i32 v[52:53], s[28:29], v68, s56, v[112:113]
	v_cvt_pk_bf16_f32 v49, v54, v55
	v_cvt_pk_bf16_f32 v50, v56, v57
	v_cvt_pk_bf16_f32 v51, v58, v59
	v_lshl_add_u64 v[52:53], v[52:53], 0, v[114:115]
	v_mul_f32_e32 v54, 0xbfb8aa3b, v44
	global_store_dwordx4 v[52:53], v[48:51], off sc0 sc1
	v_pk_add_f32 v[46:47], v[46:47], 0 op_sel_hi:[1,0]
	v_exp_f32_e32 v54, v54
	v_mul_f32_e32 v48, 0xbfb8aa3b, v45
	v_exp_f32_e32 v49, v48
	v_mul_f32_e32 v50, 0xbfb8aa3b, v46
	v_mul_f32_e32 v51, 0xbfb8aa3b, v47
	v_exp_f32_e32 v50, v50
	v_exp_f32_e32 v51, v51
	v_add_f32_e32 v48, 1.0, v54
	v_add_f32_e32 v49, 1.0, v49
	v_rcp_f32_e32 v48, v48
	v_rcp_f32_e32 v49, v49
	v_add_f32_e32 v50, 1.0, v50
	v_add_f32_e32 v51, 1.0, v51
	v_rcp_f32_e32 v50, v50
	v_rcp_f32_e32 v51, v51
	v_pk_add_f32 v[36:37], v[36:37], 0 op_sel_hi:[1,0]
	v_pk_mul_f32 v[44:45], v[44:45], v[48:49]
	v_pk_add_f32 v[40:41], v[40:41], 0 op_sel_hi:[1,0]
	v_pk_mul_f32 v[36:37], v[44:45], v[36:37]
	v_pk_mul_f32 v[44:45], v[46:47], v[50:51]
	v_mul_f32_e32 v46, 0xbfb8aa3b, v40
	v_exp_f32_e32 v46, v46
	v_pk_add_f32 v[38:39], v[38:39], 0 op_sel_hi:[1,0]
	v_pk_add_f32 v[42:43], v[42:43], 0 op_sel_hi:[1,0]
	v_pk_mul_f32 v[38:39], v[44:45], v[38:39]
	v_mul_f32_e32 v44, 0xbfb8aa3b, v41
	v_exp_f32_e32 v45, v44
	v_add_f32_e32 v44, 1.0, v46
	v_mul_f32_e32 v46, 0xbfb8aa3b, v42
	v_mul_f32_e32 v47, 0xbfb8aa3b, v43
	v_exp_f32_e32 v46, v46
	v_exp_f32_e32 v47, v47
	v_add_f32_e32 v45, 1.0, v45
	v_rcp_f32_e32 v44, v44
	v_rcp_f32_e32 v45, v45
	v_add_f32_e32 v46, 1.0, v46
	v_add_f32_e32 v47, 1.0, v47
	v_rcp_f32_e32 v46, v46
	v_rcp_f32_e32 v47, v47
	v_pk_add_f32 v[32:33], v[32:33], 0 op_sel_hi:[1,0]
	v_pk_mul_f32 v[40:41], v[40:41], v[44:45]
	v_add_u32_e32 v44, 0x90, v150
	v_pk_mul_f32 v[40:41], v[40:41], v[32:33]
	v_pk_add_f32 v[32:33], v[34:35], 0 op_sel_hi:[1,0]
	v_pk_mul_f32 v[34:35], v[42:43], v[46:47]
	v_pk_add_f32 v[28:29], v[28:29], 0 op_sel_hi:[1,0]
	v_pk_mul_f32 v[42:43], v[34:35], v[32:33]
	v_cvt_pk_bf16_f32 v32, v36, v37
	v_mad_i64_i32 v[36:37], s[28:29], v44, s56, v[112:113]
	v_cvt_pk_bf16_f32 v33, v38, v39
	v_cvt_pk_bf16_f32 v34, v40, v41
	v_cvt_pk_bf16_f32 v35, v42, v43
	v_lshl_add_u64 v[36:37], v[36:37], 0, v[114:115]
	v_mul_f32_e32 v38, 0xbfb8aa3b, v28
	global_store_dwordx4 v[36:37], v[32:35], off sc0 sc1
	v_pk_add_f32 v[30:31], v[30:31], 0 op_sel_hi:[1,0]
	v_exp_f32_e32 v38, v38
	v_mul_f32_e32 v32, 0xbfb8aa3b, v29
	v_exp_f32_e32 v33, v32
	v_mul_f32_e32 v34, 0xbfb8aa3b, v30
	v_mul_f32_e32 v35, 0xbfb8aa3b, v31
	v_exp_f32_e32 v34, v34
	v_exp_f32_e32 v35, v35
	v_add_f32_e32 v32, 1.0, v38
	v_add_f32_e32 v33, 1.0, v33
	v_rcp_f32_e32 v32, v32
	v_rcp_f32_e32 v33, v33
	v_add_f32_e32 v34, 1.0, v34
	v_add_f32_e32 v35, 1.0, v35
	v_rcp_f32_e32 v34, v34
	v_rcp_f32_e32 v35, v35
	v_pk_add_f32 v[20:21], v[20:21], 0 op_sel_hi:[1,0]
	v_pk_mul_f32 v[28:29], v[28:29], v[32:33]
	v_pk_add_f32 v[24:25], v[24:25], 0 op_sel_hi:[1,0]
	v_pk_mul_f32 v[20:21], v[28:29], v[20:21]
	v_pk_mul_f32 v[28:29], v[30:31], v[34:35]
	v_mul_f32_e32 v30, 0xbfb8aa3b, v24
	v_exp_f32_e32 v30, v30
	v_pk_add_f32 v[22:23], v[22:23], 0 op_sel_hi:[1,0]
	v_pk_add_f32 v[26:27], v[26:27], 0 op_sel_hi:[1,0]
	v_pk_mul_f32 v[22:23], v[28:29], v[22:23]
	v_mul_f32_e32 v28, 0xbfb8aa3b, v25
	v_exp_f32_e32 v29, v28
	v_add_f32_e32 v28, 1.0, v30
	v_mul_f32_e32 v30, 0xbfb8aa3b, v26
	v_mul_f32_e32 v31, 0xbfb8aa3b, v27
	v_exp_f32_e32 v30, v30
	v_exp_f32_e32 v31, v31
	v_add_f32_e32 v29, 1.0, v29
	v_rcp_f32_e32 v28, v28
	v_rcp_f32_e32 v29, v29
	v_add_f32_e32 v30, 1.0, v30
	v_add_f32_e32 v31, 1.0, v31
	v_rcp_f32_e32 v30, v30
	v_rcp_f32_e32 v31, v31
	v_pk_add_f32 v[16:17], v[16:17], 0 op_sel_hi:[1,0]
	v_pk_mul_f32 v[24:25], v[24:25], v[28:29]
	v_add_u32_e32 v28, 0xa0, v150
	v_pk_mul_f32 v[24:25], v[24:25], v[16:17]
	v_pk_add_f32 v[16:17], v[18:19], 0 op_sel_hi:[1,0]
	v_pk_mul_f32 v[18:19], v[26:27], v[30:31]
	v_pk_add_f32 v[12:13], v[12:13], 0 op_sel_hi:[1,0]
	v_pk_mul_f32 v[26:27], v[18:19], v[16:17]
	v_cvt_pk_bf16_f32 v16, v20, v21
	v_mad_i64_i32 v[20:21], s[28:29], v28, s56, v[112:113]
	v_cvt_pk_bf16_f32 v17, v22, v23
	v_cvt_pk_bf16_f32 v18, v24, v25
	v_cvt_pk_bf16_f32 v19, v26, v27
	v_lshl_add_u64 v[20:21], v[20:21], 0, v[114:115]
	v_mul_f32_e32 v22, 0xbfb8aa3b, v12
	global_store_dwordx4 v[20:21], v[16:19], off sc0 sc1
	v_pk_add_f32 v[14:15], v[14:15], 0 op_sel_hi:[1,0]
	v_exp_f32_e32 v22, v22
	v_mul_f32_e32 v16, 0xbfb8aa3b, v13
	v_exp_f32_e32 v17, v16
	v_mul_f32_e32 v18, 0xbfb8aa3b, v14
	v_mul_f32_e32 v19, 0xbfb8aa3b, v15
	v_exp_f32_e32 v18, v18
	v_exp_f32_e32 v19, v19
	v_add_f32_e32 v16, 1.0, v22
	v_add_f32_e32 v17, 1.0, v17
	v_rcp_f32_e32 v16, v16
	v_rcp_f32_e32 v17, v17
	v_add_f32_e32 v18, 1.0, v18
	v_add_f32_e32 v19, 1.0, v19
	v_rcp_f32_e32 v18, v18
	v_rcp_f32_e32 v19, v19
	v_pk_add_f32 v[4:5], v[4:5], 0 op_sel_hi:[1,0]
	v_pk_mul_f32 v[12:13], v[12:13], v[16:17]
	v_pk_add_f32 v[8:9], v[8:9], 0 op_sel_hi:[1,0]
	v_pk_mul_f32 v[4:5], v[12:13], v[4:5]
	v_pk_mul_f32 v[12:13], v[14:15], v[18:19]
	v_mul_f32_e32 v14, 0xbfb8aa3b, v8
	v_exp_f32_e32 v14, v14
	v_pk_add_f32 v[6:7], v[6:7], 0 op_sel_hi:[1,0]
	v_pk_add_f32 v[10:11], v[10:11], 0 op_sel_hi:[1,0]
	v_pk_mul_f32 v[6:7], v[12:13], v[6:7]
	v_mul_f32_e32 v12, 0xbfb8aa3b, v9
	v_exp_f32_e32 v13, v12
	v_add_f32_e32 v12, 1.0, v14
	v_mul_f32_e32 v14, 0xbfb8aa3b, v10
	v_mul_f32_e32 v15, 0xbfb8aa3b, v11
	v_exp_f32_e32 v14, v14
	v_exp_f32_e32 v15, v15
	v_add_f32_e32 v13, 1.0, v13
	v_rcp_f32_e32 v12, v12
	v_rcp_f32_e32 v13, v13
	v_add_f32_e32 v14, 1.0, v14
	v_add_f32_e32 v15, 1.0, v15
	v_rcp_f32_e32 v14, v14
	v_rcp_f32_e32 v15, v15
	v_pk_add_f32 v[0:1], v[0:1], 0 op_sel_hi:[1,0]
	v_pk_mul_f32 v[8:9], v[8:9], v[12:13]
	v_add_u32_e32 v12, 0xb0, v150
	v_pk_mul_f32 v[8:9], v[8:9], v[0:1]
	v_pk_add_f32 v[0:1], v[2:3], 0 op_sel_hi:[1,0]
	v_pk_mul_f32 v[2:3], v[10:11], v[14:15]
	s_and_b64 vcc, exec, s[16:17]
	v_pk_mul_f32 v[10:11], v[2:3], v[0:1]
	v_cvt_pk_bf16_f32 v0, v4, v5
	v_mad_i64_i32 v[4:5], s[28:29], v12, s56, v[112:113]
	v_cvt_pk_bf16_f32 v1, v6, v7
	v_cvt_pk_bf16_f32 v2, v8, v9
	v_cvt_pk_bf16_f32 v3, v10, v11
	v_lshl_add_u64 v[4:5], v[4:5], 0, v[114:115]
	s_mov_b32 s57, s10
	s_mov_b32 s30, s12
	s_mov_b64 s[36:37], s[18:19]
	s_mov_b64 s[34:35], s[14:15]
	global_store_dwordx4 v[4:5], v[0:3], off sc0 sc1
	s_cbranch_vccz .LBB0_1198
	s_branch .LBB0_1206

.LBB0_1284:
	s_add_u32 s36, s36, 0x160080
	s_addc_u32 s37, s37, 0
	s_add_u32 s28, s38, 0x100
	s_addc_u32 s29, s39, 0
	s_mov_b32 s68, -2
	v_add_u32_e32 v244, 0x18000, v167
	v_add_u32_e32 v245, 0x1c000, v167
	ds_read_b128 v[128:131], v169
	ds_read_b128 v[132:135], v169 offset:1024
	ds_read_b128 v[136:139], v169 offset:2048
	ds_read_b128 v[140:143], v169 offset:3072
	s_add_u32 s38, s36, 0xffea0080
	s_addc_u32 s39, s37, -1
	s_cmpk_eq_i32 s68, 0x54
	s_cselect_b32 s41, s35, s39
	s_cselect_b32 s40, s34, s38
	s_cselect_b32 s39, s1, s29
	s_cselect_b32 s38, s0, s28
	s_add_i32 m0, s47, 0xc000
	ds_read_b128 v[156:159], v170
	ds_read_b128 v[160:163], v170 offset:1024
	ds_read_b128 v[172:175], v170 offset:2048
	ds_read_b128 v[176:179], v170 offset:3072
	ds_read_b128 v[180:183], v170 offset:4096
	ds_read_b128 v[184:187], v170 offset:5120
	ds_read_b128 v[188:191], v170 offset:6144
	ds_read_b128 v[192:195], v170 offset:7168
	global_load_lds_dwordx4 v150, s[36:37]
	s_add_i32 m0, s47, 0xe000
	s_nop 0
	global_load_lds_dwordx4 v152, s[36:37]
	s_waitcnt lgkmcnt(8)
	s_barrier
	s_waitcnt lgkmcnt(0)
	v_mfma_f32_16x16x32_bf16 v[124:127], v[128:131], v[156:159], 0
	v_mfma_f32_16x16x32_bf16 v[120:123], v[136:139], v[156:159], 0
	v_mfma_f32_16x16x32_bf16 v[116:119], v[128:131], v[172:175], 0
	v_mfma_f32_16x16x32_bf16 v[104:107], v[136:139], v[172:175], 0
	v_mfma_f32_16x16x32_bf16 v[92:95], v[128:131], v[180:183], 0
	v_mfma_f32_16x16x32_bf16 v[88:91], v[136:139], v[180:183], 0
	v_mfma_f32_16x16x32_bf16 v[76:79], v[128:131], v[188:191], 0
	v_mfma_f32_16x16x32_bf16 v[72:75], v[136:139], v[188:191], 0
	v_mfma_f32_16x16x32_bf16 v[124:127], v[132:135], v[160:163], v[124:127]
	v_mfma_f32_16x16x32_bf16 v[120:123], v[140:143], v[160:163], v[120:123]
	v_mfma_f32_16x16x32_bf16 v[116:119], v[132:135], v[176:179], v[116:119]
	v_mfma_f32_16x16x32_bf16 v[104:107], v[140:143], v[176:179], v[104:107]
	v_mfma_f32_16x16x32_bf16 v[92:95], v[132:135], v[184:187], v[92:95]
	v_mfma_f32_16x16x32_bf16 v[88:91], v[140:143], v[184:187], v[88:91]
	v_mfma_f32_16x16x32_bf16 v[76:79], v[132:135], v[192:195], v[76:79]
	v_mfma_f32_16x16x32_bf16 v[72:75], v[140:143], v[192:195], v[72:75]
	s_barrier
	s_add_i32 s69, s58, s46
	s_add_u32 s98, s38, s10
	s_addc_u32 s99, s39, s11
	s_mov_b32 m0, s69
	ds_read_b128 v[196:199], v171
	ds_read_b128 v[200:203], v171 offset:1024
	ds_read_b128 v[204:207], v171 offset:2048
	ds_read_b128 v[208:211], v171 offset:3072
	global_load_lds_dwordx4 v146, s[38:39]
	s_add_i32 m0, s69, 0x2000
	s_nop 0
	global_load_lds_dwordx4 v148, s[38:39]
	s_barrier
	s_waitcnt lgkmcnt(0)
	v_mfma_f32_16x16x32_bf16 v[112:115], v[196:199], v[156:159], 0
	v_mfma_f32_16x16x32_bf16 v[108:111], v[204:207], v[156:159], 0
	v_mfma_f32_16x16x32_bf16 v[100:103], v[196:199], v[172:175], 0
	v_mfma_f32_16x16x32_bf16 v[96:99], v[204:207], v[172:175], 0
	v_mfma_f32_16x16x32_bf16 v[84:87], v[196:199], v[180:183], 0
	v_mfma_f32_16x16x32_bf16 v[80:83], v[204:207], v[180:183], 0
	v_mfma_f32_16x16x32_bf16 v[68:71], v[196:199], v[188:191], 0
	v_mfma_f32_16x16x32_bf16 v[64:67], v[204:207], v[188:191], 0
	v_mfma_f32_16x16x32_bf16 v[112:115], v[200:203], v[160:163], v[112:115]
	v_mfma_f32_16x16x32_bf16 v[108:111], v[208:211], v[160:163], v[108:111]
	v_mfma_f32_16x16x32_bf16 v[100:103], v[200:203], v[176:179], v[100:103]
	v_mfma_f32_16x16x32_bf16 v[96:99], v[208:211], v[176:179], v[96:99]
	v_mfma_f32_16x16x32_bf16 v[84:87], v[200:203], v[184:187], v[84:87]
	v_mfma_f32_16x16x32_bf16 v[80:83], v[208:211], v[184:187], v[80:83]
	v_mfma_f32_16x16x32_bf16 v[68:71], v[200:203], v[192:195], v[68:71]
	v_mfma_f32_16x16x32_bf16 v[64:67], v[208:211], v[192:195], v[64:67]
	s_mov_b32 m0, s47
	s_add_u32 s100, s40, s10
	s_addc_u32 s101, s41, s11
	s_barrier
	ds_read_b128 v[156:159], v170 offset:16384
	ds_read_b128 v[160:163], v170 offset:17408
	ds_read_b128 v[172:175], v170 offset:18432
	ds_read_b128 v[176:179], v170 offset:19456
	ds_read_b128 v[180:183], v170 offset:20480
	ds_read_b128 v[184:187], v170 offset:21504
	ds_read_b128 v[188:191], v170 offset:22528
	ds_read_b128 v[192:195], v170 offset:23552
	global_load_lds_dwordx4 v146, s[40:41]
	s_mov_b32 m0, s48
	s_nop 0
	global_load_lds_dwordx4 v148, s[40:41]
	s_barrier
	s_waitcnt lgkmcnt(0)
	v_mfma_f32_16x16x32_bf16 v[60:63], v[128:131], v[156:159], 0
	v_mfma_f32_16x16x32_bf16 v[56:59], v[136:139], v[156:159], 0
	v_mfma_f32_16x16x32_bf16 v[44:47], v[128:131], v[172:175], 0
	v_mfma_f32_16x16x32_bf16 v[40:43], v[136:139], v[172:175], 0
	v_mfma_f32_16x16x32_bf16 v[36:39], v[128:131], v[180:183], 0
	v_mfma_f32_16x16x32_bf16 v[28:31], v[136:139], v[180:183], 0
	v_mfma_f32_16x16x32_bf16 v[20:23], v[128:131], v[188:191], 0
	v_mfma_f32_16x16x32_bf16 v[12:15], v[136:139], v[188:191], 0
	v_mfma_f32_16x16x32_bf16 v[60:63], v[132:135], v[160:163], v[60:63]
	v_mfma_f32_16x16x32_bf16 v[56:59], v[140:143], v[160:163], v[56:59]
	v_mfma_f32_16x16x32_bf16 v[44:47], v[132:135], v[176:179], v[44:47]
	v_mfma_f32_16x16x32_bf16 v[40:43], v[140:143], v[176:179], v[40:43]
	v_mfma_f32_16x16x32_bf16 v[36:39], v[132:135], v[184:187], v[36:39]
	v_mfma_f32_16x16x32_bf16 v[28:31], v[140:143], v[184:187], v[28:31]
	v_mfma_f32_16x16x32_bf16 v[20:23], v[132:135], v[192:195], v[20:23]
	v_mfma_f32_16x16x32_bf16 v[12:15], v[140:143], v[192:195], v[12:15]
	s_barrier
	s_add_u32 s70, s38, 0x160000
	s_addc_u32 s71, s39, 0
	s_add_i32 s69, s59, s46
	s_mov_b32 m0, s69
	s_nop 0
	global_load_lds_dwordx4 v146, s[70:71]
	s_add_i32 m0, s69, 0x2000
	s_nop 0
	global_load_lds_dwordx4 v148, s[70:71]
	s_waitcnt vmcnt(6)
	s_barrier
	v_mfma_f32_16x16x32_bf16 v[52:55], v[196:199], v[156:159], 0
	v_mfma_f32_16x16x32_bf16 v[48:51], v[204:207], v[156:159], 0
	v_mfma_f32_16x16x32_bf16 v[32:35], v[196:199], v[172:175], 0
	v_mfma_f32_16x16x32_bf16 v[24:27], v[204:207], v[172:175], 0
	v_mfma_f32_16x16x32_bf16 v[16:19], v[196:199], v[180:183], 0
	v_mfma_f32_16x16x32_bf16 v[8:11], v[204:207], v[180:183], 0
	v_mfma_f32_16x16x32_bf16 v[4:7], v[196:199], v[188:191], 0
	v_mfma_f32_16x16x32_bf16 v[0:3], v[204:207], v[188:191], 0
	v_mfma_f32_16x16x32_bf16 v[52:55], v[200:203], v[160:163], v[52:55]
	v_mfma_f32_16x16x32_bf16 v[48:51], v[208:211], v[160:163], v[48:51]
	v_mfma_f32_16x16x32_bf16 v[32:35], v[200:203], v[176:179], v[32:35]
	v_mfma_f32_16x16x32_bf16 v[24:27], v[208:211], v[176:179], v[24:27]
	v_mfma_f32_16x16x32_bf16 v[16:19], v[200:203], v[184:187], v[16:19]
	v_mfma_f32_16x16x32_bf16 v[8:11], v[208:211], v[184:187], v[8:11]
	v_mfma_f32_16x16x32_bf16 v[4:7], v[200:203], v[192:195], v[4:7]
	v_mfma_f32_16x16x32_bf16 v[0:3], v[208:211], v[192:195], v[0:3]
	s_add_i32 s69, 0, 0x18000
	s_barrier
	ds_read_b128 v[128:131], v244
	ds_read_b128 v[132:135], v244 offset:1024
	ds_read_b128 v[136:139], v244 offset:2048
	ds_read_b128 v[140:143], v244 offset:3072
	s_add_u32 s40, s40, 0x160000
	s_addc_u32 s41, s41, 0
	s_mov_b32 m0, s49
	ds_read_b128 v[156:159], v170 offset:32768
	ds_read_b128 v[160:163], v170 offset:33792
	ds_read_b128 v[172:175], v170 offset:34816
	ds_read_b128 v[176:179], v170 offset:35840
	ds_read_b128 v[180:183], v170 offset:36864
	ds_read_b128 v[184:187], v170 offset:37888
	ds_read_b128 v[188:191], v170 offset:38912
	ds_read_b128 v[192:195], v170 offset:39936
	global_load_lds_dwordx4 v146, s[40:41]
	s_mov_b32 m0, s50
	s_nop 0
	global_load_lds_dwordx4 v148, s[40:41]
	s_waitcnt lgkmcnt(8)
	s_barrier
	s_waitcnt lgkmcnt(0)
	v_mfma_f32_16x16x32_bf16 v[124:127], v[128:131], v[156:159], v[124:127]
	v_mfma_f32_16x16x32_bf16 v[120:123], v[136:139], v[156:159], v[120:123]
	v_mfma_f32_16x16x32_bf16 v[116:119], v[128:131], v[172:175], v[116:119]
	v_mfma_f32_16x16x32_bf16 v[104:107], v[136:139], v[172:175], v[104:107]
	v_mfma_f32_16x16x32_bf16 v[92:95], v[128:131], v[180:183], v[92:95]
	v_mfma_f32_16x16x32_bf16 v[88:91], v[136:139], v[180:183], v[88:91]
	v_mfma_f32_16x16x32_bf16 v[76:79], v[128:131], v[188:191], v[76:79]
	v_mfma_f32_16x16x32_bf16 v[72:75], v[136:139], v[188:191], v[72:75]
	v_mfma_f32_16x16x32_bf16 v[124:127], v[132:135], v[160:163], v[124:127]
	v_mfma_f32_16x16x32_bf16 v[120:123], v[140:143], v[160:163], v[120:123]
	v_mfma_f32_16x16x32_bf16 v[116:119], v[132:135], v[176:179], v[116:119]
	v_mfma_f32_16x16x32_bf16 v[104:107], v[140:143], v[176:179], v[104:107]
	v_mfma_f32_16x16x32_bf16 v[92:95], v[132:135], v[184:187], v[92:95]
	v_mfma_f32_16x16x32_bf16 v[88:91], v[140:143], v[184:187], v[88:91]
	v_mfma_f32_16x16x32_bf16 v[76:79], v[132:135], v[192:195], v[76:79]
	v_mfma_f32_16x16x32_bf16 v[72:75], v[140:143], v[192:195], v[72:75]
	s_barrier
	s_add_i32 s40, 0, 0x1c000
	s_add_i32 s41, s69, s46
	s_mov_b32 m0, s41
	ds_read_b128 v[196:199], v245
	ds_read_b128 v[200:203], v245 offset:1024
	ds_read_b128 v[204:207], v245 offset:2048
	ds_read_b128 v[208:211], v245 offset:3072
	global_load_lds_dwordx4 v146, s[98:99]
	s_add_i32 m0, s41, 0x2000
	s_nop 0
	global_load_lds_dwordx4 v148, s[98:99]
	s_barrier
	s_waitcnt lgkmcnt(0)
	v_mfma_f32_16x16x32_bf16 v[112:115], v[196:199], v[156:159], v[112:115]
	v_mfma_f32_16x16x32_bf16 v[108:111], v[204:207], v[156:159], v[108:111]
	v_mfma_f32_16x16x32_bf16 v[100:103], v[196:199], v[172:175], v[100:103]
	v_mfma_f32_16x16x32_bf16 v[96:99], v[204:207], v[172:175], v[96:99]
	v_mfma_f32_16x16x32_bf16 v[84:87], v[196:199], v[180:183], v[84:87]
	v_mfma_f32_16x16x32_bf16 v[80:83], v[204:207], v[180:183], v[80:83]
	v_mfma_f32_16x16x32_bf16 v[68:71], v[196:199], v[188:191], v[68:71]
	v_mfma_f32_16x16x32_bf16 v[64:67], v[204:207], v[188:191], v[64:67]
	v_mfma_f32_16x16x32_bf16 v[112:115], v[200:203], v[160:163], v[112:115]
	v_mfma_f32_16x16x32_bf16 v[108:111], v[208:211], v[160:163], v[108:111]
	v_mfma_f32_16x16x32_bf16 v[100:103], v[200:203], v[176:179], v[100:103]
	v_mfma_f32_16x16x32_bf16 v[96:99], v[208:211], v[176:179], v[96:99]
	v_mfma_f32_16x16x32_bf16 v[84:87], v[200:203], v[184:187], v[84:87]
	v_mfma_f32_16x16x32_bf16 v[80:83], v[208:211], v[184:187], v[80:83]
	v_mfma_f32_16x16x32_bf16 v[68:71], v[200:203], v[192:195], v[68:71]
	v_mfma_f32_16x16x32_bf16 v[64:67], v[208:211], v[192:195], v[64:67]
	s_mov_b32 m0, s54
	s_barrier
	ds_read_b128 v[156:159], v170 offset:49152
	ds_read_b128 v[160:163], v170 offset:50176
	ds_read_b128 v[172:175], v170 offset:51200
	ds_read_b128 v[176:179], v170 offset:52224
	ds_read_b128 v[180:183], v170 offset:53248
	ds_read_b128 v[184:187], v170 offset:54272
	ds_read_b128 v[188:191], v170 offset:55296
	ds_read_b128 v[192:195], v170 offset:56320
	global_load_lds_dwordx4 v146, s[100:101]
	s_mov_b32 m0, s55
	s_nop 0
	global_load_lds_dwordx4 v148, s[100:101]
	s_barrier
	s_waitcnt lgkmcnt(0)
	v_mfma_f32_16x16x32_bf16 v[60:63], v[128:131], v[156:159], v[60:63]
	v_mfma_f32_16x16x32_bf16 v[56:59], v[136:139], v[156:159], v[56:59]
	v_mfma_f32_16x16x32_bf16 v[44:47], v[128:131], v[172:175], v[44:47]
	v_mfma_f32_16x16x32_bf16 v[40:43], v[136:139], v[172:175], v[40:43]
	v_mfma_f32_16x16x32_bf16 v[36:39], v[128:131], v[180:183], v[36:39]
	v_mfma_f32_16x16x32_bf16 v[28:31], v[136:139], v[180:183], v[28:31]
	v_mfma_f32_16x16x32_bf16 v[20:23], v[128:131], v[188:191], v[20:23]
	v_mfma_f32_16x16x32_bf16 v[12:15], v[136:139], v[188:191], v[12:15]
	v_mfma_f32_16x16x32_bf16 v[60:63], v[132:135], v[160:163], v[60:63]
	v_mfma_f32_16x16x32_bf16 v[56:59], v[140:143], v[160:163], v[56:59]
	v_mfma_f32_16x16x32_bf16 v[44:47], v[132:135], v[176:179], v[44:47]
	v_mfma_f32_16x16x32_bf16 v[40:43], v[140:143], v[176:179], v[40:43]
	v_mfma_f32_16x16x32_bf16 v[36:39], v[132:135], v[184:187], v[36:39]
	v_mfma_f32_16x16x32_bf16 v[28:31], v[140:143], v[184:187], v[28:31]
	v_mfma_f32_16x16x32_bf16 v[20:23], v[132:135], v[192:195], v[20:23]
	v_mfma_f32_16x16x32_bf16 v[12:15], v[140:143], v[192:195], v[12:15]
	s_barrier
	s_add_u32 s38, s38, 0x160080
	s_addc_u32 s39, s39, 0
	s_add_i32 s40, s40, s46
	s_mov_b32 m0, s40
	s_nop 0
	global_load_lds_dwordx4 v146, s[38:39]
	s_add_i32 m0, s40, 0x2000
	s_nop 0
	global_load_lds_dwordx4 v148, s[38:39]
	s_waitcnt vmcnt(6)
	s_barrier
	v_mfma_f32_16x16x32_bf16 v[52:55], v[196:199], v[156:159], v[52:55]
	v_mfma_f32_16x16x32_bf16 v[48:51], v[204:207], v[156:159], v[48:51]
	v_mfma_f32_16x16x32_bf16 v[32:35], v[196:199], v[172:175], v[32:35]
	v_mfma_f32_16x16x32_bf16 v[24:27], v[204:207], v[172:175], v[24:27]
	v_mfma_f32_16x16x32_bf16 v[16:19], v[196:199], v[180:183], v[16:19]
	v_mfma_f32_16x16x32_bf16 v[8:11], v[204:207], v[180:183], v[8:11]
	v_mfma_f32_16x16x32_bf16 v[4:7], v[196:199], v[188:191], v[4:7]
	v_mfma_f32_16x16x32_bf16 v[0:3], v[204:207], v[188:191], v[0:3]
	v_mfma_f32_16x16x32_bf16 v[52:55], v[200:203], v[160:163], v[52:55]
	v_mfma_f32_16x16x32_bf16 v[48:51], v[208:211], v[160:163], v[48:51]
	v_mfma_f32_16x16x32_bf16 v[32:35], v[200:203], v[176:179], v[32:35]
	v_mfma_f32_16x16x32_bf16 v[24:27], v[208:211], v[176:179], v[24:27]
	v_mfma_f32_16x16x32_bf16 v[16:19], v[200:203], v[184:187], v[16:19]
	v_mfma_f32_16x16x32_bf16 v[8:11], v[208:211], v[184:187], v[8:11]
	v_mfma_f32_16x16x32_bf16 v[4:7], v[200:203], v[192:195], v[4:7]
	v_mfma_f32_16x16x32_bf16 v[0:3], v[208:211], v[192:195], v[0:3]
	s_add_i32 s68, s68, 2
	s_add_u32 s36, s36, 0x100
	s_addc_u32 s37, s37, 0
	s_add_u32 s28, s28, 0x100
	s_addc_u32 s29, s29, 0
	s_cmpk_gt_u32 s68, 0x55
	s_barrier
	s_cbranch_scc0 .LBB0_1285
.LBB0_1285:
	ds_read_b128 v[128:131], v169
	ds_read_b128 v[132:135], v169 offset:1024
	ds_read_b128 v[136:139], v169 offset:2048
	ds_read_b128 v[140:143], v169 offset:3072
	s_add_u32 s38, s36, 0xffea0080
	s_addc_u32 s39, s37, -1
	s_cmpk_eq_i32 s68, 0x54
	s_cselect_b32 s41, s35, s39
	s_cselect_b32 s40, s34, s38
	s_cselect_b32 s39, s1, s29
	s_cselect_b32 s38, s0, s28
	s_add_i32 m0, s47, 0xc000
	ds_read_b128 v[156:159], v170
	ds_read_b128 v[160:163], v170 offset:1024
	ds_read_b128 v[172:175], v170 offset:2048
	ds_read_b128 v[176:179], v170 offset:3072
	ds_read_b128 v[180:183], v170 offset:4096
	ds_read_b128 v[184:187], v170 offset:5120
	ds_read_b128 v[188:191], v170 offset:6144
	ds_read_b128 v[192:195], v170 offset:7168
	global_load_lds_dwordx4 v150, s[36:37]
	s_add_i32 m0, s47, 0xe000
	s_nop 0
	global_load_lds_dwordx4 v152, s[36:37]
	s_waitcnt lgkmcnt(8)
	s_barrier
	s_waitcnt lgkmcnt(0)
	v_mfma_f32_16x16x32_bf16 v[124:127], v[128:131], v[156:159], v[124:127]
	v_mfma_f32_16x16x32_bf16 v[120:123], v[136:139], v[156:159], v[120:123]
	v_mfma_f32_16x16x32_bf16 v[116:119], v[128:131], v[172:175], v[116:119]
	v_mfma_f32_16x16x32_bf16 v[104:107], v[136:139], v[172:175], v[104:107]
	v_mfma_f32_16x16x32_bf16 v[92:95], v[128:131], v[180:183], v[92:95]
	v_mfma_f32_16x16x32_bf16 v[88:91], v[136:139], v[180:183], v[88:91]
	v_mfma_f32_16x16x32_bf16 v[76:79], v[128:131], v[188:191], v[76:79]
	v_mfma_f32_16x16x32_bf16 v[72:75], v[136:139], v[188:191], v[72:75]
	v_mfma_f32_16x16x32_bf16 v[124:127], v[132:135], v[160:163], v[124:127]
	v_mfma_f32_16x16x32_bf16 v[120:123], v[140:143], v[160:163], v[120:123]
	v_mfma_f32_16x16x32_bf16 v[116:119], v[132:135], v[176:179], v[116:119]
	v_mfma_f32_16x16x32_bf16 v[104:107], v[140:143], v[176:179], v[104:107]
	v_mfma_f32_16x16x32_bf16 v[92:95], v[132:135], v[184:187], v[92:95]
	v_mfma_f32_16x16x32_bf16 v[88:91], v[140:143], v[184:187], v[88:91]
	v_mfma_f32_16x16x32_bf16 v[76:79], v[132:135], v[192:195], v[76:79]
	v_mfma_f32_16x16x32_bf16 v[72:75], v[140:143], v[192:195], v[72:75]
	s_barrier
	s_add_i32 s69, s58, s46
	s_add_u32 s98, s38, s10
	s_addc_u32 s99, s39, s11
	s_mov_b32 m0, s69
	ds_read_b128 v[196:199], v171
	ds_read_b128 v[200:203], v171 offset:1024
	ds_read_b128 v[204:207], v171 offset:2048
	ds_read_b128 v[208:211], v171 offset:3072
	global_load_lds_dwordx4 v146, s[38:39]
	s_add_i32 m0, s69, 0x2000
	s_nop 0
	global_load_lds_dwordx4 v148, s[38:39]
	s_barrier
	s_waitcnt lgkmcnt(0)
	v_mfma_f32_16x16x32_bf16 v[112:115], v[196:199], v[156:159], v[112:115]
	v_mfma_f32_16x16x32_bf16 v[108:111], v[204:207], v[156:159], v[108:111]
	v_mfma_f32_16x16x32_bf16 v[100:103], v[196:199], v[172:175], v[100:103]
	v_mfma_f32_16x16x32_bf16 v[96:99], v[204:207], v[172:175], v[96:99]
	v_mfma_f32_16x16x32_bf16 v[84:87], v[196:199], v[180:183], v[84:87]
	v_mfma_f32_16x16x32_bf16 v[80:83], v[204:207], v[180:183], v[80:83]
	v_mfma_f32_16x16x32_bf16 v[68:71], v[196:199], v[188:191], v[68:71]
	v_mfma_f32_16x16x32_bf16 v[64:67], v[204:207], v[188:191], v[64:67]
	v_mfma_f32_16x16x32_bf16 v[112:115], v[200:203], v[160:163], v[112:115]
	v_mfma_f32_16x16x32_bf16 v[108:111], v[208:211], v[160:163], v[108:111]
	v_mfma_f32_16x16x32_bf16 v[100:103], v[200:203], v[176:179], v[100:103]
	v_mfma_f32_16x16x32_bf16 v[96:99], v[208:211], v[176:179], v[96:99]
	v_mfma_f32_16x16x32_bf16 v[84:87], v[200:203], v[184:187], v[84:87]
	v_mfma_f32_16x16x32_bf16 v[80:83], v[208:211], v[184:187], v[80:83]
	v_mfma_f32_16x16x32_bf16 v[68:71], v[200:203], v[192:195], v[68:71]
	v_mfma_f32_16x16x32_bf16 v[64:67], v[208:211], v[192:195], v[64:67]
	s_mov_b32 m0, s47
	s_add_u32 s100, s40, s10
	s_addc_u32 s101, s41, s11
	s_barrier
	ds_read_b128 v[156:159], v170 offset:16384
	ds_read_b128 v[160:163], v170 offset:17408
	ds_read_b128 v[172:175], v170 offset:18432
	ds_read_b128 v[176:179], v170 offset:19456
	ds_read_b128 v[180:183], v170 offset:20480
	ds_read_b128 v[184:187], v170 offset:21504
	ds_read_b128 v[188:191], v170 offset:22528
	ds_read_b128 v[192:195], v170 offset:23552
	global_load_lds_dwordx4 v146, s[40:41]
	s_mov_b32 m0, s48
	s_nop 0
	global_load_lds_dwordx4 v148, s[40:41]
	s_barrier
	s_waitcnt lgkmcnt(0)
	v_mfma_f32_16x16x32_bf16 v[60:63], v[128:131], v[156:159], v[60:63]
	v_mfma_f32_16x16x32_bf16 v[56:59], v[136:139], v[156:159], v[56:59]
	v_mfma_f32_16x16x32_bf16 v[44:47], v[128:131], v[172:175], v[44:47]
	v_mfma_f32_16x16x32_bf16 v[40:43], v[136:139], v[172:175], v[40:43]
	v_mfma_f32_16x16x32_bf16 v[36:39], v[128:131], v[180:183], v[36:39]
	v_mfma_f32_16x16x32_bf16 v[28:31], v[136:139], v[180:183], v[28:31]
	v_mfma_f32_16x16x32_bf16 v[20:23], v[128:131], v[188:191], v[20:23]
	v_mfma_f32_16x16x32_bf16 v[12:15], v[136:139], v[188:191], v[12:15]
	v_mfma_f32_16x16x32_bf16 v[60:63], v[132:135], v[160:163], v[60:63]
	v_mfma_f32_16x16x32_bf16 v[56:59], v[140:143], v[160:163], v[56:59]
	v_mfma_f32_16x16x32_bf16 v[44:47], v[132:135], v[176:179], v[44:47]
	v_mfma_f32_16x16x32_bf16 v[40:43], v[140:143], v[176:179], v[40:43]
	v_mfma_f32_16x16x32_bf16 v[36:39], v[132:135], v[184:187], v[36:39]
	v_mfma_f32_16x16x32_bf16 v[28:31], v[140:143], v[184:187], v[28:31]
	v_mfma_f32_16x16x32_bf16 v[20:23], v[132:135], v[192:195], v[20:23]
	v_mfma_f32_16x16x32_bf16 v[12:15], v[140:143], v[192:195], v[12:15]
	s_barrier
	s_add_u32 s70, s38, 0x160000
	s_addc_u32 s71, s39, 0
	s_add_i32 s69, s59, s46
	s_mov_b32 m0, s69
	s_nop 0
	global_load_lds_dwordx4 v146, s[70:71]
	s_add_i32 m0, s69, 0x2000
	s_nop 0
	global_load_lds_dwordx4 v148, s[70:71]
	s_waitcnt vmcnt(6)
	s_barrier
	v_mfma_f32_16x16x32_bf16 v[52:55], v[196:199], v[156:159], v[52:55]
	v_mfma_f32_16x16x32_bf16 v[48:51], v[204:207], v[156:159], v[48:51]
	v_mfma_f32_16x16x32_bf16 v[32:35], v[196:199], v[172:175], v[32:35]
	v_mfma_f32_16x16x32_bf16 v[24:27], v[204:207], v[172:175], v[24:27]
	v_mfma_f32_16x16x32_bf16 v[16:19], v[196:199], v[180:183], v[16:19]
	v_mfma_f32_16x16x32_bf16 v[8:11], v[204:207], v[180:183], v[8:11]
	v_mfma_f32_16x16x32_bf16 v[4:7], v[196:199], v[188:191], v[4:7]
	v_mfma_f32_16x16x32_bf16 v[0:3], v[204:207], v[188:191], v[0:3]
	v_mfma_f32_16x16x32_bf16 v[52:55], v[200:203], v[160:163], v[52:55]
	v_mfma_f32_16x16x32_bf16 v[48:51], v[208:211], v[160:163], v[48:51]
	v_mfma_f32_16x16x32_bf16 v[32:35], v[200:203], v[176:179], v[32:35]
	v_mfma_f32_16x16x32_bf16 v[24:27], v[208:211], v[176:179], v[24:27]
	v_mfma_f32_16x16x32_bf16 v[16:19], v[200:203], v[184:187], v[16:19]
	v_mfma_f32_16x16x32_bf16 v[8:11], v[208:211], v[184:187], v[8:11]
	v_mfma_f32_16x16x32_bf16 v[4:7], v[200:203], v[192:195], v[4:7]
	v_mfma_f32_16x16x32_bf16 v[0:3], v[208:211], v[192:195], v[0:3]
	s_add_i32 s69, 0, 0x18000
	s_barrier
	ds_read_b128 v[128:131], v244
	ds_read_b128 v[132:135], v244 offset:1024
	ds_read_b128 v[136:139], v244 offset:2048
	ds_read_b128 v[140:143], v244 offset:3072
	s_add_u32 s40, s40, 0x160000
	s_addc_u32 s41, s41, 0
	s_mov_b32 m0, s49
	ds_read_b128 v[156:159], v170 offset:32768
	ds_read_b128 v[160:163], v170 offset:33792
	ds_read_b128 v[172:175], v170 offset:34816
	ds_read_b128 v[176:179], v170 offset:35840
	ds_read_b128 v[180:183], v170 offset:36864
	ds_read_b128 v[184:187], v170 offset:37888
	ds_read_b128 v[188:191], v170 offset:38912
	ds_read_b128 v[192:195], v170 offset:39936
	global_load_lds_dwordx4 v146, s[40:41]
	s_mov_b32 m0, s50
	s_nop 0
	global_load_lds_dwordx4 v148, s[40:41]
	s_waitcnt lgkmcnt(8)
	s_barrier
	s_waitcnt lgkmcnt(0)
	v_mfma_f32_16x16x32_bf16 v[124:127], v[128:131], v[156:159], v[124:127]
	v_mfma_f32_16x16x32_bf16 v[120:123], v[136:139], v[156:159], v[120:123]
	v_mfma_f32_16x16x32_bf16 v[116:119], v[128:131], v[172:175], v[116:119]
	v_mfma_f32_16x16x32_bf16 v[104:107], v[136:139], v[172:175], v[104:107]
	v_mfma_f32_16x16x32_bf16 v[92:95], v[128:131], v[180:183], v[92:95]
	v_mfma_f32_16x16x32_bf16 v[88:91], v[136:139], v[180:183], v[88:91]
	v_mfma_f32_16x16x32_bf16 v[76:79], v[128:131], v[188:191], v[76:79]
	v_mfma_f32_16x16x32_bf16 v[72:75], v[136:139], v[188:191], v[72:75]
	v_mfma_f32_16x16x32_bf16 v[124:127], v[132:135], v[160:163], v[124:127]
	v_mfma_f32_16x16x32_bf16 v[120:123], v[140:143], v[160:163], v[120:123]
	v_mfma_f32_16x16x32_bf16 v[116:119], v[132:135], v[176:179], v[116:119]
	v_mfma_f32_16x16x32_bf16 v[104:107], v[140:143], v[176:179], v[104:107]
	v_mfma_f32_16x16x32_bf16 v[92:95], v[132:135], v[184:187], v[92:95]
	v_mfma_f32_16x16x32_bf16 v[88:91], v[140:143], v[184:187], v[88:91]
	v_mfma_f32_16x16x32_bf16 v[76:79], v[132:135], v[192:195], v[76:79]
	v_mfma_f32_16x16x32_bf16 v[72:75], v[140:143], v[192:195], v[72:75]
	s_barrier
	s_add_i32 s40, 0, 0x1c000
	s_add_i32 s41, s69, s46
	s_mov_b32 m0, s41
	ds_read_b128 v[196:199], v245
	ds_read_b128 v[200:203], v245 offset:1024
	ds_read_b128 v[204:207], v245 offset:2048
	ds_read_b128 v[208:211], v245 offset:3072
	global_load_lds_dwordx4 v146, s[98:99]
	s_add_i32 m0, s41, 0x2000
	s_nop 0
	global_load_lds_dwordx4 v148, s[98:99]
	s_barrier
	s_waitcnt lgkmcnt(0)
	v_mfma_f32_16x16x32_bf16 v[112:115], v[196:199], v[156:159], v[112:115]
	v_mfma_f32_16x16x32_bf16 v[108:111], v[204:207], v[156:159], v[108:111]
	v_mfma_f32_16x16x32_bf16 v[100:103], v[196:199], v[172:175], v[100:103]
	v_mfma_f32_16x16x32_bf16 v[96:99], v[204:207], v[172:175], v[96:99]
	v_mfma_f32_16x16x32_bf16 v[84:87], v[196:199], v[180:183], v[84:87]
	v_mfma_f32_16x16x32_bf16 v[80:83], v[204:207], v[180:183], v[80:83]
	v_mfma_f32_16x16x32_bf16 v[68:71], v[196:199], v[188:191], v[68:71]
	v_mfma_f32_16x16x32_bf16 v[64:67], v[204:207], v[188:191], v[64:67]
	v_mfma_f32_16x16x32_bf16 v[112:115], v[200:203], v[160:163], v[112:115]
	v_mfma_f32_16x16x32_bf16 v[108:111], v[208:211], v[160:163], v[108:111]
	v_mfma_f32_16x16x32_bf16 v[100:103], v[200:203], v[176:179], v[100:103]
	v_mfma_f32_16x16x32_bf16 v[96:99], v[208:211], v[176:179], v[96:99]
	v_mfma_f32_16x16x32_bf16 v[84:87], v[200:203], v[184:187], v[84:87]
	v_mfma_f32_16x16x32_bf16 v[80:83], v[208:211], v[184:187], v[80:83]
	v_mfma_f32_16x16x32_bf16 v[68:71], v[200:203], v[192:195], v[68:71]
	v_mfma_f32_16x16x32_bf16 v[64:67], v[208:211], v[192:195], v[64:67]
	s_mov_b32 m0, s54
	s_barrier
	ds_read_b128 v[156:159], v170 offset:49152
	ds_read_b128 v[160:163], v170 offset:50176
	ds_read_b128 v[172:175], v170 offset:51200
	ds_read_b128 v[176:179], v170 offset:52224
	ds_read_b128 v[180:183], v170 offset:53248
	ds_read_b128 v[184:187], v170 offset:54272
	ds_read_b128 v[188:191], v170 offset:55296
	ds_read_b128 v[192:195], v170 offset:56320
	global_load_lds_dwordx4 v146, s[100:101]
	s_mov_b32 m0, s55
	s_nop 0
	global_load_lds_dwordx4 v148, s[100:101]
	s_barrier
	s_waitcnt lgkmcnt(0)
	v_mfma_f32_16x16x32_bf16 v[60:63], v[128:131], v[156:159], v[60:63]
	v_mfma_f32_16x16x32_bf16 v[56:59], v[136:139], v[156:159], v[56:59]
	v_mfma_f32_16x16x32_bf16 v[44:47], v[128:131], v[172:175], v[44:47]
	v_mfma_f32_16x16x32_bf16 v[40:43], v[136:139], v[172:175], v[40:43]
	v_mfma_f32_16x16x32_bf16 v[36:39], v[128:131], v[180:183], v[36:39]
	v_mfma_f32_16x16x32_bf16 v[28:31], v[136:139], v[180:183], v[28:31]
	v_mfma_f32_16x16x32_bf16 v[20:23], v[128:131], v[188:191], v[20:23]
	v_mfma_f32_16x16x32_bf16 v[12:15], v[136:139], v[188:191], v[12:15]
	v_mfma_f32_16x16x32_bf16 v[60:63], v[132:135], v[160:163], v[60:63]
	v_mfma_f32_16x16x32_bf16 v[56:59], v[140:143], v[160:163], v[56:59]
	v_mfma_f32_16x16x32_bf16 v[44:47], v[132:135], v[176:179], v[44:47]
	v_mfma_f32_16x16x32_bf16 v[40:43], v[140:143], v[176:179], v[40:43]
	v_mfma_f32_16x16x32_bf16 v[36:39], v[132:135], v[184:187], v[36:39]
	v_mfma_f32_16x16x32_bf16 v[28:31], v[140:143], v[184:187], v[28:31]
	v_mfma_f32_16x16x32_bf16 v[20:23], v[132:135], v[192:195], v[20:23]
	v_mfma_f32_16x16x32_bf16 v[12:15], v[140:143], v[192:195], v[12:15]
	s_barrier
	s_add_u32 s38, s38, 0x160080
	s_addc_u32 s39, s39, 0
	s_add_i32 s40, s40, s46
	s_mov_b32 m0, s40
	s_nop 0
	global_load_lds_dwordx4 v146, s[38:39]
	s_add_i32 m0, s40, 0x2000
	s_nop 0
	global_load_lds_dwordx4 v148, s[38:39]
	s_waitcnt vmcnt(6)
	s_barrier
	v_mfma_f32_16x16x32_bf16 v[52:55], v[196:199], v[156:159], v[52:55]
	v_mfma_f32_16x16x32_bf16 v[48:51], v[204:207], v[156:159], v[48:51]
	v_mfma_f32_16x16x32_bf16 v[32:35], v[196:199], v[172:175], v[32:35]
	v_mfma_f32_16x16x32_bf16 v[24:27], v[204:207], v[172:175], v[24:27]
	v_mfma_f32_16x16x32_bf16 v[16:19], v[196:199], v[180:183], v[16:19]
	v_mfma_f32_16x16x32_bf16 v[8:11], v[204:207], v[180:183], v[8:11]
	v_mfma_f32_16x16x32_bf16 v[4:7], v[196:199], v[188:191], v[4:7]
	v_mfma_f32_16x16x32_bf16 v[0:3], v[204:207], v[188:191], v[0:3]
	v_mfma_f32_16x16x32_bf16 v[52:55], v[200:203], v[160:163], v[52:55]
	v_mfma_f32_16x16x32_bf16 v[48:51], v[208:211], v[160:163], v[48:51]
	v_mfma_f32_16x16x32_bf16 v[32:35], v[200:203], v[176:179], v[32:35]
	v_mfma_f32_16x16x32_bf16 v[24:27], v[208:211], v[176:179], v[24:27]
	v_mfma_f32_16x16x32_bf16 v[16:19], v[200:203], v[184:187], v[16:19]
	v_mfma_f32_16x16x32_bf16 v[8:11], v[208:211], v[184:187], v[8:11]
	v_mfma_f32_16x16x32_bf16 v[4:7], v[200:203], v[192:195], v[4:7]
	v_mfma_f32_16x16x32_bf16 v[0:3], v[208:211], v[192:195], v[0:3]
	s_add_i32 s68, s68, 2
	s_add_u32 s36, s36, 0x100
	s_addc_u32 s37, s37, 0
	s_add_u32 s28, s28, 0x100
	s_addc_u32 s29, s29, 0
	s_cmpk_gt_u32 s68, 0x55
	s_barrier
	s_cbranch_scc0 .LBB0_1285
	v_lshl_add_u32 v164, s66, 8, v166
	v_lshl_or_b32 v128, s67, 8, v168
	v_ashrrev_i32_e32 v165, 31, v164
	s_ashr_i32 s28, s66, 3
	v_ashrrev_i32_e32 v129, 31, v128
	v_lshlrev_b64 v[130:131], 12, v[164:165]
	s_mul_hi_i32 s29, s28, 0xc000
	s_mul_i32 s28, s28, 0xc000
	v_lshl_add_u64 v[130:131], s[8:9], 0, v[130:131]
	v_lshlrev_b64 v[158:159], 1, v[128:129]
	s_add_u32 s28, s52, s28
	v_lshl_add_u64 v[156:157], v[130:131], 0, v[158:159]
	v_or_b32_e32 v130, 16, v164
	s_addc_u32 s29, s53, s29
	v_lshl_add_u64 v[128:129], v[128:129], 2, s[28:29]
	v_ashrrev_i32_e32 v131, 31, v130
	global_load_dwordx2 v[162:163], v[156:157], off
	global_load_dwordx2 v[172:173], v[156:157], off offset:32
	global_load_dwordx2 v[174:175], v[156:157], off offset:256
	global_load_dwordx4 v[132:135], v[128:129], off offset:512
	global_load_dwordx2 v[176:177], v[156:157], off offset:288
	global_load_dwordx4 v[140:143], v[128:129], off
	global_load_dwordx4 v[136:139], v[128:129], off offset:64
	v_lshlrev_b64 v[130:131], 12, v[130:131]
	v_lshl_add_u64 v[160:161], s[8:9], 0, v[130:131]
	global_load_dwordx4 v[128:131], v[128:129], off offset:576
	v_lshl_add_u64 v[160:161], v[160:161], 0, v[158:159]
	global_load_dwordx2 v[178:179], v[160:161], off
	global_load_dwordx2 v[180:181], v[160:161], off offset:32
	global_load_dwordx2 v[182:183], v[160:161], off offset:256
	global_load_dwordx2 v[186:187], v[160:161], off offset:288
	v_or_b32_e32 v184, 32, v164
	v_or_b32_e32 v164, 48, v164
	v_ashrrev_i32_e32 v185, 31, v184
	v_ashrrev_i32_e32 v165, 31, v164
	v_lshlrev_b64 v[184:185], 12, v[184:185]
	v_lshlrev_b64 v[164:165], 12, v[164:165]
	v_lshl_add_u64 v[184:185], s[8:9], 0, v[184:185]
	v_lshl_add_u64 v[164:165], s[8:9], 0, v[164:165]
	v_lshl_add_u64 v[184:185], v[184:185], 0, v[158:159]
	v_lshl_add_u64 v[158:159], v[164:165], 0, v[158:159]
	global_load_dwordx2 v[164:165], v[184:185], off
	global_load_dwordx2 v[188:189], v[184:185], off offset:32
	global_load_dwordx2 v[190:191], v[184:185], off offset:256
	global_load_dwordx2 v[192:193], v[184:185], off offset:288
	global_load_dwordx2 v[194:195], v[158:159], off
	s_mov_b32 s67, s64
	s_mov_b32 s66, s65
	s_mov_b64 s[38:39], s[0:1]
	s_mov_b64 s[36:37], s[34:35]
	s_waitcnt vmcnt(0)
	v_lshlrev_b32_e32 v196, 16, v162
	v_and_b32_e32 v197, 0xffff0000, v162
	v_lshlrev_b32_e32 v162, 16, v163
	v_and_b32_e32 v163, 0xffff0000, v163
	v_lshlrev_b32_e32 v198, 16, v172
	v_and_b32_e32 v199, 0xffff0000, v172
	v_lshlrev_b32_e32 v172, 16, v173
	v_and_b32_e32 v173, 0xffff0000, v173
	v_lshlrev_b32_e32 v200, 16, v174
	v_and_b32_e32 v201, 0xffff0000, v174
	v_lshlrev_b32_e32 v174, 16, v175
	v_and_b32_e32 v175, 0xffff0000, v175
	v_lshlrev_b32_e32 v202, 16, v176
	v_and_b32_e32 v203, 0xffff0000, v176
	v_lshlrev_b32_e32 v176, 16, v177
	v_and_b32_e32 v177, 0xffff0000, v177
	v_pk_fma_f32 v[126:127], v[126:127], v[142:143], v[162:163]
	v_pk_fma_f32 v[124:125], v[124:125], v[140:141], v[196:197]
	v_pk_fma_f32 v[122:123], v[122:123], v[138:139], v[172:173]
	v_pk_fma_f32 v[120:121], v[120:121], v[136:137], v[198:199]
	v_pk_fma_f32 v[114:115], v[114:115], v[134:135], v[174:175]
	v_pk_fma_f32 v[112:113], v[112:113], v[132:133], v[200:201]
	v_pk_fma_f32 v[110:111], v[110:111], v[130:131], v[176:177]
	v_pk_fma_f32 v[108:109], v[108:109], v[128:129], v[202:203]
	v_cvt_pk_bf16_f32 v124, v124, v125
	v_cvt_pk_bf16_f32 v125, v126, v127
	v_cvt_pk_bf16_f32 v120, v120, v121
	v_cvt_pk_bf16_f32 v121, v122, v123
	v_cvt_pk_bf16_f32 v112, v112, v113
	v_cvt_pk_bf16_f32 v113, v114, v115
	v_cvt_pk_bf16_f32 v108, v108, v109
	v_cvt_pk_bf16_f32 v109, v110, v111
	global_store_dwordx2 v[156:157], v[124:125], off
	global_store_dwordx2 v[156:157], v[120:121], off offset:32
	global_store_dwordx2 v[156:157], v[112:113], off offset:256
	global_store_dwordx2 v[156:157], v[108:109], off offset:288
	global_load_dwordx2 v[112:113], v[158:159], off offset:32
	v_lshlrev_b32_e32 v162, 16, v178
	v_and_b32_e32 v163, 0xffff0000, v178
	v_lshlrev_b32_e32 v172, 16, v179
	v_and_b32_e32 v173, 0xffff0000, v179
	v_pk_fma_f32 v[110:111], v[118:119], v[142:143], v[172:173]
	v_pk_fma_f32 v[114:115], v[116:117], v[140:141], v[162:163]
	v_cvt_pk_bf16_f32 v109, v110, v111
	v_cvt_pk_bf16_f32 v108, v114, v115
	global_store_dwordx2 v[160:161], v[108:109], off
	v_lshlrev_b32_e32 v108, 16, v180
	v_and_b32_e32 v109, 0xffff0000, v180
	v_lshlrev_b32_e32 v110, 16, v181
	v_and_b32_e32 v111, 0xffff0000, v181
	v_pk_fma_f32 v[106:107], v[106:107], v[138:139], v[110:111]
	v_pk_fma_f32 v[104:105], v[104:105], v[136:137], v[108:109]
	s_nop 0
	v_cvt_pk_bf16_f32 v104, v104, v105
	v_cvt_pk_bf16_f32 v105, v106, v107
	global_store_dwordx2 v[160:161], v[104:105], off offset:32
	v_lshlrev_b32_e32 v104, 16, v182
	v_and_b32_e32 v105, 0xffff0000, v182
	v_lshlrev_b32_e32 v106, 16, v183
	v_and_b32_e32 v107, 0xffff0000, v183
	v_pk_fma_f32 v[102:103], v[102:103], v[134:135], v[106:107]
	v_pk_fma_f32 v[100:101], v[100:101], v[132:133], v[104:105]
	v_lshlrev_b32_e32 v104, 16, v187
	v_cvt_pk_bf16_f32 v100, v100, v101
	v_cvt_pk_bf16_f32 v101, v102, v103
	global_load_dwordx2 v[102:103], v[158:159], off offset:256
	v_and_b32_e32 v105, 0xffff0000, v187
	global_store_dwordx2 v[160:161], v[100:101], off offset:256
	v_lshlrev_b32_e32 v100, 16, v186
	v_and_b32_e32 v101, 0xffff0000, v186
	v_pk_fma_f32 v[98:99], v[98:99], v[130:131], v[104:105]
	v_pk_fma_f32 v[96:97], v[96:97], v[128:129], v[100:101]
	v_lshlrev_b32_e32 v100, 16, v165
	v_cvt_pk_bf16_f32 v96, v96, v97
	v_cvt_pk_bf16_f32 v97, v98, v99
	global_store_dwordx2 v[160:161], v[96:97], off offset:288
	global_load_dwordx2 v[96:97], v[158:159], off offset:288
	v_and_b32_e32 v101, 0xffff0000, v165
	v_pk_fma_f32 v[94:95], v[94:95], v[142:143], v[100:101]
	v_add_co_u32_e32 v100, vcc, s60, v156
	v_lshlrev_b32_e32 v98, 16, v164
	v_and_b32_e32 v99, 0xffff0000, v164
	v_addc_co_u32_e32 v101, vcc, 0, v157, vcc
	global_load_dwordx2 v[104:105], v[100:101], off
	v_pk_fma_f32 v[92:93], v[92:93], v[140:141], v[98:99]
	s_nop 0
	v_cvt_pk_bf16_f32 v92, v92, v93
	v_cvt_pk_bf16_f32 v93, v94, v95
	global_store_dwordx2 v[184:185], v[92:93], off
	v_lshlrev_b32_e32 v92, 16, v188
	v_and_b32_e32 v93, 0xffff0000, v188
	v_lshlrev_b32_e32 v94, 16, v189
	v_and_b32_e32 v95, 0xffff0000, v189
	v_pk_fma_f32 v[90:91], v[90:91], v[138:139], v[94:95]
	v_pk_fma_f32 v[88:89], v[88:89], v[136:137], v[92:93]
	v_lshlrev_b32_e32 v92, 16, v190
	v_cvt_pk_bf16_f32 v88, v88, v89
	v_cvt_pk_bf16_f32 v89, v90, v91
	global_store_dwordx2 v[184:185], v[88:89], off offset:32
	v_lshl_add_u64 v[88:89], v[156:157], 0, s[12:13]
	global_load_dwordx2 v[90:91], v[88:89], off offset:32
	v_and_b32_e32 v93, 0xffff0000, v190
	v_lshlrev_b32_e32 v94, 16, v191
	v_and_b32_e32 v95, 0xffff0000, v191
	v_pk_fma_f32 v[86:87], v[86:87], v[134:135], v[94:95]
	v_pk_fma_f32 v[84:85], v[84:85], v[132:133], v[92:93]
	v_lshlrev_b32_e32 v92, 16, v193
	v_cvt_pk_bf16_f32 v84, v84, v85
	v_cvt_pk_bf16_f32 v85, v86, v87
	global_load_dwordx2 v[86:87], v[88:89], off offset:256
	v_and_b32_e32 v93, 0xffff0000, v193
	global_store_dwordx2 v[184:185], v[84:85], off offset:256
	v_lshlrev_b32_e32 v84, 16, v192
	v_and_b32_e32 v85, 0xffff0000, v192
	v_pk_fma_f32 v[82:83], v[82:83], v[130:131], v[92:93]
	v_pk_fma_f32 v[80:81], v[80:81], v[128:129], v[84:85]
	v_lshlrev_b32_e32 v84, 16, v195
	v_cvt_pk_bf16_f32 v80, v80, v81
	v_cvt_pk_bf16_f32 v81, v82, v83
	global_load_dwordx2 v[82:83], v[88:89], off offset:288
	v_and_b32_e32 v85, 0xffff0000, v195
	global_store_dwordx2 v[184:185], v[80:81], off offset:288
	v_lshlrev_b32_e32 v80, 16, v194
	v_and_b32_e32 v81, 0xffff0000, v194
	v_pk_fma_f32 v[78:79], v[78:79], v[142:143], v[84:85]
	v_pk_fma_f32 v[76:77], v[76:77], v[140:141], v[80:81]
	s_waitcnt vmcnt(0)
	v_lshlrev_b32_e32 v84, 16, v113
	v_cvt_pk_bf16_f32 v76, v76, v77
	v_cvt_pk_bf16_f32 v77, v78, v79
	v_add_co_u32_e32 v78, vcc, s61, v156
	global_store_dwordx2 v[158:159], v[76:77], off
	v_lshlrev_b32_e32 v76, 16, v112
	v_and_b32_e32 v77, 0xffff0000, v112
	v_addc_co_u32_e32 v79, vcc, 0, v157, vcc
	v_and_b32_e32 v85, 0xffff0000, v113
	global_load_dwordx2 v[80:81], v[78:79], off
	v_pk_fma_f32 v[74:75], v[74:75], v[138:139], v[84:85]
	v_pk_fma_f32 v[72:73], v[72:73], v[136:137], v[76:77]
	v_lshlrev_b32_e32 v84, 16, v103
	v_cvt_pk_bf16_f32 v72, v72, v73
	v_cvt_pk_bf16_f32 v73, v74, v75
	global_store_dwordx2 v[158:159], v[72:73], off offset:32
	v_lshl_add_u64 v[72:73], v[156:157], 0, s[14:15]
	global_load_dwordx2 v[76:77], v[72:73], off offset:32
	v_lshlrev_b32_e32 v74, 16, v102
	v_and_b32_e32 v75, 0xffff0000, v102
	v_and_b32_e32 v85, 0xffff0000, v103
	v_pk_fma_f32 v[70:71], v[70:71], v[134:135], v[84:85]
	v_pk_fma_f32 v[68:69], v[68:69], v[132:133], v[74:75]
	v_lshlrev_b32_e32 v74, 16, v97
	v_cvt_pk_bf16_f32 v68, v68, v69
	v_cvt_pk_bf16_f32 v69, v70, v71
	global_store_dwordx2 v[158:159], v[68:69], off offset:256
	v_lshlrev_b32_e32 v68, 16, v96
	v_and_b32_e32 v69, 0xffff0000, v96
	global_load_dwordx2 v[70:71], v[72:73], off offset:256
	v_and_b32_e32 v75, 0xffff0000, v97
	v_pk_fma_f32 v[66:67], v[66:67], v[130:131], v[74:75]
	v_pk_fma_f32 v[64:65], v[64:65], v[128:129], v[68:69]
	v_lshlrev_b32_e32 v68, 16, v105
	v_cvt_pk_bf16_f32 v64, v64, v65
	v_cvt_pk_bf16_f32 v65, v66, v67
	global_store_dwordx2 v[158:159], v[64:65], off offset:288
	v_lshlrev_b32_e32 v64, 16, v104
	v_and_b32_e32 v65, 0xffff0000, v104
	global_load_dwordx2 v[66:67], v[72:73], off offset:288
	v_pk_fma_f32 v[60:61], v[60:61], v[140:141], v[64:65]
	v_add_co_u32_e32 v64, vcc, s62, v156
	v_and_b32_e32 v69, 0xffff0000, v105
	s_nop 0
	v_addc_co_u32_e32 v65, vcc, 0, v157, vcc
	v_pk_fma_f32 v[62:63], v[62:63], v[142:143], v[68:69]
	global_load_dwordx2 v[68:69], v[64:65], off
	v_cvt_pk_bf16_f32 v60, v60, v61
	v_cvt_pk_bf16_f32 v61, v62, v63
	v_lshl_add_u64 v[74:75], v[156:157], 0, s[16:17]
	global_store_dwordx2 v[100:101], v[60:61], off
	v_lshlrev_b32_e32 v60, 16, v90
	v_and_b32_e32 v61, 0xffff0000, v90
	v_lshlrev_b32_e32 v62, 16, v91
	v_and_b32_e32 v63, 0xffff0000, v91
	global_load_dwordx2 v[84:85], v[74:75], off offset:32
	v_pk_fma_f32 v[58:59], v[58:59], v[138:139], v[62:63]
	v_pk_fma_f32 v[56:57], v[56:57], v[136:137], v[60:61]
	global_load_dwordx2 v[60:61], v[74:75], off offset:256
	v_cvt_pk_bf16_f32 v56, v56, v57
	v_cvt_pk_bf16_f32 v57, v58, v59
	global_store_dwordx2 v[88:89], v[56:57], off offset:32
	v_lshlrev_b32_e32 v56, 16, v86
	v_and_b32_e32 v57, 0xffff0000, v86
	v_lshlrev_b32_e32 v58, 16, v87
	v_and_b32_e32 v59, 0xffff0000, v87
	v_pk_fma_f32 v[54:55], v[54:55], v[134:135], v[58:59]
	v_pk_fma_f32 v[52:53], v[52:53], v[132:133], v[56:57]
	v_lshlrev_b32_e32 v56, 16, v83
	v_cvt_pk_bf16_f32 v52, v52, v53
	v_cvt_pk_bf16_f32 v53, v54, v55
	global_store_dwordx2 v[88:89], v[52:53], off offset:256
	v_lshlrev_b32_e32 v52, 16, v82
	v_and_b32_e32 v53, 0xffff0000, v82
	global_load_dwordx2 v[54:55], v[74:75], off offset:288
	v_pk_fma_f32 v[48:49], v[48:49], v[128:129], v[52:53]
	v_add_co_u32_e32 v52, vcc, s63, v156
	v_and_b32_e32 v57, 0xffff0000, v83
	s_nop 0
	v_addc_co_u32_e32 v53, vcc, 0, v157, vcc
	v_pk_fma_f32 v[50:51], v[50:51], v[130:131], v[56:57]
	global_load_dwordx2 v[56:57], v[52:53], off
	v_lshl_add_u64 v[58:59], v[156:157], 0, s[18:19]
	v_cvt_pk_bf16_f32 v48, v48, v49
	v_cvt_pk_bf16_f32 v49, v50, v51
	global_load_dwordx2 v[62:63], v[58:59], off offset:32
	s_waitcnt vmcnt(0)
	v_lshlrev_b32_e32 v50, 16, v81
	global_store_dwordx2 v[88:89], v[48:49], off offset:288
	v_lshlrev_b32_e32 v48, 16, v80
	v_and_b32_e32 v49, 0xffff0000, v80
	v_and_b32_e32 v51, 0xffff0000, v81
	v_pk_fma_f32 v[46:47], v[46:47], v[142:143], v[50:51]
	v_pk_fma_f32 v[44:45], v[44:45], v[140:141], v[48:49]
	global_load_dwordx2 v[48:49], v[58:59], off offset:256
	v_cvt_pk_bf16_f32 v44, v44, v45
	v_cvt_pk_bf16_f32 v45, v46, v47
	global_store_dwordx2 v[78:79], v[44:45], off
	v_lshlrev_b32_e32 v44, 16, v76
	v_and_b32_e32 v45, 0xffff0000, v76
	v_lshlrev_b32_e32 v46, 16, v77
	v_and_b32_e32 v47, 0xffff0000, v77
	v_pk_fma_f32 v[42:43], v[42:43], v[138:139], v[46:47]
	v_pk_fma_f32 v[40:41], v[40:41], v[136:137], v[44:45]
	s_and_b64 vcc, exec, s[30:31]
	v_cvt_pk_bf16_f32 v40, v40, v41
	v_cvt_pk_bf16_f32 v41, v42, v43
	global_load_dwordx2 v[42:43], v[58:59], off offset:288
	v_lshlrev_b32_e32 v44, 16, v71
	global_store_dwordx2 v[72:73], v[40:41], off offset:32
	v_lshlrev_b32_e32 v40, 16, v70
	v_and_b32_e32 v41, 0xffff0000, v70
	v_and_b32_e32 v45, 0xffff0000, v71
	v_pk_fma_f32 v[34:35], v[34:35], v[134:135], v[44:45]
	v_pk_fma_f32 v[32:33], v[32:33], v[132:133], v[40:41]
	s_nop 0
	v_cvt_pk_bf16_f32 v32, v32, v33
	v_cvt_pk_bf16_f32 v33, v34, v35
	global_store_dwordx2 v[72:73], v[32:33], off offset:256
	v_lshlrev_b32_e32 v32, 16, v66
	v_and_b32_e32 v33, 0xffff0000, v66
	v_lshlrev_b32_e32 v34, 16, v67
	v_and_b32_e32 v35, 0xffff0000, v67
	v_pk_fma_f32 v[26:27], v[26:27], v[130:131], v[34:35]
	v_pk_fma_f32 v[24:25], v[24:25], v[128:129], v[32:33]
	s_nop 0
	v_cvt_pk_bf16_f32 v24, v24, v25
	v_cvt_pk_bf16_f32 v25, v26, v27
	global_store_dwordx2 v[72:73], v[24:25], off offset:288
	v_lshlrev_b32_e32 v24, 16, v68
	v_and_b32_e32 v25, 0xffff0000, v68
	v_lshlrev_b32_e32 v26, 16, v69
	v_and_b32_e32 v27, 0xffff0000, v69
	v_pk_fma_f32 v[26:27], v[38:39], v[142:143], v[26:27]
	v_pk_fma_f32 v[24:25], v[36:37], v[140:141], v[24:25]
	s_nop 0
	v_cvt_pk_bf16_f32 v24, v24, v25
	v_cvt_pk_bf16_f32 v25, v26, v27
	global_store_dwordx2 v[64:65], v[24:25], off
	v_lshlrev_b32_e32 v24, 16, v84
	v_and_b32_e32 v25, 0xffff0000, v84
	v_lshlrev_b32_e32 v26, 16, v85
	v_and_b32_e32 v27, 0xffff0000, v85
	v_pk_fma_f32 v[26:27], v[30:31], v[138:139], v[26:27]
	v_pk_fma_f32 v[24:25], v[28:29], v[136:137], v[24:25]
	s_nop 0
	v_cvt_pk_bf16_f32 v24, v24, v25
	v_cvt_pk_bf16_f32 v25, v26, v27
	global_store_dwordx2 v[74:75], v[24:25], off offset:32
	v_lshlrev_b32_e32 v24, 16, v60
	v_and_b32_e32 v25, 0xffff0000, v60
	v_lshlrev_b32_e32 v26, 16, v61
	v_and_b32_e32 v27, 0xffff0000, v61
	v_pk_fma_f32 v[18:19], v[18:19], v[134:135], v[26:27]
	v_pk_fma_f32 v[16:17], v[16:17], v[132:133], v[24:25]
	s_nop 0
	v_cvt_pk_bf16_f32 v16, v16, v17
	v_cvt_pk_bf16_f32 v17, v18, v19
	global_store_dwordx2 v[74:75], v[16:17], off offset:256
	v_lshlrev_b32_e32 v16, 16, v54
	v_and_b32_e32 v17, 0xffff0000, v54
	v_lshlrev_b32_e32 v18, 16, v55
	v_and_b32_e32 v19, 0xffff0000, v55
	v_pk_fma_f32 v[10:11], v[10:11], v[130:131], v[18:19]
	v_pk_fma_f32 v[8:9], v[8:9], v[128:129], v[16:17]
	s_nop 0
	v_cvt_pk_bf16_f32 v8, v8, v9
	v_cvt_pk_bf16_f32 v9, v10, v11
	global_store_dwordx2 v[74:75], v[8:9], off offset:288
	v_lshlrev_b32_e32 v8, 16, v56
	v_and_b32_e32 v9, 0xffff0000, v56
	v_lshlrev_b32_e32 v10, 16, v57
	v_and_b32_e32 v11, 0xffff0000, v57
	v_pk_fma_f32 v[10:11], v[22:23], v[142:143], v[10:11]
	v_pk_fma_f32 v[8:9], v[20:21], v[140:141], v[8:9]
	s_nop 0
	v_cvt_pk_bf16_f32 v8, v8, v9
	v_cvt_pk_bf16_f32 v9, v10, v11
	global_store_dwordx2 v[52:53], v[8:9], off
	v_lshlrev_b32_e32 v8, 16, v62
	v_and_b32_e32 v9, 0xffff0000, v62
	v_lshlrev_b32_e32 v10, 16, v63
	v_and_b32_e32 v11, 0xffff0000, v63
	v_pk_fma_f32 v[10:11], v[14:15], v[138:139], v[10:11]
	v_pk_fma_f32 v[8:9], v[12:13], v[136:137], v[8:9]
	s_nop 0
	v_cvt_pk_bf16_f32 v8, v8, v9
	v_cvt_pk_bf16_f32 v9, v10, v11
	global_store_dwordx2 v[58:59], v[8:9], off offset:32
	s_waitcnt vmcnt(0)
	v_lshlrev_b32_e32 v8, 16, v48
	v_and_b32_e32 v9, 0xffff0000, v48
	v_lshlrev_b32_e32 v10, 16, v49
	v_and_b32_e32 v11, 0xffff0000, v49
	v_pk_fma_f32 v[6:7], v[6:7], v[134:135], v[10:11]
	v_pk_fma_f32 v[4:5], v[4:5], v[132:133], v[8:9]
	s_nop 0
	v_cvt_pk_bf16_f32 v4, v4, v5
	v_cvt_pk_bf16_f32 v5, v6, v7
	global_store_dwordx2 v[58:59], v[4:5], off offset:256
	v_lshlrev_b32_e32 v4, 16, v42
	v_and_b32_e32 v5, 0xffff0000, v42
	v_lshlrev_b32_e32 v6, 16, v43
	v_and_b32_e32 v7, 0xffff0000, v43
	v_pk_fma_f32 v[2:3], v[2:3], v[130:131], v[6:7]
	v_pk_fma_f32 v[0:1], v[0:1], v[128:129], v[4:5]
	s_nop 0
	v_cvt_pk_bf16_f32 v0, v0, v1
	v_cvt_pk_bf16_f32 v1, v2, v3
	global_store_dwordx2 v[58:59], v[0:1], off offset:288
	s_cbranch_vccz .LBB0_1272
	s_branch .LBB0_1288
